# conv epilogue dead DPP zero-inits removed + weight loads hoisted; select: row-level chunk skip in transform/mask build, DPP mask reduction
# speedup vs baseline: 1.0161x; 1.0161x over previous
.LBB0_551:
	v_readlane_b32 s50, v247, 42
	s_waitcnt vmcnt(1)
	v_cmp_lt_i32_e32 vcc, -1, v0
	s_add_i32 s63, s82, s50
	s_lshr_b32 s98, s63, 8
	s_lshl_b32 s50, s82, 2
	v_cndmask_b32_e32 v137, -1, v230, vcc
	s_add_i32 s52, s50, 0
	v_xor_b32_e32 v0, v137, v0
	v_cmp_ge_i32_e32 vcc, s63, v208
	s_add_i32 s50, s52, 0x21600
	v_mov_b32_e32 v136, s50
	v_cndmask_b32_e32 v0, 0, v0, vcc
	v_cmp_lt_i32_e32 vcc, -1, v1
	v_cmp_lt_i32_e64 s[50:51], -1, v2
	ds_read_b32 v136, v136
	v_cndmask_b32_e32 v137, -1, v230, vcc
	v_xor_b32_e32 v1, v137, v1
	v_cndmask_b32_e64 v137, -1, v230, s[50:51]
	v_cmp_gt_i32_e32 vcc, s63, v208
	v_xor_b32_e32 v2, v137, v2
	v_cmp_lt_i32_e64 s[50:51], -1, v10
	v_cndmask_b32_e32 v1, 0, v1, vcc
	v_cndmask_b32_e32 v2, 0, v2, vcc
	v_cmp_lt_i32_e32 vcc, -1, v3
	s_nop 1
	v_cndmask_b32_e32 v137, -1, v230, vcc
	v_xor_b32_e32 v3, v137, v3
	v_cmp_ge_i32_e32 vcc, s63, v146
	s_nop 1
	v_cndmask_b32_e32 v3, 0, v3, vcc
	s_cmp_lt_u32 s98, 1
	s_cbranch_scc1 .Ltr_a_end
	v_cmp_lt_i32_e32 vcc, -1, v8
	s_nop 1
	v_cndmask_b32_e32 v137, -1, v230, vcc
	v_xor_b32_e32 v8, v137, v8
	v_cmp_ge_i32_e32 vcc, s63, v147
	s_nop 1
	v_cndmask_b32_e32 v8, 0, v8, vcc
	v_cmp_lt_i32_e32 vcc, -1, v9
	s_nop 1
	v_cndmask_b32_e32 v137, -1, v230, vcc
	v_xor_b32_e32 v9, v137, v9
	v_cndmask_b32_e64 v137, -1, v230, s[50:51]
	v_cmp_gt_i32_e32 vcc, s63, v147
	v_xor_b32_e32 v10, v137, v10
	v_cmp_lt_i32_e64 s[50:51], -1, v6
	v_cndmask_b32_e32 v9, 0, v9, vcc
	v_cndmask_b32_e32 v10, 0, v10, vcc
	v_cmp_lt_i32_e32 vcc, -1, v11
	s_nop 1
	v_cndmask_b32_e32 v137, -1, v230, vcc
	v_xor_b32_e32 v11, v137, v11
	v_cmp_ge_i32_e32 vcc, s63, v148
	s_nop 1
	v_cndmask_b32_e32 v11, 0, v11, vcc
	s_cmp_lt_u32 s98, 2
	s_cbranch_scc1 .Ltr_a_end
	v_cmp_lt_i32_e32 vcc, -1, v4
	s_nop 1
	v_cndmask_b32_e32 v137, -1, v230, vcc
	v_xor_b32_e32 v4, v137, v4
	v_cmp_ge_i32_e32 vcc, s63, v149
	s_nop 1
	v_cndmask_b32_e32 v4, 0, v4, vcc
	v_cmp_lt_i32_e32 vcc, -1, v5
	s_nop 1
	v_cndmask_b32_e32 v137, -1, v230, vcc
	v_xor_b32_e32 v5, v137, v5
	v_cndmask_b32_e64 v137, -1, v230, s[50:51]
	v_cmp_gt_i32_e32 vcc, s63, v149
	v_xor_b32_e32 v6, v137, v6
	v_cmp_lt_i32_e64 s[50:51], -1, v14
	v_cndmask_b32_e32 v5, 0, v5, vcc
	v_cndmask_b32_e32 v6, 0, v6, vcc
	v_cmp_lt_i32_e32 vcc, -1, v7
	s_nop 1
	v_cndmask_b32_e32 v137, -1, v230, vcc
	v_xor_b32_e32 v7, v137, v7
	v_cmp_ge_i32_e32 vcc, s63, v150
	s_nop 1
	v_cndmask_b32_e32 v7, 0, v7, vcc
	s_cmp_lt_u32 s98, 3
	s_cbranch_scc1 .Ltr_a_end
	v_cmp_lt_i32_e32 vcc, -1, v12
	s_nop 1
	v_cndmask_b32_e32 v137, -1, v230, vcc
	v_xor_b32_e32 v12, v137, v12
	v_cmp_ge_i32_e32 vcc, s63, v151
	s_nop 1
	v_cndmask_b32_e32 v12, 0, v12, vcc
	v_cmp_lt_i32_e32 vcc, -1, v13
	s_nop 1
	v_cndmask_b32_e32 v137, -1, v230, vcc
	v_xor_b32_e32 v13, v137, v13
	v_cndmask_b32_e64 v137, -1, v230, s[50:51]
	v_cmp_gt_i32_e32 vcc, s63, v151
	v_xor_b32_e32 v14, v137, v14
	v_cmp_lt_i32_e64 s[50:51], -1, v18
	v_cndmask_b32_e32 v13, 0, v13, vcc
	v_cndmask_b32_e32 v14, 0, v14, vcc
	v_cmp_lt_i32_e32 vcc, -1, v15
	s_nop 1
	v_cndmask_b32_e32 v137, -1, v230, vcc
	v_xor_b32_e32 v15, v137, v15
	v_cmp_ge_i32_e32 vcc, s63, v152
	s_nop 1
	v_cndmask_b32_e32 v15, 0, v15, vcc
	s_cmp_lt_u32 s98, 4
	s_cbranch_scc1 .Ltr_a_end
	v_cmp_lt_i32_e32 vcc, -1, v16
	s_nop 1
	v_cndmask_b32_e32 v137, -1, v230, vcc
	v_xor_b32_e32 v16, v137, v16
	v_cmp_ge_i32_e32 vcc, s63, v153
	s_nop 1
	v_cndmask_b32_e32 v16, 0, v16, vcc
	v_cmp_lt_i32_e32 vcc, -1, v17
	s_nop 1
	v_cndmask_b32_e32 v137, -1, v230, vcc
	v_xor_b32_e32 v17, v137, v17
	v_cndmask_b32_e64 v137, -1, v230, s[50:51]
	v_cmp_gt_i32_e32 vcc, s63, v153
	v_xor_b32_e32 v18, v137, v18
	v_cmp_lt_i32_e64 s[50:51], -1, v26
	v_cndmask_b32_e32 v17, 0, v17, vcc
	v_cndmask_b32_e32 v18, 0, v18, vcc
	v_cmp_lt_i32_e32 vcc, -1, v19
	s_nop 1
	v_cndmask_b32_e32 v137, -1, v230, vcc
	v_xor_b32_e32 v19, v137, v19
	v_cmp_ge_i32_e32 vcc, s63, v154
	s_nop 1
	v_cndmask_b32_e32 v19, 0, v19, vcc
	s_cmp_lt_u32 s98, 5
	s_cbranch_scc1 .Ltr_a_end
	v_cmp_lt_i32_e32 vcc, -1, v24
	s_nop 1
	v_cndmask_b32_e32 v137, -1, v230, vcc
	v_xor_b32_e32 v24, v137, v24
	v_cmp_ge_i32_e32 vcc, s63, v155
	s_nop 1
	v_cndmask_b32_e32 v24, 0, v24, vcc
	v_cmp_lt_i32_e32 vcc, -1, v25
	s_nop 1
	v_cndmask_b32_e32 v137, -1, v230, vcc
	v_xor_b32_e32 v25, v137, v25
	v_cndmask_b32_e64 v137, -1, v230, s[50:51]
	v_cmp_gt_i32_e32 vcc, s63, v155
	v_xor_b32_e32 v26, v137, v26
	v_cmp_lt_i32_e64 s[50:51], -1, v22
	v_cndmask_b32_e32 v25, 0, v25, vcc
	v_cndmask_b32_e32 v26, 0, v26, vcc
	v_cmp_lt_i32_e32 vcc, -1, v27
	s_nop 1
	v_cndmask_b32_e32 v137, -1, v230, vcc
	v_xor_b32_e32 v27, v137, v27
	v_cmp_ge_i32_e32 vcc, s63, v156
	s_nop 1
	v_cndmask_b32_e32 v27, 0, v27, vcc
	s_cmp_lt_u32 s98, 6
	s_cbranch_scc1 .Ltr_a_end
	v_cmp_lt_i32_e32 vcc, -1, v20
	s_nop 1
	v_cndmask_b32_e32 v137, -1, v230, vcc
	v_xor_b32_e32 v20, v137, v20
	v_cmp_ge_i32_e32 vcc, s63, v157
	s_nop 1
	v_cndmask_b32_e32 v20, 0, v20, vcc
	v_cmp_lt_i32_e32 vcc, -1, v21
	s_nop 1
	v_cndmask_b32_e32 v137, -1, v230, vcc
	v_xor_b32_e32 v21, v137, v21
	v_cndmask_b32_e64 v137, -1, v230, s[50:51]
	v_cmp_gt_i32_e32 vcc, s63, v157
	v_xor_b32_e32 v22, v137, v22
	v_cmp_lt_i32_e64 s[50:51], -1, v34
	v_cndmask_b32_e32 v21, 0, v21, vcc
	v_cndmask_b32_e32 v22, 0, v22, vcc
	v_cmp_lt_i32_e32 vcc, -1, v23
	s_nop 1
	v_cndmask_b32_e32 v137, -1, v230, vcc
	v_xor_b32_e32 v23, v137, v23
	v_cmp_ge_i32_e32 vcc, s63, v158
	s_nop 1
	v_cndmask_b32_e32 v23, 0, v23, vcc
	s_cmp_lt_u32 s98, 7
	s_cbranch_scc1 .Ltr_a_end
	v_cmp_lt_i32_e32 vcc, -1, v32
	s_nop 1
	v_cndmask_b32_e32 v137, -1, v230, vcc
	v_xor_b32_e32 v32, v137, v32
	v_cmp_ge_i32_e32 vcc, s63, v159
	s_nop 1
	v_cndmask_b32_e32 v32, 0, v32, vcc
	v_cmp_lt_i32_e32 vcc, -1, v33
	s_nop 1
	v_cndmask_b32_e32 v137, -1, v230, vcc
	v_xor_b32_e32 v33, v137, v33
	v_cndmask_b32_e64 v137, -1, v230, s[50:51]
	v_cmp_gt_i32_e32 vcc, s63, v159
	v_xor_b32_e32 v34, v137, v34
	v_cmp_lt_i32_e64 s[50:51], -1, v30
	v_cndmask_b32_e32 v33, 0, v33, vcc
	v_cndmask_b32_e32 v34, 0, v34, vcc
	v_cmp_lt_i32_e32 vcc, -1, v35
	s_nop 1
	v_cndmask_b32_e32 v137, -1, v230, vcc
	v_xor_b32_e32 v35, v137, v35
	v_cmp_ge_i32_e32 vcc, s63, v160
	s_nop 1
	v_cndmask_b32_e32 v35, 0, v35, vcc
	s_cmp_lt_u32 s98, 8
	s_cbranch_scc1 .Ltr_a_end
	v_cmp_lt_i32_e32 vcc, -1, v28
	s_nop 1
	v_cndmask_b32_e32 v137, -1, v230, vcc
	v_xor_b32_e32 v28, v137, v28
	v_cmp_ge_i32_e32 vcc, s63, v161
	s_nop 1
	v_cndmask_b32_e32 v28, 0, v28, vcc
	v_cmp_lt_i32_e32 vcc, -1, v29
	s_nop 1
	v_cndmask_b32_e32 v137, -1, v230, vcc
	v_xor_b32_e32 v29, v137, v29
	v_cndmask_b32_e64 v137, -1, v230, s[50:51]
	v_cmp_gt_i32_e32 vcc, s63, v161
	v_xor_b32_e32 v30, v137, v30
	v_cmp_lt_i32_e64 s[50:51], -1, v42
	v_cndmask_b32_e32 v29, 0, v29, vcc
	v_cndmask_b32_e32 v30, 0, v30, vcc
	v_cmp_lt_i32_e32 vcc, -1, v31
	s_nop 1
	v_cndmask_b32_e32 v137, -1, v230, vcc
	v_xor_b32_e32 v31, v137, v31
	v_cmp_ge_i32_e32 vcc, s63, v162
	s_nop 1
	v_cndmask_b32_e32 v31, 0, v31, vcc
	s_cmp_lt_u32 s98, 9
	s_cbranch_scc1 .Ltr_a_end
	v_cmp_lt_i32_e32 vcc, -1, v40
	s_nop 1
	v_cndmask_b32_e32 v137, -1, v230, vcc
	v_xor_b32_e32 v40, v137, v40
	v_cmp_ge_i32_e32 vcc, s63, v163
	s_nop 1
	v_cndmask_b32_e32 v40, 0, v40, vcc
	v_cmp_lt_i32_e32 vcc, -1, v41
	s_nop 1
	v_cndmask_b32_e32 v137, -1, v230, vcc
	v_xor_b32_e32 v41, v137, v41
	v_cndmask_b32_e64 v137, -1, v230, s[50:51]
	v_cmp_gt_i32_e32 vcc, s63, v163
	v_xor_b32_e32 v42, v137, v42
	v_cmp_lt_i32_e64 s[50:51], -1, v38
	v_cndmask_b32_e32 v41, 0, v41, vcc
	v_cndmask_b32_e32 v42, 0, v42, vcc
	v_cmp_lt_i32_e32 vcc, -1, v43
	s_nop 1
	v_cndmask_b32_e32 v137, -1, v230, vcc
	v_xor_b32_e32 v43, v137, v43
	v_cmp_ge_i32_e32 vcc, s63, v164
	s_nop 1
	v_cndmask_b32_e32 v43, 0, v43, vcc
	s_cmp_lt_u32 s98, 10
	s_cbranch_scc1 .Ltr_a_end
	v_cmp_lt_i32_e32 vcc, -1, v36
	s_nop 1
	v_cndmask_b32_e32 v137, -1, v230, vcc
	v_xor_b32_e32 v36, v137, v36
	v_cmp_ge_i32_e32 vcc, s63, v165
	s_nop 1
	v_cndmask_b32_e32 v36, 0, v36, vcc
	v_cmp_lt_i32_e32 vcc, -1, v37
	s_nop 1
	v_cndmask_b32_e32 v137, -1, v230, vcc
	v_xor_b32_e32 v37, v137, v37
	v_cndmask_b32_e64 v137, -1, v230, s[50:51]
	v_cmp_gt_i32_e32 vcc, s63, v165
	v_xor_b32_e32 v38, v137, v38
	v_cmp_lt_i32_e64 s[50:51], -1, v50
	v_cndmask_b32_e32 v37, 0, v37, vcc
	v_cndmask_b32_e32 v38, 0, v38, vcc
	v_cmp_lt_i32_e32 vcc, -1, v39
	s_nop 1
	v_cndmask_b32_e32 v137, -1, v230, vcc
	v_xor_b32_e32 v39, v137, v39
	v_cmp_ge_i32_e32 vcc, s63, v166
	s_nop 1
	v_cndmask_b32_e32 v39, 0, v39, vcc
	s_cmp_lt_u32 s98, 11
	s_cbranch_scc1 .Ltr_a_end
	v_cmp_lt_i32_e32 vcc, -1, v48
	s_nop 1
	v_cndmask_b32_e32 v137, -1, v230, vcc
	v_xor_b32_e32 v48, v137, v48
	v_cmp_ge_i32_e32 vcc, s63, v167
	s_nop 1
	v_cndmask_b32_e32 v48, 0, v48, vcc
	v_cmp_lt_i32_e32 vcc, -1, v49
	s_nop 1
	v_cndmask_b32_e32 v137, -1, v230, vcc
	v_xor_b32_e32 v49, v137, v49
	v_cndmask_b32_e64 v137, -1, v230, s[50:51]
	v_cmp_gt_i32_e32 vcc, s63, v167
	v_xor_b32_e32 v50, v137, v50
	v_cmp_lt_i32_e64 s[50:51], -1, v46
	v_cndmask_b32_e32 v49, 0, v49, vcc
	v_cndmask_b32_e32 v50, 0, v50, vcc
	v_cmp_lt_i32_e32 vcc, -1, v51
	s_nop 1
	v_cndmask_b32_e32 v137, -1, v230, vcc
	v_xor_b32_e32 v51, v137, v51
	v_cmp_ge_i32_e32 vcc, s63, v168
	s_nop 1
	v_cndmask_b32_e32 v51, 0, v51, vcc
	s_cmp_lt_u32 s98, 12
	s_cbranch_scc1 .Ltr_a_end
	v_cmp_lt_i32_e32 vcc, -1, v44
	s_nop 1
	v_cndmask_b32_e32 v137, -1, v230, vcc
	v_xor_b32_e32 v44, v137, v44
	v_cmp_ge_i32_e32 vcc, s63, v169
	s_nop 1
	v_cndmask_b32_e32 v44, 0, v44, vcc
	v_cmp_lt_i32_e32 vcc, -1, v45
	s_nop 1
	v_cndmask_b32_e32 v137, -1, v230, vcc
	v_xor_b32_e32 v45, v137, v45
	v_cndmask_b32_e64 v137, -1, v230, s[50:51]
	v_cmp_gt_i32_e32 vcc, s63, v169
	v_xor_b32_e32 v46, v137, v46
	v_cmp_lt_i32_e64 s[50:51], -1, v58
	v_cndmask_b32_e32 v45, 0, v45, vcc
	v_cndmask_b32_e32 v46, 0, v46, vcc
	v_cmp_lt_i32_e32 vcc, -1, v47
	s_nop 1
	v_cndmask_b32_e32 v137, -1, v230, vcc
	v_xor_b32_e32 v47, v137, v47
	v_cmp_ge_i32_e32 vcc, s63, v170
	s_nop 1
	v_cndmask_b32_e32 v47, 0, v47, vcc
	s_cmp_lt_u32 s98, 13
	s_cbranch_scc1 .Ltr_a_end
	v_cmp_lt_i32_e32 vcc, -1, v56
	s_nop 1
	v_cndmask_b32_e32 v137, -1, v230, vcc
	v_xor_b32_e32 v56, v137, v56
	v_cmp_ge_i32_e32 vcc, s63, v171
	s_nop 1
	v_cndmask_b32_e32 v56, 0, v56, vcc
	v_cmp_lt_i32_e32 vcc, -1, v57
	s_nop 1
	v_cndmask_b32_e32 v137, -1, v230, vcc
	v_xor_b32_e32 v57, v137, v57
	v_cndmask_b32_e64 v137, -1, v230, s[50:51]
	v_cmp_gt_i32_e32 vcc, s63, v171
	v_xor_b32_e32 v58, v137, v58
	v_cmp_lt_i32_e64 s[50:51], -1, v54
	v_cndmask_b32_e32 v57, 0, v57, vcc
	v_cndmask_b32_e32 v58, 0, v58, vcc
	v_cmp_lt_i32_e32 vcc, -1, v59
	s_nop 1
	v_cndmask_b32_e32 v137, -1, v230, vcc
	v_xor_b32_e32 v59, v137, v59
	v_cmp_ge_i32_e32 vcc, s63, v172
	s_nop 1
	v_cndmask_b32_e32 v59, 0, v59, vcc
	s_cmp_lt_u32 s98, 14
	s_cbranch_scc1 .Ltr_a_end
	v_cmp_lt_i32_e32 vcc, -1, v52
	s_nop 1
	v_cndmask_b32_e32 v137, -1, v230, vcc
	v_xor_b32_e32 v52, v137, v52
	v_cmp_ge_i32_e32 vcc, s63, v173
	s_nop 1
	v_cndmask_b32_e32 v52, 0, v52, vcc
	v_cmp_lt_i32_e32 vcc, -1, v53
	s_nop 1
	v_cndmask_b32_e32 v137, -1, v230, vcc
	v_xor_b32_e32 v53, v137, v53
	v_cndmask_b32_e64 v137, -1, v230, s[50:51]
	v_cmp_gt_i32_e32 vcc, s63, v173
	v_xor_b32_e32 v54, v137, v54
	v_cmp_lt_i32_e64 s[50:51], -1, v62
	v_cndmask_b32_e32 v53, 0, v53, vcc
	v_cndmask_b32_e32 v54, 0, v54, vcc
	v_cmp_lt_i32_e32 vcc, -1, v55
	s_nop 1
	v_cndmask_b32_e32 v137, -1, v230, vcc
	v_xor_b32_e32 v55, v137, v55
	v_cmp_ge_i32_e32 vcc, s63, v174
	s_nop 1
	v_cndmask_b32_e32 v55, 0, v55, vcc
	s_cmp_lt_u32 s98, 15
	s_cbranch_scc1 .Ltr_a_end
	v_cmp_lt_i32_e32 vcc, -1, v60
	s_nop 1
	v_cndmask_b32_e32 v137, -1, v230, vcc
	v_xor_b32_e32 v60, v137, v60
	v_cmp_ge_i32_e32 vcc, s63, v175
	s_nop 1
	v_cndmask_b32_e32 v60, 0, v60, vcc
	v_cmp_lt_i32_e32 vcc, -1, v61
	s_nop 1
	v_cndmask_b32_e32 v137, -1, v230, vcc
	v_xor_b32_e32 v61, v137, v61
	v_cndmask_b32_e64 v137, -1, v230, s[50:51]
	v_cmp_gt_i32_e32 vcc, s63, v175
	v_xor_b32_e32 v62, v137, v62
	v_cmp_ge_i32_e64 s[50:51], s63, v176
	v_cndmask_b32_e32 v61, 0, v61, vcc
	v_cndmask_b32_e32 v62, 0, v62, vcc
	v_cmp_lt_i32_e32 vcc, -1, v63
	s_nop 1
	v_cndmask_b32_e32 v137, -1, v230, vcc
	v_xor_b32_e32 v63, v137, v63
.Ltr_a_end:
	s_waitcnt lgkmcnt(0)
	v_cmp_gt_i32_e32 vcc, 1, v136
	v_cndmask_b32_e64 v63, 0, v63, s[50:51]
	s_cbranch_vccnz .LBB0_556
	s_add_i32 s50, s52, 0x21700
	v_mov_b32_e32 v137, s50
	ds_read_b32 v137, v137
	s_add_i32 s50, s52, 0x21500
	v_mov_b32_e32 v192, s50
	ds_read_b32 v192, v192
	s_waitcnt lgkmcnt(1)
	v_cmp_eq_u32_e32 vcc, v136, v137
	s_cbranch_vccnz .LBB0_557
	s_mov_b32 s83, 1
	v_mov_b32_e32 v137, 0
	s_mov_b32 s50, 24
	s_mov_b64 s[54:55], 0

.LBB0_566:
	v_cmp_eq_u32_e64 s[50:51], v0, v137
	v_cmp_le_i32_e64 s[52:53], v208, v193
	v_cmp_gt_u32_e32 vcc, v0, v137
	s_and_b64 s[50:51], s[50:51], s[52:53]
	s_or_b64 s[50:51], vcc, s[50:51]
	v_cndmask_b32_e64 v136, 0, 1, s[50:51]
	v_cmp_eq_u32_e64 s[50:51], v1, v137
	v_cmp_lt_i32_e64 s[52:53], v208, v193
	v_cmp_gt_u32_e32 vcc, v1, v137
	s_and_b64 s[50:51], s[50:51], s[52:53]
	s_or_b64 s[50:51], vcc, s[50:51]
	v_cndmask_b32_e64 v192, 0, 2, s[50:51]
	v_cmp_eq_u32_e64 s[50:51], v2, v137
	v_cmp_le_i32_e64 s[52:53], v145, v193
	v_cmp_gt_u32_e32 vcc, v2, v137
	s_and_b64 s[50:51], s[50:51], s[52:53]
	s_or_b64 s[50:51], vcc, s[50:51]
	v_cndmask_b32_e64 v194, 0, 4, s[50:51]
	v_cmp_eq_u32_e64 s[50:51], v3, v137
	v_cmp_le_i32_e64 s[52:53], v146, v193
	v_cmp_gt_u32_e32 vcc, v3, v137
	s_and_b64 s[50:51], s[50:51], s[52:53]
	s_or_b64 s[50:51], vcc, s[50:51]
	v_cndmask_b32_e64 v195, 0, 8, s[50:51]
	v_or_b32_e32 v136, v192, v136
	v_or3_b32 v136, v136, v194, v195
	v_lshlrev_b32_e32 v136, v139, v136
	s_nop 1
	v_or_b32_dpp v136, v136, v136 quad_perm:[1,0,3,2] row_mask:0xf bank_mask:0xf
	s_mul_i32 s50, s82, 0x208
	s_add_i32 s54, s50, 0
	s_add_i32 s54, s54, 0x18000
	s_waitcnt lgkmcnt(0)
	s_nop 1
	v_or_b32_dpp v136, v136, v136 quad_perm:[2,3,0,1] row_mask:0xf bank_mask:0xf
	s_waitcnt lgkmcnt(0)
	s_nop 1
	v_or_b32_dpp v136, v136, v136 row_half_mirror row_mask:0xf bank_mask:0xf
	s_and_saveexec_b64 s[50:51], s[56:57]
	s_cbranch_execz .LBB0_597
	s_waitcnt lgkmcnt(0)
	v_lshl_add_u32 v192, v140, 2, s54
	ds_write_b32 v192, v136
	s_or_b64 exec, exec, s[50:51]
	s_and_b64 vcc, exec, s[48:49]
	s_cbranch_vccz .LBB0_598

.LBB0_569:
	s_cmp_lt_u32 s98, 2
	s_cbranch_scc1 .Lmz_a_2
	v_cmp_eq_u32_e64 s[50:51], v4, v137
	v_cmp_le_i32_e64 s[52:53], v149, v193
	v_cmp_gt_u32_e32 vcc, v4, v137
	s_and_b64 s[50:51], s[50:51], s[52:53]
	s_or_b64 s[50:51], vcc, s[50:51]
	v_cndmask_b32_e64 v136, 0, 1, s[50:51]
	v_cmp_eq_u32_e64 s[50:51], v5, v137
	v_cmp_lt_i32_e64 s[52:53], v149, v193
	v_cmp_gt_u32_e32 vcc, v5, v137
	s_and_b64 s[50:51], s[50:51], s[52:53]
	s_or_b64 s[50:51], vcc, s[50:51]
	s_waitcnt lgkmcnt(0)
	v_cndmask_b32_e64 v192, 0, 2, s[50:51]
	v_cmp_eq_u32_e64 s[50:51], v6, v137
	v_cmp_le_i32_e64 s[52:53], v178, v193
	v_cmp_gt_u32_e32 vcc, v6, v137
	s_and_b64 s[50:51], s[50:51], s[52:53]
	s_or_b64 s[50:51], vcc, s[50:51]
	v_cndmask_b32_e64 v194, 0, 4, s[50:51]
	v_cmp_eq_u32_e64 s[50:51], v7, v137
	v_cmp_le_i32_e64 s[52:53], v150, v193
	v_cmp_gt_u32_e32 vcc, v7, v137
	s_and_b64 s[50:51], s[50:51], s[52:53]
	s_or_b64 s[50:51], vcc, s[50:51]
	v_cndmask_b32_e64 v195, 0, 8, s[50:51]
	v_or_b32_e32 v136, v192, v136
	v_or3_b32 v136, v136, v194, v195
	v_lshlrev_b32_e32 v136, v139, v136
	s_nop 1
	v_or_b32_dpp v136, v136, v136 quad_perm:[1,0,3,2] row_mask:0xf bank_mask:0xf
	s_waitcnt lgkmcnt(0)
	s_nop 1
	v_or_b32_dpp v136, v136, v136 quad_perm:[2,3,0,1] row_mask:0xf bank_mask:0xf
	s_waitcnt lgkmcnt(0)
	s_nop 1
	v_or_b32_dpp v136, v136, v136 row_half_mirror row_mask:0xf bank_mask:0xf
.Lmst_a_2:
	s_mov_b64 s[50:51], exec
	v_readlane_b32 s52, v247, 55
	v_readlane_b32 s53, v247, 56
	s_and_b64 s[52:53], s[50:51], s[52:53]
	s_mov_b64 exec, s[52:53]
	s_cbranch_execz .LBB0_571
	s_waitcnt lgkmcnt(0)
	v_lshl_add_u32 v192, v140, 2, s54
	ds_write_b32 v192, v136 offset:64

.LBB0_573:
	s_cmp_lt_u32 s98, 4
	s_cbranch_scc1 .Lmz_a_4
	v_cmp_eq_u32_e64 s[50:51], v16, v137
	v_cmp_le_i32_e64 s[52:53], v153, v193
	v_cmp_gt_u32_e32 vcc, v16, v137
	s_and_b64 s[50:51], s[50:51], s[52:53]
	s_or_b64 s[50:51], vcc, s[50:51]
	v_cndmask_b32_e64 v136, 0, 1, s[50:51]
	v_cmp_eq_u32_e64 s[50:51], v17, v137
	v_cmp_lt_i32_e64 s[52:53], v153, v193
	v_cmp_gt_u32_e32 vcc, v17, v137
	s_and_b64 s[50:51], s[50:51], s[52:53]
	s_or_b64 s[50:51], vcc, s[50:51]
	s_waitcnt lgkmcnt(0)
	v_cndmask_b32_e64 v192, 0, 2, s[50:51]
	v_cmp_eq_u32_e64 s[50:51], v18, v137
	v_cmp_le_i32_e64 s[52:53], v180, v193
	v_cmp_gt_u32_e32 vcc, v18, v137
	s_and_b64 s[50:51], s[50:51], s[52:53]
	s_or_b64 s[50:51], vcc, s[50:51]
	v_cndmask_b32_e64 v194, 0, 4, s[50:51]
	v_cmp_eq_u32_e64 s[50:51], v19, v137
	v_cmp_le_i32_e64 s[52:53], v154, v193
	v_cmp_gt_u32_e32 vcc, v19, v137
	s_and_b64 s[50:51], s[50:51], s[52:53]
	s_or_b64 s[50:51], vcc, s[50:51]
	v_cndmask_b32_e64 v195, 0, 8, s[50:51]
	v_or_b32_e32 v136, v192, v136
	v_or3_b32 v136, v136, v194, v195
	v_lshlrev_b32_e32 v136, v139, v136
	s_nop 1
	v_or_b32_dpp v136, v136, v136 quad_perm:[1,0,3,2] row_mask:0xf bank_mask:0xf
	s_waitcnt lgkmcnt(0)
	s_nop 1
	v_or_b32_dpp v136, v136, v136 quad_perm:[2,3,0,1] row_mask:0xf bank_mask:0xf
	s_waitcnt lgkmcnt(0)
	s_nop 1
	v_or_b32_dpp v136, v136, v136 row_half_mirror row_mask:0xf bank_mask:0xf
.Lmst_a_4:
	s_mov_b64 s[50:51], exec
	v_readlane_b32 s52, v247, 59
	v_readlane_b32 s53, v247, 60
	s_and_b64 s[52:53], s[50:51], s[52:53]
	s_mov_b64 exec, s[52:53]
	s_cbranch_execz .LBB0_575
	s_waitcnt lgkmcnt(0)
	v_lshl_add_u32 v192, v140, 2, s54
	ds_write_b32 v192, v136 offset:128

.LBB0_577:
	s_cmp_lt_u32 s98, 6
	s_cbranch_scc1 .Lmz_a_6
	v_cmp_eq_u32_e64 s[50:51], v20, v137
	v_cmp_le_i32_e64 s[52:53], v157, v193
	v_cmp_gt_u32_e32 vcc, v20, v137
	s_and_b64 s[50:51], s[50:51], s[52:53]
	s_or_b64 s[50:51], vcc, s[50:51]
	v_cndmask_b32_e64 v136, 0, 1, s[50:51]
	v_cmp_eq_u32_e64 s[50:51], v21, v137
	v_cmp_lt_i32_e64 s[52:53], v157, v193
	v_cmp_gt_u32_e32 vcc, v21, v137
	s_and_b64 s[50:51], s[50:51], s[52:53]
	s_or_b64 s[50:51], vcc, s[50:51]
	s_waitcnt lgkmcnt(0)
	v_cndmask_b32_e64 v192, 0, 2, s[50:51]
	v_cmp_eq_u32_e64 s[50:51], v22, v137
	v_cmp_le_i32_e64 s[52:53], v182, v193
	v_cmp_gt_u32_e32 vcc, v22, v137
	s_and_b64 s[50:51], s[50:51], s[52:53]
	s_or_b64 s[50:51], vcc, s[50:51]
	v_cndmask_b32_e64 v194, 0, 4, s[50:51]
	v_cmp_eq_u32_e64 s[50:51], v23, v137
	v_cmp_le_i32_e64 s[52:53], v158, v193
	v_cmp_gt_u32_e32 vcc, v23, v137
	s_and_b64 s[50:51], s[50:51], s[52:53]
	s_or_b64 s[50:51], vcc, s[50:51]
	v_cndmask_b32_e64 v195, 0, 8, s[50:51]
	v_or_b32_e32 v136, v192, v136
	v_or3_b32 v136, v136, v194, v195
	v_lshlrev_b32_e32 v136, v139, v136
	s_nop 1
	v_or_b32_dpp v136, v136, v136 quad_perm:[1,0,3,2] row_mask:0xf bank_mask:0xf
	s_waitcnt lgkmcnt(0)
	s_nop 1
	v_or_b32_dpp v136, v136, v136 quad_perm:[2,3,0,1] row_mask:0xf bank_mask:0xf
	s_waitcnt lgkmcnt(0)
	s_nop 1
	v_or_b32_dpp v136, v136, v136 row_half_mirror row_mask:0xf bank_mask:0xf
.Lmst_a_6:
	s_mov_b64 s[50:51], exec
	v_readlane_b32 s52, v247, 63
	v_readlane_b32 s53, v246, 0
	s_and_b64 s[52:53], s[50:51], s[52:53]
	s_mov_b64 exec, s[52:53]
	s_cbranch_execz .LBB0_579
	s_waitcnt lgkmcnt(0)
	v_lshl_add_u32 v192, v140, 2, s54
	ds_write_b32 v192, v136 offset:192

.LBB0_581:
	s_cmp_lt_u32 s98, 8
	s_cbranch_scc1 .Lmz_a_8
	v_cmp_eq_u32_e64 s[50:51], v28, v137
	v_cmp_le_i32_e64 s[52:53], v161, v193
	v_cmp_gt_u32_e32 vcc, v28, v137
	s_and_b64 s[50:51], s[50:51], s[52:53]
	s_or_b64 s[50:51], vcc, s[50:51]
	v_cndmask_b32_e64 v136, 0, 1, s[50:51]
	v_cmp_eq_u32_e64 s[50:51], v29, v137
	v_cmp_lt_i32_e64 s[52:53], v161, v193
	v_cmp_gt_u32_e32 vcc, v29, v137
	s_and_b64 s[50:51], s[50:51], s[52:53]
	s_or_b64 s[50:51], vcc, s[50:51]
	s_waitcnt lgkmcnt(0)
	v_cndmask_b32_e64 v192, 0, 2, s[50:51]
	v_cmp_eq_u32_e64 s[50:51], v30, v137
	v_cmp_le_i32_e64 s[52:53], v184, v193
	v_cmp_gt_u32_e32 vcc, v30, v137
	s_and_b64 s[50:51], s[50:51], s[52:53]
	s_or_b64 s[50:51], vcc, s[50:51]
	v_cndmask_b32_e64 v194, 0, 4, s[50:51]
	v_cmp_eq_u32_e64 s[50:51], v31, v137
	v_cmp_le_i32_e64 s[52:53], v162, v193
	v_cmp_gt_u32_e32 vcc, v31, v137
	s_and_b64 s[50:51], s[50:51], s[52:53]
	s_or_b64 s[50:51], vcc, s[50:51]
	v_cndmask_b32_e64 v195, 0, 8, s[50:51]
	v_or_b32_e32 v136, v192, v136
	v_or3_b32 v136, v136, v194, v195
	v_lshlrev_b32_e32 v136, v139, v136
	s_nop 1
	v_or_b32_dpp v136, v136, v136 quad_perm:[1,0,3,2] row_mask:0xf bank_mask:0xf
	s_waitcnt lgkmcnt(0)
	s_nop 1
	v_or_b32_dpp v136, v136, v136 quad_perm:[2,3,0,1] row_mask:0xf bank_mask:0xf
	s_waitcnt lgkmcnt(0)
	s_nop 1
	v_or_b32_dpp v136, v136, v136 row_half_mirror row_mask:0xf bank_mask:0xf
.Lmst_a_8:
	s_mov_b64 s[50:51], exec
	v_readlane_b32 s52, v246, 3
	v_readlane_b32 s53, v246, 4
	s_and_b64 s[52:53], s[50:51], s[52:53]
	s_mov_b64 exec, s[52:53]
	s_cbranch_execz .LBB0_583
	s_waitcnt lgkmcnt(0)
	v_lshl_add_u32 v192, v140, 2, s54
	ds_write_b32 v192, v136 offset:256

.LBB0_585:
	s_cmp_lt_u32 s98, 10
	s_cbranch_scc1 .Lmz_a_10
	v_cmp_eq_u32_e64 s[50:51], v36, v137
	v_cmp_le_i32_e64 s[52:53], v165, v193
	v_cmp_gt_u32_e32 vcc, v36, v137
	s_and_b64 s[50:51], s[50:51], s[52:53]
	s_or_b64 s[50:51], vcc, s[50:51]
	v_cndmask_b32_e64 v136, 0, 1, s[50:51]
	v_cmp_eq_u32_e64 s[50:51], v37, v137
	v_cmp_lt_i32_e64 s[52:53], v165, v193
	v_cmp_gt_u32_e32 vcc, v37, v137
	s_and_b64 s[50:51], s[50:51], s[52:53]
	s_or_b64 s[50:51], vcc, s[50:51]
	s_waitcnt lgkmcnt(0)
	v_cndmask_b32_e64 v192, 0, 2, s[50:51]
	v_cmp_eq_u32_e64 s[50:51], v38, v137
	v_cmp_le_i32_e64 s[52:53], v186, v193
	v_cmp_gt_u32_e32 vcc, v38, v137
	s_and_b64 s[50:51], s[50:51], s[52:53]
	s_or_b64 s[50:51], vcc, s[50:51]
	v_cndmask_b32_e64 v194, 0, 4, s[50:51]
	v_cmp_eq_u32_e64 s[50:51], v39, v137
	v_cmp_le_i32_e64 s[52:53], v166, v193
	v_cmp_gt_u32_e32 vcc, v39, v137
	s_and_b64 s[50:51], s[50:51], s[52:53]
	s_or_b64 s[50:51], vcc, s[50:51]
	v_cndmask_b32_e64 v195, 0, 8, s[50:51]
	v_or_b32_e32 v136, v192, v136
	v_or3_b32 v136, v136, v194, v195
	v_lshlrev_b32_e32 v136, v139, v136
	s_nop 1
	v_or_b32_dpp v136, v136, v136 quad_perm:[1,0,3,2] row_mask:0xf bank_mask:0xf
	s_waitcnt lgkmcnt(0)
	s_nop 1
	v_or_b32_dpp v136, v136, v136 quad_perm:[2,3,0,1] row_mask:0xf bank_mask:0xf
	s_waitcnt lgkmcnt(0)
	s_nop 1
	v_or_b32_dpp v136, v136, v136 row_half_mirror row_mask:0xf bank_mask:0xf
.Lmst_a_10:
	s_mov_b64 s[50:51], exec
	v_readlane_b32 s52, v246, 7
	v_readlane_b32 s53, v246, 8
	s_and_b64 s[52:53], s[50:51], s[52:53]
	s_mov_b64 exec, s[52:53]
	s_cbranch_execz .LBB0_587
	s_waitcnt lgkmcnt(0)
	v_lshl_add_u32 v192, v140, 2, s54
	ds_write_b32 v192, v136 offset:320

.LBB0_589:
	s_cmp_lt_u32 s98, 12
	s_cbranch_scc1 .Lmz_a_12
	v_cmp_eq_u32_e64 s[50:51], v44, v137
	v_cmp_le_i32_e64 s[52:53], v169, v193
	v_cmp_gt_u32_e32 vcc, v44, v137
	s_and_b64 s[50:51], s[50:51], s[52:53]
	s_or_b64 s[50:51], vcc, s[50:51]
	v_cndmask_b32_e64 v136, 0, 1, s[50:51]
	v_cmp_eq_u32_e64 s[50:51], v45, v137
	v_cmp_lt_i32_e64 s[52:53], v169, v193
	v_cmp_gt_u32_e32 vcc, v45, v137
	s_and_b64 s[50:51], s[50:51], s[52:53]
	s_or_b64 s[50:51], vcc, s[50:51]
	s_waitcnt lgkmcnt(0)
	v_cndmask_b32_e64 v192, 0, 2, s[50:51]
	v_cmp_eq_u32_e64 s[50:51], v46, v137
	v_cmp_le_i32_e64 s[52:53], v188, v193
	v_cmp_gt_u32_e32 vcc, v46, v137
	s_and_b64 s[50:51], s[50:51], s[52:53]
	s_or_b64 s[50:51], vcc, s[50:51]
	v_cndmask_b32_e64 v194, 0, 4, s[50:51]
	v_cmp_eq_u32_e64 s[50:51], v47, v137
	v_cmp_le_i32_e64 s[52:53], v170, v193
	v_cmp_gt_u32_e32 vcc, v47, v137
	s_and_b64 s[50:51], s[50:51], s[52:53]
	s_or_b64 s[50:51], vcc, s[50:51]
	v_cndmask_b32_e64 v195, 0, 8, s[50:51]
	v_or_b32_e32 v136, v192, v136
	v_or3_b32 v136, v136, v194, v195
	v_lshlrev_b32_e32 v136, v139, v136
	s_nop 1
	v_or_b32_dpp v136, v136, v136 quad_perm:[1,0,3,2] row_mask:0xf bank_mask:0xf
	s_waitcnt lgkmcnt(0)
	s_nop 1
	v_or_b32_dpp v136, v136, v136 quad_perm:[2,3,0,1] row_mask:0xf bank_mask:0xf
	s_waitcnt lgkmcnt(0)
	s_nop 1
	v_or_b32_dpp v136, v136, v136 row_half_mirror row_mask:0xf bank_mask:0xf
.Lmst_a_12:
	s_mov_b64 s[50:51], exec
	v_readlane_b32 s52, v246, 11
	v_readlane_b32 s53, v246, 12
	s_and_b64 s[52:53], s[50:51], s[52:53]
	s_mov_b64 exec, s[52:53]
	s_cbranch_execz .LBB0_591
	s_waitcnt lgkmcnt(0)
	v_lshl_add_u32 v192, v140, 2, s54
	ds_write_b32 v192, v136 offset:384

.LBB0_593:
	s_cmp_lt_u32 s98, 14
	s_cbranch_scc1 .Lmz_a_14
	v_cmp_eq_u32_e64 s[50:51], v52, v137
	v_cmp_le_i32_e64 s[52:53], v173, v193
	v_cmp_gt_u32_e32 vcc, v52, v137
	s_and_b64 s[50:51], s[50:51], s[52:53]
	s_or_b64 s[50:51], vcc, s[50:51]
	v_cndmask_b32_e64 v136, 0, 1, s[50:51]
	v_cmp_eq_u32_e64 s[50:51], v53, v137
	v_cmp_lt_i32_e64 s[52:53], v173, v193
	v_cmp_gt_u32_e32 vcc, v53, v137
	s_and_b64 s[50:51], s[50:51], s[52:53]
	s_or_b64 s[50:51], vcc, s[50:51]
	s_waitcnt lgkmcnt(0)
	v_cndmask_b32_e64 v192, 0, 2, s[50:51]
	v_cmp_eq_u32_e64 s[50:51], v54, v137
	v_cmp_le_i32_e64 s[52:53], v190, v193
	v_cmp_gt_u32_e32 vcc, v54, v137
	s_and_b64 s[50:51], s[50:51], s[52:53]
	s_or_b64 s[50:51], vcc, s[50:51]
	v_cndmask_b32_e64 v194, 0, 4, s[50:51]
	v_cmp_eq_u32_e64 s[50:51], v55, v137
	v_cmp_le_i32_e64 s[52:53], v174, v193
	v_cmp_gt_u32_e32 vcc, v55, v137
	s_and_b64 s[50:51], s[50:51], s[52:53]
	s_or_b64 s[50:51], vcc, s[50:51]
	v_cndmask_b32_e64 v195, 0, 8, s[50:51]
	v_or_b32_e32 v136, v192, v136
	v_or3_b32 v136, v136, v194, v195
	v_lshlrev_b32_e32 v136, v139, v136
	s_nop 1
	v_or_b32_dpp v136, v136, v136 quad_perm:[1,0,3,2] row_mask:0xf bank_mask:0xf
	s_waitcnt lgkmcnt(0)
	s_nop 1
	v_or_b32_dpp v136, v136, v136 quad_perm:[2,3,0,1] row_mask:0xf bank_mask:0xf
	s_waitcnt lgkmcnt(0)
	s_nop 1
	v_or_b32_dpp v136, v136, v136 row_half_mirror row_mask:0xf bank_mask:0xf
.Lmst_a_14:
	s_mov_b64 s[50:51], exec
	v_readlane_b32 s52, v246, 15
	v_readlane_b32 s53, v246, 16
	s_and_b64 s[52:53], s[50:51], s[52:53]
	s_mov_b64 exec, s[52:53]
	s_cbranch_execz .LBB0_595
	s_waitcnt lgkmcnt(0)
	v_lshl_add_u32 v192, v140, 2, s54
	ds_write_b32 v192, v136 offset:448

.LBB0_598:
	s_cmp_lt_u32 s98, 1
	s_cbranch_scc1 .Lmz_a_1
	v_cmp_eq_u32_e64 s[50:51], v8, v137
	v_cmp_le_i32_e64 s[52:53], v147, v193
	v_cmp_gt_u32_e32 vcc, v8, v137
	s_and_b64 s[50:51], s[50:51], s[52:53]
	s_or_b64 s[50:51], vcc, s[50:51]
	v_cndmask_b32_e64 v136, 0, 1, s[50:51]
	v_cmp_eq_u32_e64 s[50:51], v9, v137
	v_cmp_lt_i32_e64 s[52:53], v147, v193
	v_cmp_gt_u32_e32 vcc, v9, v137
	s_and_b64 s[50:51], s[50:51], s[52:53]
	s_or_b64 s[50:51], vcc, s[50:51]
	s_waitcnt lgkmcnt(0)
	v_cndmask_b32_e64 v192, 0, 2, s[50:51]
	v_cmp_eq_u32_e64 s[50:51], v10, v137
	v_cmp_le_i32_e64 s[52:53], v177, v193
	v_cmp_gt_u32_e32 vcc, v10, v137
	s_and_b64 s[50:51], s[50:51], s[52:53]
	s_or_b64 s[50:51], vcc, s[50:51]
	v_cndmask_b32_e64 v194, 0, 4, s[50:51]
	v_cmp_eq_u32_e64 s[50:51], v11, v137
	v_cmp_le_i32_e64 s[52:53], v148, v193
	v_cmp_gt_u32_e32 vcc, v11, v137
	s_and_b64 s[50:51], s[50:51], s[52:53]
	s_or_b64 s[50:51], vcc, s[50:51]
	v_cndmask_b32_e64 v195, 0, 8, s[50:51]
	v_or_b32_e32 v136, v192, v136
	v_or3_b32 v136, v136, v194, v195
	v_lshlrev_b32_e32 v136, v139, v136
	s_nop 1
	v_or_b32_dpp v136, v136, v136 quad_perm:[1,0,3,2] row_mask:0xf bank_mask:0xf
	s_waitcnt lgkmcnt(0)
	s_nop 1
	v_or_b32_dpp v136, v136, v136 quad_perm:[2,3,0,1] row_mask:0xf bank_mask:0xf
	s_waitcnt lgkmcnt(0)
	s_nop 1
	v_or_b32_dpp v136, v136, v136 row_half_mirror row_mask:0xf bank_mask:0xf
.Lmst_a_1:
	s_mov_b64 s[50:51], exec
	v_readlane_b32 s52, v247, 53
	v_readlane_b32 s53, v247, 54
	s_and_b64 s[52:53], s[50:51], s[52:53]
	s_mov_b64 exec, s[52:53]
	s_cbranch_execz .LBB0_600
	s_waitcnt lgkmcnt(0)
	v_lshl_add_u32 v192, v140, 2, s54
	ds_write_b32 v192, v136 offset:32

.LBB0_602:
	s_cmp_lt_u32 s98, 3
	s_cbranch_scc1 .Lmz_a_3
	v_cmp_eq_u32_e64 s[50:51], v12, v137
	v_cmp_le_i32_e64 s[52:53], v151, v193
	v_cmp_gt_u32_e32 vcc, v12, v137
	s_and_b64 s[50:51], s[50:51], s[52:53]
	s_or_b64 s[50:51], vcc, s[50:51]
	v_cndmask_b32_e64 v136, 0, 1, s[50:51]
	v_cmp_eq_u32_e64 s[50:51], v13, v137
	v_cmp_lt_i32_e64 s[52:53], v151, v193
	v_cmp_gt_u32_e32 vcc, v13, v137
	s_and_b64 s[50:51], s[50:51], s[52:53]
	s_or_b64 s[50:51], vcc, s[50:51]
	s_waitcnt lgkmcnt(0)
	v_cndmask_b32_e64 v192, 0, 2, s[50:51]
	v_cmp_eq_u32_e64 s[50:51], v14, v137
	v_cmp_le_i32_e64 s[52:53], v179, v193
	v_cmp_gt_u32_e32 vcc, v14, v137
	s_and_b64 s[50:51], s[50:51], s[52:53]
	s_or_b64 s[50:51], vcc, s[50:51]
	v_cndmask_b32_e64 v194, 0, 4, s[50:51]
	v_cmp_eq_u32_e64 s[50:51], v15, v137
	v_cmp_le_i32_e64 s[52:53], v152, v193
	v_cmp_gt_u32_e32 vcc, v15, v137
	s_and_b64 s[50:51], s[50:51], s[52:53]
	s_or_b64 s[50:51], vcc, s[50:51]
	v_cndmask_b32_e64 v195, 0, 8, s[50:51]
	v_or_b32_e32 v136, v192, v136
	v_or3_b32 v136, v136, v194, v195
	v_lshlrev_b32_e32 v136, v139, v136
	s_nop 1
	v_or_b32_dpp v136, v136, v136 quad_perm:[1,0,3,2] row_mask:0xf bank_mask:0xf
	s_waitcnt lgkmcnt(0)
	s_nop 1
	v_or_b32_dpp v136, v136, v136 quad_perm:[2,3,0,1] row_mask:0xf bank_mask:0xf
	s_waitcnt lgkmcnt(0)
	s_nop 1
	v_or_b32_dpp v136, v136, v136 row_half_mirror row_mask:0xf bank_mask:0xf
.Lmst_a_3:
	s_mov_b64 s[50:51], exec
	v_readlane_b32 s52, v247, 57
	v_readlane_b32 s53, v247, 58
	s_and_b64 s[52:53], s[50:51], s[52:53]
	s_mov_b64 exec, s[52:53]
	s_cbranch_execz .LBB0_604
	s_waitcnt lgkmcnt(0)
	v_lshl_add_u32 v192, v140, 2, s54
	ds_write_b32 v192, v136 offset:96

.LBB0_606:
	s_cmp_lt_u32 s98, 5
	s_cbranch_scc1 .Lmz_a_5
	v_cmp_eq_u32_e64 s[50:51], v24, v137
	v_cmp_le_i32_e64 s[52:53], v155, v193
	v_cmp_gt_u32_e32 vcc, v24, v137
	s_and_b64 s[50:51], s[50:51], s[52:53]
	s_or_b64 s[50:51], vcc, s[50:51]
	v_cndmask_b32_e64 v136, 0, 1, s[50:51]
	v_cmp_eq_u32_e64 s[50:51], v25, v137
	v_cmp_lt_i32_e64 s[52:53], v155, v193
	v_cmp_gt_u32_e32 vcc, v25, v137
	s_and_b64 s[50:51], s[50:51], s[52:53]
	s_or_b64 s[50:51], vcc, s[50:51]
	s_waitcnt lgkmcnt(0)
	v_cndmask_b32_e64 v192, 0, 2, s[50:51]
	v_cmp_eq_u32_e64 s[50:51], v26, v137
	v_cmp_le_i32_e64 s[52:53], v181, v193
	v_cmp_gt_u32_e32 vcc, v26, v137
	s_and_b64 s[50:51], s[50:51], s[52:53]
	s_or_b64 s[50:51], vcc, s[50:51]
	v_cndmask_b32_e64 v194, 0, 4, s[50:51]
	v_cmp_eq_u32_e64 s[50:51], v27, v137
	v_cmp_le_i32_e64 s[52:53], v156, v193
	v_cmp_gt_u32_e32 vcc, v27, v137
	s_and_b64 s[50:51], s[50:51], s[52:53]
	s_or_b64 s[50:51], vcc, s[50:51]
	v_cndmask_b32_e64 v195, 0, 8, s[50:51]
	v_or_b32_e32 v136, v192, v136
	v_or3_b32 v136, v136, v194, v195
	v_lshlrev_b32_e32 v136, v139, v136
	s_nop 1
	v_or_b32_dpp v136, v136, v136 quad_perm:[1,0,3,2] row_mask:0xf bank_mask:0xf
	s_waitcnt lgkmcnt(0)
	s_nop 1
	v_or_b32_dpp v136, v136, v136 quad_perm:[2,3,0,1] row_mask:0xf bank_mask:0xf
	s_waitcnt lgkmcnt(0)
	s_nop 1
	v_or_b32_dpp v136, v136, v136 row_half_mirror row_mask:0xf bank_mask:0xf
.Lmst_a_5:
	s_mov_b64 s[50:51], exec
	v_readlane_b32 s52, v247, 61
	v_readlane_b32 s53, v247, 62
	s_and_b64 s[52:53], s[50:51], s[52:53]
	s_mov_b64 exec, s[52:53]
	s_cbranch_execz .LBB0_608
	s_waitcnt lgkmcnt(0)
	v_lshl_add_u32 v192, v140, 2, s54
	ds_write_b32 v192, v136 offset:160

.LBB0_610:
	s_cmp_lt_u32 s98, 7
	s_cbranch_scc1 .Lmz_a_7
	v_cmp_eq_u32_e64 s[50:51], v32, v137
	v_cmp_le_i32_e64 s[52:53], v159, v193
	v_cmp_gt_u32_e32 vcc, v32, v137
	s_and_b64 s[50:51], s[50:51], s[52:53]
	s_or_b64 s[50:51], vcc, s[50:51]
	v_cndmask_b32_e64 v136, 0, 1, s[50:51]
	v_cmp_eq_u32_e64 s[50:51], v33, v137
	v_cmp_lt_i32_e64 s[52:53], v159, v193
	v_cmp_gt_u32_e32 vcc, v33, v137
	s_and_b64 s[50:51], s[50:51], s[52:53]
	s_or_b64 s[50:51], vcc, s[50:51]
	s_waitcnt lgkmcnt(0)
	v_cndmask_b32_e64 v192, 0, 2, s[50:51]
	v_cmp_eq_u32_e64 s[50:51], v34, v137
	v_cmp_le_i32_e64 s[52:53], v183, v193
	v_cmp_gt_u32_e32 vcc, v34, v137
	s_and_b64 s[50:51], s[50:51], s[52:53]
	s_or_b64 s[50:51], vcc, s[50:51]
	v_cndmask_b32_e64 v194, 0, 4, s[50:51]
	v_cmp_eq_u32_e64 s[50:51], v35, v137
	v_cmp_le_i32_e64 s[52:53], v160, v193
	v_cmp_gt_u32_e32 vcc, v35, v137
	s_and_b64 s[50:51], s[50:51], s[52:53]
	s_or_b64 s[50:51], vcc, s[50:51]
	v_cndmask_b32_e64 v195, 0, 8, s[50:51]
	v_or_b32_e32 v136, v192, v136
	v_or3_b32 v136, v136, v194, v195
	v_lshlrev_b32_e32 v136, v139, v136
	s_nop 1
	v_or_b32_dpp v136, v136, v136 quad_perm:[1,0,3,2] row_mask:0xf bank_mask:0xf
	s_waitcnt lgkmcnt(0)
	s_nop 1
	v_or_b32_dpp v136, v136, v136 quad_perm:[2,3,0,1] row_mask:0xf bank_mask:0xf
	s_waitcnt lgkmcnt(0)
	s_nop 1
	v_or_b32_dpp v136, v136, v136 row_half_mirror row_mask:0xf bank_mask:0xf
.Lmst_a_7:
	s_mov_b64 s[50:51], exec
	v_readlane_b32 s52, v246, 1
	v_readlane_b32 s53, v246, 2
	s_and_b64 s[52:53], s[50:51], s[52:53]
	s_mov_b64 exec, s[52:53]
	s_cbranch_execz .LBB0_612
	s_waitcnt lgkmcnt(0)
	v_lshl_add_u32 v192, v140, 2, s54
	ds_write_b32 v192, v136 offset:224

.LBB0_614:
	s_cmp_lt_u32 s98, 9
	s_cbranch_scc1 .Lmz_a_9
	v_cmp_eq_u32_e64 s[50:51], v40, v137
	v_cmp_le_i32_e64 s[52:53], v163, v193
	v_cmp_gt_u32_e32 vcc, v40, v137
	s_and_b64 s[50:51], s[50:51], s[52:53]
	s_or_b64 s[50:51], vcc, s[50:51]
	v_cndmask_b32_e64 v136, 0, 1, s[50:51]
	v_cmp_eq_u32_e64 s[50:51], v41, v137
	v_cmp_lt_i32_e64 s[52:53], v163, v193
	v_cmp_gt_u32_e32 vcc, v41, v137
	s_and_b64 s[50:51], s[50:51], s[52:53]
	s_or_b64 s[50:51], vcc, s[50:51]
	s_waitcnt lgkmcnt(0)
	v_cndmask_b32_e64 v192, 0, 2, s[50:51]
	v_cmp_eq_u32_e64 s[50:51], v42, v137
	v_cmp_le_i32_e64 s[52:53], v185, v193
	v_cmp_gt_u32_e32 vcc, v42, v137
	s_and_b64 s[50:51], s[50:51], s[52:53]
	s_or_b64 s[50:51], vcc, s[50:51]
	v_cndmask_b32_e64 v194, 0, 4, s[50:51]
	v_cmp_eq_u32_e64 s[50:51], v43, v137
	v_cmp_le_i32_e64 s[52:53], v164, v193
	v_cmp_gt_u32_e32 vcc, v43, v137
	s_and_b64 s[50:51], s[50:51], s[52:53]
	s_or_b64 s[50:51], vcc, s[50:51]
	v_cndmask_b32_e64 v195, 0, 8, s[50:51]
	v_or_b32_e32 v136, v192, v136
	v_or3_b32 v136, v136, v194, v195
	v_lshlrev_b32_e32 v136, v139, v136
	s_nop 1
	v_or_b32_dpp v136, v136, v136 quad_perm:[1,0,3,2] row_mask:0xf bank_mask:0xf
	s_waitcnt lgkmcnt(0)
	s_nop 1
	v_or_b32_dpp v136, v136, v136 quad_perm:[2,3,0,1] row_mask:0xf bank_mask:0xf
	s_waitcnt lgkmcnt(0)
	s_nop 1
	v_or_b32_dpp v136, v136, v136 row_half_mirror row_mask:0xf bank_mask:0xf
.Lmst_a_9:
	s_mov_b64 s[50:51], exec
	v_readlane_b32 s52, v246, 5
	v_readlane_b32 s53, v246, 6
	s_and_b64 s[52:53], s[50:51], s[52:53]
	s_mov_b64 exec, s[52:53]
	s_cbranch_execz .LBB0_616
	s_waitcnt lgkmcnt(0)
	v_lshl_add_u32 v192, v140, 2, s54
	ds_write_b32 v192, v136 offset:288

.LBB0_618:
	s_cmp_lt_u32 s98, 11
	s_cbranch_scc1 .Lmz_a_11
	v_cmp_eq_u32_e64 s[50:51], v48, v137
	v_cmp_le_i32_e64 s[52:53], v167, v193
	v_cmp_gt_u32_e32 vcc, v48, v137
	s_and_b64 s[50:51], s[50:51], s[52:53]
	s_or_b64 s[50:51], vcc, s[50:51]
	v_cndmask_b32_e64 v136, 0, 1, s[50:51]
	v_cmp_eq_u32_e64 s[50:51], v49, v137
	v_cmp_lt_i32_e64 s[52:53], v167, v193
	v_cmp_gt_u32_e32 vcc, v49, v137
	s_and_b64 s[50:51], s[50:51], s[52:53]
	s_or_b64 s[50:51], vcc, s[50:51]
	s_waitcnt lgkmcnt(0)
	v_cndmask_b32_e64 v192, 0, 2, s[50:51]
	v_cmp_eq_u32_e64 s[50:51], v50, v137
	v_cmp_le_i32_e64 s[52:53], v187, v193
	v_cmp_gt_u32_e32 vcc, v50, v137
	s_and_b64 s[50:51], s[50:51], s[52:53]
	s_or_b64 s[50:51], vcc, s[50:51]
	v_cndmask_b32_e64 v194, 0, 4, s[50:51]
	v_cmp_eq_u32_e64 s[50:51], v51, v137
	v_cmp_le_i32_e64 s[52:53], v168, v193
	v_cmp_gt_u32_e32 vcc, v51, v137
	s_and_b64 s[50:51], s[50:51], s[52:53]
	s_or_b64 s[50:51], vcc, s[50:51]
	v_cndmask_b32_e64 v195, 0, 8, s[50:51]
	v_or_b32_e32 v136, v192, v136
	v_or3_b32 v136, v136, v194, v195
	v_lshlrev_b32_e32 v136, v139, v136
	s_nop 1
	v_or_b32_dpp v136, v136, v136 quad_perm:[1,0,3,2] row_mask:0xf bank_mask:0xf
	s_waitcnt lgkmcnt(0)
	s_nop 1
	v_or_b32_dpp v136, v136, v136 quad_perm:[2,3,0,1] row_mask:0xf bank_mask:0xf
	s_waitcnt lgkmcnt(0)
	s_nop 1
	v_or_b32_dpp v136, v136, v136 row_half_mirror row_mask:0xf bank_mask:0xf
.Lmst_a_11:
	s_mov_b64 s[50:51], exec
	v_readlane_b32 s52, v246, 9
	v_readlane_b32 s53, v246, 10
	s_and_b64 s[52:53], s[50:51], s[52:53]
	s_mov_b64 exec, s[52:53]
	s_cbranch_execz .LBB0_620
	s_waitcnt lgkmcnt(0)
	v_lshl_add_u32 v192, v140, 2, s54
	ds_write_b32 v192, v136 offset:352

.LBB0_622:
	s_cmp_lt_u32 s98, 13
	s_cbranch_scc1 .Lmz_a_13
	v_cmp_eq_u32_e64 s[50:51], v56, v137
	v_cmp_le_i32_e64 s[52:53], v171, v193
	v_cmp_gt_u32_e32 vcc, v56, v137
	s_and_b64 s[50:51], s[50:51], s[52:53]
	s_or_b64 s[50:51], vcc, s[50:51]
	v_cndmask_b32_e64 v136, 0, 1, s[50:51]
	v_cmp_eq_u32_e64 s[50:51], v57, v137
	v_cmp_lt_i32_e64 s[52:53], v171, v193
	v_cmp_gt_u32_e32 vcc, v57, v137
	s_and_b64 s[50:51], s[50:51], s[52:53]
	s_or_b64 s[50:51], vcc, s[50:51]
	s_waitcnt lgkmcnt(0)
	v_cndmask_b32_e64 v192, 0, 2, s[50:51]
	v_cmp_eq_u32_e64 s[50:51], v58, v137
	v_cmp_le_i32_e64 s[52:53], v189, v193
	v_cmp_gt_u32_e32 vcc, v58, v137
	s_and_b64 s[50:51], s[50:51], s[52:53]
	s_or_b64 s[50:51], vcc, s[50:51]
	v_cndmask_b32_e64 v194, 0, 4, s[50:51]
	v_cmp_eq_u32_e64 s[50:51], v59, v137
	v_cmp_le_i32_e64 s[52:53], v172, v193
	v_cmp_gt_u32_e32 vcc, v59, v137
	s_and_b64 s[50:51], s[50:51], s[52:53]
	s_or_b64 s[50:51], vcc, s[50:51]
	v_cndmask_b32_e64 v195, 0, 8, s[50:51]
	v_or_b32_e32 v136, v192, v136
	v_or3_b32 v136, v136, v194, v195
	v_lshlrev_b32_e32 v136, v139, v136
	s_nop 1
	v_or_b32_dpp v136, v136, v136 quad_perm:[1,0,3,2] row_mask:0xf bank_mask:0xf
	s_waitcnt lgkmcnt(0)
	s_nop 1
	v_or_b32_dpp v136, v136, v136 quad_perm:[2,3,0,1] row_mask:0xf bank_mask:0xf
	s_waitcnt lgkmcnt(0)
	s_nop 1
	v_or_b32_dpp v136, v136, v136 row_half_mirror row_mask:0xf bank_mask:0xf
.Lmst_a_13:
	s_mov_b64 s[50:51], exec
	v_readlane_b32 s52, v246, 13
	v_readlane_b32 s53, v246, 14
	s_and_b64 s[52:53], s[50:51], s[52:53]
	s_mov_b64 exec, s[52:53]
	s_cbranch_execz .LBB0_624
	s_waitcnt lgkmcnt(0)
	v_lshl_add_u32 v192, v140, 2, s54
	ds_write_b32 v192, v136 offset:416

.LBB0_626:
	s_cmp_lt_u32 s98, 15
	s_cbranch_scc1 .Lmz_a_15
	v_cmp_eq_u32_e64 s[50:51], v60, v137
	v_cmp_le_i32_e64 s[52:53], v175, v193
	v_cmp_gt_u32_e32 vcc, v60, v137
	s_and_b64 s[50:51], s[50:51], s[52:53]
	s_or_b64 s[50:51], vcc, s[50:51]
	v_cndmask_b32_e64 v136, 0, 1, s[50:51]
	v_cmp_eq_u32_e64 s[50:51], v61, v137
	v_cmp_lt_i32_e64 s[52:53], v175, v193
	v_cmp_gt_u32_e32 vcc, v61, v137
	s_and_b64 s[50:51], s[50:51], s[52:53]
	s_or_b64 s[50:51], vcc, s[50:51]
	s_waitcnt lgkmcnt(0)
	v_cndmask_b32_e64 v192, 0, 2, s[50:51]
	v_cmp_eq_u32_e64 s[50:51], v62, v137
	v_cmp_le_i32_e64 s[52:53], v191, v193
	v_cmp_gt_u32_e32 vcc, v62, v137
	s_and_b64 s[50:51], s[50:51], s[52:53]
	s_or_b64 s[50:51], vcc, s[50:51]
	v_cndmask_b32_e64 v194, 0, 4, s[50:51]
	v_cmp_eq_u32_e64 s[50:51], v63, v137
	v_cmp_le_i32_e64 s[52:53], v176, v193
	v_cmp_gt_u32_e32 vcc, v63, v137
	s_and_b64 s[50:51], s[50:51], s[52:53]
	s_or_b64 s[50:51], vcc, s[50:51]
	v_cndmask_b32_e64 v137, 0, 8, s[50:51]
	v_or_b32_e32 v136, v192, v136
	v_or3_b32 v136, v136, v194, v137
	v_lshlrev_b32_e32 v136, v139, v136
	s_nop 1
	v_or_b32_dpp v136, v136, v136 quad_perm:[1,0,3,2] row_mask:0xf bank_mask:0xf
	s_waitcnt lgkmcnt(0)
	s_nop 1
	v_or_b32_dpp v136, v136, v136 quad_perm:[2,3,0,1] row_mask:0xf bank_mask:0xf
	s_waitcnt lgkmcnt(0)
	s_nop 1
	v_or_b32_dpp v136, v136, v136 row_half_mirror row_mask:0xf bank_mask:0xf
.Lmst_a_15:
	s_mov_b64 s[50:51], exec
	v_readlane_b32 s52, v246, 17
	v_readlane_b32 s53, v246, 18
	s_and_b64 s[52:53], s[50:51], s[52:53]
	s_mov_b64 exec, s[52:53]
	s_cbranch_execz .LBB0_628
	s_waitcnt lgkmcnt(0)
	v_lshl_add_u32 v137, v140, 2, s54
	ds_write_b32 v137, v136 offset:480

.LBB0_659:
	v_readlane_b32 s50, v247, 42
	s_add_i32 s63, s62, s50
	s_lshr_b32 s98, s63, 8
	s_lshl_b32 s50, s62, 2
	s_add_i32 s52, s50, 0
	s_add_i32 s50, s52, 0x21600
	v_mov_b32_e32 v136, s50
	s_waitcnt vmcnt(0)
	v_cmp_lt_i32_e32 vcc, -1, v84
	ds_read_b32 v241, v136
	v_cmp_ge_i32_e64 s[50:51], s63, v176
	v_cndmask_b32_e32 v136, -1, v230, vcc
	v_xor_b32_e32 v84, v136, v84
	v_cmp_ge_i32_e32 vcc, s63, v208
	s_nop 1
	v_cndmask_b32_e32 v239, 0, v84, vcc
	v_cmp_lt_i32_e32 vcc, -1, v85
	s_nop 1
	v_cndmask_b32_e32 v84, -1, v230, vcc
	v_xor_b32_e32 v84, v84, v85
	v_cmp_gt_i32_e32 vcc, s63, v208
	s_nop 1
	v_cndmask_b32_e32 v240, 0, v84, vcc
	v_cmp_lt_i32_e32 vcc, -1, v86
	s_nop 1
	v_cndmask_b32_e32 v84, -1, v230, vcc
	v_xor_b32_e32 v84, v84, v86
	v_cmp_ge_i32_e32 vcc, s63, v145
	s_nop 1
	v_cndmask_b32_e32 v238, 0, v84, vcc
	v_cmp_lt_i32_e32 vcc, -1, v87
	s_nop 1
	v_cndmask_b32_e32 v84, -1, v230, vcc
	v_xor_b32_e32 v84, v84, v87
	v_cmp_ge_i32_e32 vcc, s63, v146
	s_nop 1
	v_cndmask_b32_e32 v237, 0, v84, vcc
	s_cmp_lt_u32 s98, 1
	s_cbranch_scc1 .Ltr_b_end
	v_cmp_lt_i32_e32 vcc, -1, v72
	s_nop 1
	v_cndmask_b32_e32 v84, -1, v230, vcc
	v_xor_b32_e32 v72, v84, v72
	v_cmp_ge_i32_e32 vcc, s63, v147
	s_nop 1
	v_cndmask_b32_e32 v235, 0, v72, vcc
	v_cmp_lt_i32_e32 vcc, -1, v73
	s_nop 1
	v_cndmask_b32_e32 v72, -1, v230, vcc
	v_xor_b32_e32 v72, v72, v73
	v_cmp_gt_i32_e32 vcc, s63, v147
	s_nop 1
	v_cndmask_b32_e32 v236, 0, v72, vcc
	v_cmp_lt_i32_e32 vcc, -1, v74
	s_nop 1
	v_cndmask_b32_e32 v72, -1, v230, vcc
	v_xor_b32_e32 v72, v72, v74
	v_cmp_ge_i32_e32 vcc, s63, v177
	s_nop 1
	v_cndmask_b32_e32 v234, 0, v72, vcc
	v_cmp_lt_i32_e32 vcc, -1, v75
	s_nop 1
	v_cndmask_b32_e32 v72, -1, v230, vcc
	v_xor_b32_e32 v72, v72, v75
	v_cmp_ge_i32_e32 vcc, s63, v148
	s_nop 1
	v_cndmask_b32_e32 v233, 0, v72, vcc
	s_cmp_lt_u32 s98, 2
	s_cbranch_scc1 .Ltr_b_end
	v_cmp_lt_i32_e32 vcc, -1, v64
	s_nop 1
	v_cndmask_b32_e32 v72, -1, v230, vcc
	v_xor_b32_e32 v64, v72, v64
	v_cmp_ge_i32_e32 vcc, s63, v149
	s_nop 1
	v_cndmask_b32_e32 v213, 0, v64, vcc
	v_cmp_lt_i32_e32 vcc, -1, v65
	s_nop 1
	v_cndmask_b32_e32 v64, -1, v230, vcc
	v_xor_b32_e32 v64, v64, v65
	v_cmp_gt_i32_e32 vcc, s63, v149
	s_nop 1
	v_cndmask_b32_e32 v232, 0, v64, vcc
	v_cmp_lt_i32_e32 vcc, -1, v66
	s_nop 1
	v_cndmask_b32_e32 v64, -1, v230, vcc
	v_xor_b32_e32 v64, v64, v66
	v_cmp_ge_i32_e32 vcc, s63, v178
	s_nop 1
	v_cndmask_b32_e32 v212, 0, v64, vcc
	v_cmp_lt_i32_e32 vcc, -1, v67
	s_nop 1
	v_cndmask_b32_e32 v64, -1, v230, vcc
	v_xor_b32_e32 v64, v64, v67
	v_cmp_ge_i32_e32 vcc, s63, v150
	s_nop 1
	v_cndmask_b32_e32 v211, 0, v64, vcc
	s_cmp_lt_u32 s98, 3
	s_cbranch_scc1 .Ltr_b_end
	v_cmp_lt_i32_e32 vcc, -1, v76
	s_nop 1
	v_cndmask_b32_e32 v64, -1, v230, vcc
	v_xor_b32_e32 v64, v64, v76
	v_cmp_ge_i32_e32 vcc, s63, v151
	s_nop 1
	v_cndmask_b32_e32 v207, 0, v64, vcc
	v_cmp_lt_i32_e32 vcc, -1, v77
	s_nop 1
	v_cndmask_b32_e32 v64, -1, v230, vcc
	v_xor_b32_e32 v64, v64, v77
	v_cmp_gt_i32_e32 vcc, s63, v151
	s_nop 1
	v_cndmask_b32_e32 v210, 0, v64, vcc
	v_cmp_lt_i32_e32 vcc, -1, v78
	s_nop 1
	v_cndmask_b32_e32 v64, -1, v230, vcc
	v_xor_b32_e32 v64, v64, v78
	v_cmp_ge_i32_e32 vcc, s63, v179
	s_nop 1
	v_cndmask_b32_e32 v206, 0, v64, vcc
	v_cmp_lt_i32_e32 vcc, -1, v79
	s_nop 1
	v_cndmask_b32_e32 v64, -1, v230, vcc
	v_xor_b32_e32 v64, v64, v79
	v_cmp_ge_i32_e32 vcc, s63, v152
	s_nop 1
	v_cndmask_b32_e32 v205, 0, v64, vcc
	s_cmp_lt_u32 s98, 4
	s_cbranch_scc1 .Ltr_b_end
	v_cmp_lt_i32_e32 vcc, -1, v68
	s_nop 1
	v_cndmask_b32_e32 v64, -1, v230, vcc
	v_xor_b32_e32 v64, v64, v68
	v_cmp_ge_i32_e32 vcc, s63, v153
	s_nop 1
	v_cndmask_b32_e32 v203, 0, v64, vcc
	v_cmp_lt_i32_e32 vcc, -1, v69
	s_nop 1
	v_cndmask_b32_e32 v64, -1, v230, vcc
	v_xor_b32_e32 v64, v64, v69
	v_cmp_gt_i32_e32 vcc, s63, v153
	s_nop 1
	v_cndmask_b32_e32 v204, 0, v64, vcc
	v_cmp_lt_i32_e32 vcc, -1, v70
	s_nop 1
	v_cndmask_b32_e32 v64, -1, v230, vcc
	v_xor_b32_e32 v64, v64, v70
	v_cmp_ge_i32_e32 vcc, s63, v180
	s_nop 1
	v_cndmask_b32_e32 v202, 0, v64, vcc
	v_cmp_lt_i32_e32 vcc, -1, v71
	s_nop 1
	v_cndmask_b32_e32 v64, -1, v230, vcc
	v_xor_b32_e32 v64, v64, v71
	v_cmp_ge_i32_e32 vcc, s63, v154
	s_nop 1
	v_cndmask_b32_e32 v201, 0, v64, vcc
	s_cmp_lt_u32 s98, 5
	s_cbranch_scc1 .Ltr_b_end
	v_cmp_lt_i32_e32 vcc, -1, v88
	s_nop 1
	v_cndmask_b32_e32 v64, -1, v230, vcc
	v_xor_b32_e32 v64, v64, v88
	v_cmp_ge_i32_e32 vcc, s63, v155
	s_nop 1
	v_cndmask_b32_e32 v199, 0, v64, vcc
	v_cmp_lt_i32_e32 vcc, -1, v89
	s_nop 1
	v_cndmask_b32_e32 v64, -1, v230, vcc
	v_xor_b32_e32 v64, v64, v89
	v_cmp_gt_i32_e32 vcc, s63, v155
	s_nop 1
	v_cndmask_b32_e32 v200, 0, v64, vcc
	v_cmp_lt_i32_e32 vcc, -1, v90
	s_nop 1
	v_cndmask_b32_e32 v64, -1, v230, vcc
	v_xor_b32_e32 v64, v64, v90
	v_cmp_ge_i32_e32 vcc, s63, v181
	s_nop 1
	v_cndmask_b32_e32 v198, 0, v64, vcc
	v_cmp_lt_i32_e32 vcc, -1, v91
	s_nop 1
	v_cndmask_b32_e32 v64, -1, v230, vcc
	v_xor_b32_e32 v64, v64, v91
	v_cmp_ge_i32_e32 vcc, s63, v156
	s_nop 1
	v_cndmask_b32_e32 v197, 0, v64, vcc
	s_cmp_lt_u32 s98, 6
	s_cbranch_scc1 .Ltr_b_end
	v_cmp_lt_i32_e32 vcc, -1, v80
	s_nop 1
	v_cndmask_b32_e32 v64, -1, v230, vcc
	v_xor_b32_e32 v64, v64, v80
	v_cmp_ge_i32_e32 vcc, s63, v157
	s_nop 1
	v_cndmask_b32_e32 v195, 0, v64, vcc
	v_cmp_lt_i32_e32 vcc, -1, v81
	s_nop 1
	v_cndmask_b32_e32 v64, -1, v230, vcc
	v_xor_b32_e32 v64, v64, v81
	v_cmp_gt_i32_e32 vcc, s63, v157
	s_nop 1
	v_cndmask_b32_e32 v196, 0, v64, vcc
	v_cmp_lt_i32_e32 vcc, -1, v82
	s_nop 1
	v_cndmask_b32_e32 v64, -1, v230, vcc
	v_xor_b32_e32 v64, v64, v82
	v_cmp_ge_i32_e32 vcc, s63, v182
	s_nop 1
	v_cndmask_b32_e32 v194, 0, v64, vcc
	v_cmp_lt_i32_e32 vcc, -1, v83
	s_nop 1
	v_cndmask_b32_e32 v64, -1, v230, vcc
	v_xor_b32_e32 v64, v64, v83
	v_cmp_ge_i32_e32 vcc, s63, v158
	s_nop 1
	v_cndmask_b32_e32 v193, 0, v64, vcc
	s_cmp_lt_u32 s98, 7
	s_cbranch_scc1 .Ltr_b_end
	v_cmp_lt_i32_e32 vcc, -1, v96
	s_nop 1
	v_cndmask_b32_e32 v64, -1, v230, vcc
	v_xor_b32_e32 v64, v64, v96
	v_cmp_ge_i32_e32 vcc, s63, v159
	s_waitcnt lgkmcnt(1)
	s_nop 0
	v_cndmask_b32_e32 v137, 0, v64, vcc
	v_cmp_lt_i32_e32 vcc, -1, v97
	s_nop 1
	v_cndmask_b32_e32 v64, -1, v230, vcc
	v_xor_b32_e32 v64, v64, v97
	v_cmp_gt_i32_e32 vcc, s63, v159
	s_nop 1
	v_cndmask_b32_e32 v192, 0, v64, vcc
	v_cmp_lt_i32_e32 vcc, -1, v98
	s_nop 1
	v_cndmask_b32_e32 v64, -1, v230, vcc
	v_xor_b32_e32 v64, v64, v98
	v_cmp_ge_i32_e32 vcc, s63, v183
	s_nop 1
	v_cndmask_b32_e32 v136, 0, v64, vcc
	v_cmp_lt_i32_e32 vcc, -1, v99
	s_nop 1
	v_cndmask_b32_e32 v64, -1, v230, vcc
	v_xor_b32_e32 v64, v64, v99
	v_cmp_ge_i32_e32 vcc, s63, v160
	s_nop 1
	v_cndmask_b32_e32 v99, 0, v64, vcc
	s_cmp_lt_u32 s98, 8
	s_cbranch_scc1 .Ltr_b_end
	v_cmp_lt_i32_e32 vcc, -1, v92
	s_nop 1
	v_cndmask_b32_e32 v64, -1, v230, vcc
	v_xor_b32_e32 v64, v64, v92
	v_cmp_ge_i32_e32 vcc, s63, v161
	s_nop 1
	v_cndmask_b32_e32 v97, 0, v64, vcc
	v_cmp_lt_i32_e32 vcc, -1, v93
	s_nop 1
	v_cndmask_b32_e32 v64, -1, v230, vcc
	v_xor_b32_e32 v64, v64, v93
	v_cmp_gt_i32_e32 vcc, s63, v161
	s_nop 1
	v_cndmask_b32_e32 v98, 0, v64, vcc
	v_cmp_lt_i32_e32 vcc, -1, v94
	s_nop 1
	v_cndmask_b32_e32 v64, -1, v230, vcc
	v_xor_b32_e32 v64, v64, v94
	v_cmp_ge_i32_e32 vcc, s63, v184
	s_nop 1
	v_cndmask_b32_e32 v96, 0, v64, vcc
	v_cmp_lt_i32_e32 vcc, -1, v95
	s_nop 1
	v_cndmask_b32_e32 v64, -1, v230, vcc
	v_xor_b32_e32 v64, v64, v95
	v_cmp_ge_i32_e32 vcc, s63, v162
	s_nop 1
	v_cndmask_b32_e32 v94, 0, v64, vcc
	s_cmp_lt_u32 s98, 9
	s_cbranch_scc1 .Ltr_b_end
	v_cmp_lt_i32_e32 vcc, -1, v104
	s_nop 1
	v_cndmask_b32_e32 v64, -1, v230, vcc
	v_xor_b32_e32 v64, v64, v104
	v_cmp_ge_i32_e32 vcc, s63, v163
	s_nop 1
	v_cndmask_b32_e32 v92, 0, v64, vcc
	v_cmp_lt_i32_e32 vcc, -1, v105
	s_nop 1
	v_cndmask_b32_e32 v64, -1, v230, vcc
	v_xor_b32_e32 v64, v64, v105
	v_cmp_gt_i32_e32 vcc, s63, v163
	s_nop 1
	v_cndmask_b32_e32 v93, 0, v64, vcc
	v_cmp_lt_i32_e32 vcc, -1, v106
	s_nop 1
	v_cndmask_b32_e32 v64, -1, v230, vcc
	v_xor_b32_e32 v64, v64, v106
	v_cmp_ge_i32_e32 vcc, s63, v185
	s_nop 1
	v_cndmask_b32_e32 v91, 0, v64, vcc
	v_cmp_lt_i32_e32 vcc, -1, v107
	s_nop 1
	v_cndmask_b32_e32 v64, -1, v230, vcc
	v_xor_b32_e32 v64, v64, v107
	v_cmp_ge_i32_e32 vcc, s63, v164
	s_nop 1
	v_cndmask_b32_e32 v90, 0, v64, vcc
	s_cmp_lt_u32 s98, 10
	s_cbranch_scc1 .Ltr_b_end
	v_cmp_lt_i32_e32 vcc, -1, v100
	s_nop 1
	v_cndmask_b32_e32 v64, -1, v230, vcc
	v_xor_b32_e32 v64, v64, v100
	v_cmp_ge_i32_e32 vcc, s63, v165
	s_nop 1
	v_cndmask_b32_e32 v88, 0, v64, vcc
	v_cmp_lt_i32_e32 vcc, -1, v101
	s_nop 1
	v_cndmask_b32_e32 v64, -1, v230, vcc
	v_xor_b32_e32 v64, v64, v101
	v_cmp_gt_i32_e32 vcc, s63, v165
	s_nop 1
	v_cndmask_b32_e32 v89, 0, v64, vcc
	v_cmp_lt_i32_e32 vcc, -1, v102
	s_nop 1
	v_cndmask_b32_e32 v64, -1, v230, vcc
	v_xor_b32_e32 v64, v64, v102
	v_cmp_ge_i32_e32 vcc, s63, v186
	s_nop 1
	v_cndmask_b32_e32 v87, 0, v64, vcc
	v_cmp_lt_i32_e32 vcc, -1, v103
	s_nop 1
	v_cndmask_b32_e32 v64, -1, v230, vcc
	v_xor_b32_e32 v64, v64, v103
	v_cmp_ge_i32_e32 vcc, s63, v166
	s_nop 1
	v_cndmask_b32_e32 v86, 0, v64, vcc
	s_cmp_lt_u32 s98, 11
	s_cbranch_scc1 .Ltr_b_end
	v_cmp_lt_i32_e32 vcc, -1, v112
	s_nop 1
	v_cndmask_b32_e32 v64, -1, v230, vcc
	v_xor_b32_e32 v64, v64, v112
	v_cmp_ge_i32_e32 vcc, s63, v167
	s_nop 1
	v_cndmask_b32_e32 v84, 0, v64, vcc
	v_cmp_lt_i32_e32 vcc, -1, v113
	s_nop 1
	v_cndmask_b32_e32 v64, -1, v230, vcc
	v_xor_b32_e32 v64, v64, v113
	v_cmp_gt_i32_e32 vcc, s63, v167
	s_nop 1
	v_cndmask_b32_e32 v85, 0, v64, vcc
	v_cmp_lt_i32_e32 vcc, -1, v114
	s_nop 1
	v_cndmask_b32_e32 v64, -1, v230, vcc
	v_xor_b32_e32 v64, v64, v114
	v_cmp_ge_i32_e32 vcc, s63, v187
	s_nop 1
	v_cndmask_b32_e32 v83, 0, v64, vcc
	v_cmp_lt_i32_e32 vcc, -1, v115
	s_nop 1
	v_cndmask_b32_e32 v64, -1, v230, vcc
	v_xor_b32_e32 v64, v64, v115
	v_cmp_ge_i32_e32 vcc, s63, v168
	s_nop 1
	v_cndmask_b32_e32 v82, 0, v64, vcc
	s_cmp_lt_u32 s98, 12
	s_cbranch_scc1 .Ltr_b_end
	v_cmp_lt_i32_e32 vcc, -1, v108
	s_nop 1
	v_cndmask_b32_e32 v64, -1, v230, vcc
	v_xor_b32_e32 v64, v64, v108
	v_cmp_ge_i32_e32 vcc, s63, v169
	s_nop 1
	v_cndmask_b32_e32 v80, 0, v64, vcc
	v_cmp_lt_i32_e32 vcc, -1, v109
	s_nop 1
	v_cndmask_b32_e32 v64, -1, v230, vcc
	v_xor_b32_e32 v64, v64, v109
	v_cmp_gt_i32_e32 vcc, s63, v169
	s_nop 1
	v_cndmask_b32_e32 v81, 0, v64, vcc
	v_cmp_lt_i32_e32 vcc, -1, v110
	s_nop 1
	v_cndmask_b32_e32 v64, -1, v230, vcc
	v_xor_b32_e32 v64, v64, v110
	v_cmp_ge_i32_e32 vcc, s63, v188
	s_nop 1
	v_cndmask_b32_e32 v79, 0, v64, vcc
	v_cmp_lt_i32_e32 vcc, -1, v111
	s_nop 1
	v_cndmask_b32_e32 v64, -1, v230, vcc
	v_xor_b32_e32 v64, v64, v111
	v_cmp_ge_i32_e32 vcc, s63, v170
	s_nop 1
	v_cndmask_b32_e32 v78, 0, v64, vcc
	s_cmp_lt_u32 s98, 13
	s_cbranch_scc1 .Ltr_b_end
	v_cmp_lt_i32_e32 vcc, -1, v120
	s_nop 1
	v_cndmask_b32_e32 v64, -1, v230, vcc
	v_xor_b32_e32 v64, v64, v120
	v_cmp_ge_i32_e32 vcc, s63, v171
	s_nop 1
	v_cndmask_b32_e32 v76, 0, v64, vcc
	v_cmp_lt_i32_e32 vcc, -1, v121
	s_nop 1
	v_cndmask_b32_e32 v64, -1, v230, vcc
	v_xor_b32_e32 v64, v64, v121
	v_cmp_gt_i32_e32 vcc, s63, v171
	s_nop 1
	v_cndmask_b32_e32 v77, 0, v64, vcc
	v_cmp_lt_i32_e32 vcc, -1, v122
	s_nop 1
	v_cndmask_b32_e32 v64, -1, v230, vcc
	v_xor_b32_e32 v64, v64, v122
	v_cmp_ge_i32_e32 vcc, s63, v189
	s_nop 1
	v_cndmask_b32_e32 v75, 0, v64, vcc
	v_cmp_lt_i32_e32 vcc, -1, v123
	s_nop 1
	v_cndmask_b32_e32 v64, -1, v230, vcc
	v_xor_b32_e32 v64, v64, v123
	v_cmp_ge_i32_e32 vcc, s63, v172
	s_nop 1
	v_cndmask_b32_e32 v74, 0, v64, vcc
	s_cmp_lt_u32 s98, 14
	s_cbranch_scc1 .Ltr_b_end
	v_cmp_lt_i32_e32 vcc, -1, v116
	s_nop 1
	v_cndmask_b32_e32 v64, -1, v230, vcc
	v_xor_b32_e32 v64, v64, v116
	v_cmp_ge_i32_e32 vcc, s63, v173
	s_nop 1
	v_cndmask_b32_e32 v72, 0, v64, vcc
	v_cmp_lt_i32_e32 vcc, -1, v117
	s_nop 1
	v_cndmask_b32_e32 v64, -1, v230, vcc
	v_xor_b32_e32 v64, v64, v117
	v_cmp_gt_i32_e32 vcc, s63, v173
	s_nop 1
	v_cndmask_b32_e32 v73, 0, v64, vcc
	v_cmp_lt_i32_e32 vcc, -1, v118
	s_nop 1
	v_cndmask_b32_e32 v64, -1, v230, vcc
	v_xor_b32_e32 v64, v64, v118
	v_cmp_ge_i32_e32 vcc, s63, v190
	s_nop 1
	v_cndmask_b32_e32 v71, 0, v64, vcc
	v_cmp_lt_i32_e32 vcc, -1, v119
	s_nop 1
	v_cndmask_b32_e32 v64, -1, v230, vcc
	v_xor_b32_e32 v64, v64, v119
	v_cmp_ge_i32_e32 vcc, s63, v174
	s_nop 1
	v_cndmask_b32_e32 v70, 0, v64, vcc
	s_cmp_lt_u32 s98, 15
	s_cbranch_scc1 .Ltr_b_end
	v_cmp_lt_i32_e32 vcc, -1, v124
	s_nop 1
	v_cndmask_b32_e32 v64, -1, v230, vcc
	v_xor_b32_e32 v64, v64, v124
	v_cmp_ge_i32_e32 vcc, s63, v175
	s_nop 1
	v_cndmask_b32_e32 v67, 0, v64, vcc
	v_cmp_lt_i32_e32 vcc, -1, v125
	s_nop 1
	v_cndmask_b32_e32 v64, -1, v230, vcc
	v_xor_b32_e32 v64, v64, v125
	v_cmp_gt_i32_e32 vcc, s63, v175
	s_nop 1
	v_cndmask_b32_e32 v68, 0, v64, vcc
	v_cmp_lt_i32_e32 vcc, -1, v126
	s_nop 1
	v_cndmask_b32_e32 v64, -1, v230, vcc
	v_xor_b32_e32 v64, v64, v126
	v_cmp_ge_i32_e32 vcc, s63, v191
	s_nop 1
	v_cndmask_b32_e32 v66, 0, v64, vcc
	v_cmp_lt_i32_e32 vcc, -1, v127
	s_nop 1
	v_cndmask_b32_e32 v64, -1, v230, vcc
	v_xor_b32_e32 v64, v64, v127
.Ltr_b_end:
	s_waitcnt lgkmcnt(0)
	v_cmp_gt_i32_e32 vcc, 1, v241
	v_cndmask_b32_e64 v69, 0, v64, s[50:51]
	s_cbranch_vccnz .LBB0_664
	s_add_i32 s50, s52, 0x21700
	v_mov_b32_e32 v64, s50
	ds_read_b32 v64, v64
	s_add_i32 s50, s52, 0x21500
	v_mov_b32_e32 v65, s50
	ds_read_b32 v95, v65
	s_waitcnt lgkmcnt(1)
	v_cmp_eq_u32_e32 vcc, v241, v64
	s_cbranch_vccnz .LBB0_665
	s_mov_b32 s65, 1
	v_mov_b32_e32 v64, 0
	s_mov_b32 s50, 24
	s_mov_b64 s[82:83], 0

.LBB0_674:
	s_mul_i32 s50, s62, 0x208
	s_add_i32 s62, s50, 0
	v_cmp_eq_u32_e64 s[50:51], v239, v64
	v_cmp_le_i32_e64 s[52:53], v208, v65
	v_cmp_gt_u32_e32 vcc, v239, v64
	s_and_b64 s[50:51], s[50:51], s[52:53]
	s_or_b64 s[50:51], vcc, s[50:51]
	v_cndmask_b32_e64 v95, 0, 1, s[50:51]
	v_cmp_eq_u32_e64 s[50:51], v240, v64
	v_cmp_lt_i32_e64 s[52:53], v208, v65
	v_cmp_gt_u32_e32 vcc, v240, v64
	s_and_b64 s[50:51], s[50:51], s[52:53]
	s_or_b64 s[50:51], vcc, s[50:51]
	v_cndmask_b32_e64 v100, 0, 2, s[50:51]
	v_cmp_eq_u32_e64 s[50:51], v238, v64
	v_cmp_le_i32_e64 s[52:53], v145, v65
	v_cmp_gt_u32_e32 vcc, v238, v64
	s_and_b64 s[50:51], s[50:51], s[52:53]
	s_or_b64 s[50:51], vcc, s[50:51]
	v_cndmask_b32_e64 v101, 0, 4, s[50:51]
	v_cmp_eq_u32_e64 s[50:51], v237, v64
	v_cmp_le_i32_e64 s[52:53], v146, v65
	v_cmp_gt_u32_e32 vcc, v237, v64
	s_and_b64 s[50:51], s[50:51], s[52:53]
	s_or_b64 s[50:51], vcc, s[50:51]
	v_cndmask_b32_e64 v102, 0, 8, s[50:51]
	v_or_b32_e32 v95, v100, v95
	v_or3_b32 v95, v95, v101, v102
	v_lshlrev_b32_e32 v95, v139, v95
	s_nop 1
	v_or_b32_dpp v95, v95, v95 quad_perm:[1,0,3,2] row_mask:0xf bank_mask:0xf
	s_add_i32 s62, s62, 0x18000
	s_waitcnt lgkmcnt(0)
	s_nop 1
	v_or_b32_dpp v95, v95, v95 quad_perm:[2,3,0,1] row_mask:0xf bank_mask:0xf
	s_waitcnt lgkmcnt(0)
	s_nop 1
	v_or_b32_dpp v95, v95, v95 row_half_mirror row_mask:0xf bank_mask:0xf
	s_and_saveexec_b64 s[50:51], s[56:57]
	s_cbranch_execz .LBB0_704
	s_waitcnt lgkmcnt(0)
	v_lshl_add_u32 v100, v140, 2, s62
	ds_write_b32 v100, v95
	s_or_b64 exec, exec, s[50:51]
	s_and_b64 vcc, exec, s[48:49]
	s_cbranch_vccz .LBB0_705

.LBB0_677:
	s_cmp_lt_u32 s98, 2
	s_cbranch_scc1 .Lmz_b_2
	v_cmp_eq_u32_e64 s[46:47], v213, v64
	v_cmp_le_i32_e64 s[48:49], v149, v65
	v_cmp_gt_u32_e32 vcc, v213, v64
	s_and_b64 s[46:47], s[46:47], s[48:49]
	s_or_b64 s[46:47], vcc, s[46:47]
	v_cndmask_b32_e64 v95, 0, 1, s[46:47]
	v_cmp_eq_u32_e64 s[46:47], v232, v64
	v_cmp_lt_i32_e64 s[48:49], v149, v65
	v_cmp_gt_u32_e32 vcc, v232, v64
	s_and_b64 s[46:47], s[46:47], s[48:49]
	s_or_b64 s[46:47], vcc, s[46:47]
	s_waitcnt lgkmcnt(0)
	v_cndmask_b32_e64 v100, 0, 2, s[46:47]
	v_cmp_eq_u32_e64 s[46:47], v212, v64
	v_cmp_le_i32_e64 s[48:49], v178, v65
	v_cmp_gt_u32_e32 vcc, v212, v64
	s_and_b64 s[46:47], s[46:47], s[48:49]
	s_or_b64 s[46:47], vcc, s[46:47]
	v_cndmask_b32_e64 v101, 0, 4, s[46:47]
	v_cmp_eq_u32_e64 s[46:47], v211, v64
	v_cmp_le_i32_e64 s[48:49], v150, v65
	v_cmp_gt_u32_e32 vcc, v211, v64
	s_and_b64 s[46:47], s[46:47], s[48:49]
	s_or_b64 s[46:47], vcc, s[46:47]
	v_cndmask_b32_e64 v102, 0, 8, s[46:47]
	v_or_b32_e32 v95, v100, v95
	v_or3_b32 v95, v95, v101, v102
	v_lshlrev_b32_e32 v95, v139, v95
	s_nop 1
	v_or_b32_dpp v95, v95, v95 quad_perm:[1,0,3,2] row_mask:0xf bank_mask:0xf
	s_waitcnt lgkmcnt(0)
	s_nop 1
	v_or_b32_dpp v95, v95, v95 quad_perm:[2,3,0,1] row_mask:0xf bank_mask:0xf
	s_waitcnt lgkmcnt(0)
	s_nop 1
	v_or_b32_dpp v95, v95, v95 row_half_mirror row_mask:0xf bank_mask:0xf
.Lmst_b_2:
	s_mov_b64 s[46:47], exec
	v_readlane_b32 s48, v247, 55
	v_readlane_b32 s49, v247, 56
	s_and_b64 s[48:49], s[46:47], s[48:49]
	s_mov_b64 exec, s[48:49]
	s_cbranch_execz .LBB0_679
	s_waitcnt lgkmcnt(0)
	v_lshl_add_u32 v100, v140, 2, s62
	ds_write_b32 v100, v95 offset:64

.LBB0_681:
	s_cmp_lt_u32 s98, 4
	s_cbranch_scc1 .Lmz_b_4
	v_cmp_eq_u32_e64 s[42:43], v203, v64
	v_cmp_le_i32_e64 s[44:45], v153, v65
	v_cmp_gt_u32_e32 vcc, v203, v64
	s_and_b64 s[42:43], s[42:43], s[44:45]
	s_or_b64 s[42:43], vcc, s[42:43]
	v_cndmask_b32_e64 v95, 0, 1, s[42:43]
	v_cmp_eq_u32_e64 s[42:43], v204, v64
	v_cmp_lt_i32_e64 s[44:45], v153, v65
	v_cmp_gt_u32_e32 vcc, v204, v64
	s_and_b64 s[42:43], s[42:43], s[44:45]
	s_or_b64 s[42:43], vcc, s[42:43]
	s_waitcnt lgkmcnt(0)
	v_cndmask_b32_e64 v100, 0, 2, s[42:43]
	v_cmp_eq_u32_e64 s[42:43], v202, v64
	v_cmp_le_i32_e64 s[44:45], v180, v65
	v_cmp_gt_u32_e32 vcc, v202, v64
	s_and_b64 s[42:43], s[42:43], s[44:45]
	s_or_b64 s[42:43], vcc, s[42:43]
	v_cndmask_b32_e64 v101, 0, 4, s[42:43]
	v_cmp_eq_u32_e64 s[42:43], v201, v64
	v_cmp_le_i32_e64 s[44:45], v154, v65
	v_cmp_gt_u32_e32 vcc, v201, v64
	s_and_b64 s[42:43], s[42:43], s[44:45]
	s_or_b64 s[42:43], vcc, s[42:43]
	v_cndmask_b32_e64 v102, 0, 8, s[42:43]
	v_or_b32_e32 v95, v100, v95
	v_or3_b32 v95, v95, v101, v102
	v_lshlrev_b32_e32 v95, v139, v95
	s_nop 1
	v_or_b32_dpp v95, v95, v95 quad_perm:[1,0,3,2] row_mask:0xf bank_mask:0xf
	s_waitcnt lgkmcnt(0)
	s_nop 1
	v_or_b32_dpp v95, v95, v95 quad_perm:[2,3,0,1] row_mask:0xf bank_mask:0xf
	s_waitcnt lgkmcnt(0)
	s_nop 1
	v_or_b32_dpp v95, v95, v95 row_half_mirror row_mask:0xf bank_mask:0xf
.Lmst_b_4:
	s_mov_b64 s[42:43], exec
	v_readlane_b32 s44, v247, 59
	v_readlane_b32 s45, v247, 60
	s_and_b64 s[44:45], s[42:43], s[44:45]
	s_mov_b64 exec, s[44:45]
	s_cbranch_execz .LBB0_683
	s_waitcnt lgkmcnt(0)
	v_lshl_add_u32 v100, v140, 2, s62
	ds_write_b32 v100, v95 offset:128

.LBB0_685:
	s_cmp_lt_u32 s98, 6
	s_cbranch_scc1 .Lmz_b_6
	v_cmp_eq_u32_e64 s[38:39], v195, v64
	v_cmp_le_i32_e64 s[40:41], v157, v65
	v_cmp_gt_u32_e32 vcc, v195, v64
	s_and_b64 s[38:39], s[38:39], s[40:41]
	s_or_b64 s[38:39], vcc, s[38:39]
	v_cndmask_b32_e64 v95, 0, 1, s[38:39]
	v_cmp_eq_u32_e64 s[38:39], v196, v64
	v_cmp_lt_i32_e64 s[40:41], v157, v65
	v_cmp_gt_u32_e32 vcc, v196, v64
	s_and_b64 s[38:39], s[38:39], s[40:41]
	s_or_b64 s[38:39], vcc, s[38:39]
	s_waitcnt lgkmcnt(0)
	v_cndmask_b32_e64 v100, 0, 2, s[38:39]
	v_cmp_eq_u32_e64 s[38:39], v194, v64
	v_cmp_le_i32_e64 s[40:41], v182, v65
	v_cmp_gt_u32_e32 vcc, v194, v64
	s_and_b64 s[38:39], s[38:39], s[40:41]
	s_or_b64 s[38:39], vcc, s[38:39]
	v_cndmask_b32_e64 v101, 0, 4, s[38:39]
	v_cmp_eq_u32_e64 s[38:39], v193, v64
	v_cmp_le_i32_e64 s[40:41], v158, v65
	v_cmp_gt_u32_e32 vcc, v193, v64
	s_and_b64 s[38:39], s[38:39], s[40:41]
	s_or_b64 s[38:39], vcc, s[38:39]
	v_cndmask_b32_e64 v102, 0, 8, s[38:39]
	v_or_b32_e32 v95, v100, v95
	v_or3_b32 v95, v95, v101, v102
	v_lshlrev_b32_e32 v95, v139, v95
	s_nop 1
	v_or_b32_dpp v95, v95, v95 quad_perm:[1,0,3,2] row_mask:0xf bank_mask:0xf
	s_waitcnt lgkmcnt(0)
	s_nop 1
	v_or_b32_dpp v95, v95, v95 quad_perm:[2,3,0,1] row_mask:0xf bank_mask:0xf
	s_waitcnt lgkmcnt(0)
	s_nop 1
	v_or_b32_dpp v95, v95, v95 row_half_mirror row_mask:0xf bank_mask:0xf
.Lmst_b_6:
	s_mov_b64 s[38:39], exec
	v_readlane_b32 s40, v247, 63
	v_readlane_b32 s41, v246, 0
	s_and_b64 s[40:41], s[38:39], s[40:41]
	s_mov_b64 exec, s[40:41]
	s_cbranch_execz .LBB0_687
	s_waitcnt lgkmcnt(0)
	v_lshl_add_u32 v100, v140, 2, s62
	ds_write_b32 v100, v95 offset:192

.LBB0_689:
	s_cmp_lt_u32 s98, 8
	s_cbranch_scc1 .Lmz_b_8
	v_cmp_eq_u32_e64 s[34:35], v97, v64
	v_cmp_le_i32_e64 s[36:37], v161, v65
	v_cmp_gt_u32_e32 vcc, v97, v64
	s_and_b64 s[34:35], s[34:35], s[36:37]
	s_or_b64 s[34:35], vcc, s[34:35]
	v_cndmask_b32_e64 v95, 0, 1, s[34:35]
	v_cmp_eq_u32_e64 s[34:35], v98, v64
	v_cmp_lt_i32_e64 s[36:37], v161, v65
	v_cmp_gt_u32_e32 vcc, v98, v64
	s_and_b64 s[34:35], s[34:35], s[36:37]
	s_or_b64 s[34:35], vcc, s[34:35]
	v_cndmask_b32_e64 v97, 0, 2, s[34:35]
	v_cmp_eq_u32_e64 s[34:35], v96, v64
	v_cmp_le_i32_e64 s[36:37], v184, v65
	v_cmp_gt_u32_e32 vcc, v96, v64
	s_and_b64 s[34:35], s[34:35], s[36:37]
	s_or_b64 s[34:35], vcc, s[34:35]
	v_cndmask_b32_e64 v96, 0, 4, s[34:35]
	v_cmp_eq_u32_e64 s[34:35], v94, v64
	v_cmp_le_i32_e64 s[36:37], v162, v65
	v_cmp_gt_u32_e32 vcc, v94, v64
	s_and_b64 s[34:35], s[34:35], s[36:37]
	s_or_b64 s[34:35], vcc, s[34:35]
	v_cndmask_b32_e64 v94, 0, 8, s[34:35]
	v_or_b32_e32 v95, v97, v95
	v_or3_b32 v94, v95, v96, v94
	v_lshlrev_b32_e32 v94, v139, v94
	s_nop 1
	v_or_b32_dpp v94, v94, v94 quad_perm:[1,0,3,2] row_mask:0xf bank_mask:0xf
	s_waitcnt lgkmcnt(0)
	s_nop 1
	v_or_b32_dpp v94, v94, v94 quad_perm:[2,3,0,1] row_mask:0xf bank_mask:0xf
	s_waitcnt lgkmcnt(0)
	s_nop 1
	v_or_b32_dpp v94, v94, v94 row_half_mirror row_mask:0xf bank_mask:0xf
.Lmst_b_8:
	s_mov_b64 s[34:35], exec
	v_readlane_b32 s36, v246, 3
	v_readlane_b32 s37, v246, 4
	s_and_b64 s[36:37], s[34:35], s[36:37]
	s_mov_b64 exec, s[36:37]
	s_cbranch_execz .LBB0_691
	s_waitcnt lgkmcnt(0)
	v_lshl_add_u32 v95, v140, 2, s62
	ds_write_b32 v95, v94 offset:256

.LBB0_693:
	s_cmp_lt_u32 s98, 10
	s_cbranch_scc1 .Lmz_b_10
	v_cmp_eq_u32_e64 s[28:29], v88, v64
	v_cmp_le_i32_e64 s[30:31], v165, v65
	v_cmp_gt_u32_e32 vcc, v88, v64
	s_and_b64 s[28:29], s[28:29], s[30:31]
	s_or_b64 s[28:29], vcc, s[28:29]
	v_cndmask_b32_e64 v88, 0, 1, s[28:29]
	v_cmp_eq_u32_e64 s[28:29], v89, v64
	v_cmp_lt_i32_e64 s[30:31], v165, v65
	v_cmp_gt_u32_e32 vcc, v89, v64
	s_and_b64 s[28:29], s[28:29], s[30:31]
	s_or_b64 s[28:29], vcc, s[28:29]
	v_cndmask_b32_e64 v89, 0, 2, s[28:29]
	v_cmp_eq_u32_e64 s[28:29], v87, v64
	v_cmp_le_i32_e64 s[30:31], v186, v65
	v_cmp_gt_u32_e32 vcc, v87, v64
	s_and_b64 s[28:29], s[28:29], s[30:31]
	s_or_b64 s[28:29], vcc, s[28:29]
	v_cndmask_b32_e64 v87, 0, 4, s[28:29]
	v_cmp_eq_u32_e64 s[28:29], v86, v64
	v_cmp_le_i32_e64 s[30:31], v166, v65
	v_cmp_gt_u32_e32 vcc, v86, v64
	s_and_b64 s[28:29], s[28:29], s[30:31]
	s_or_b64 s[28:29], vcc, s[28:29]
	v_cndmask_b32_e64 v86, 0, 8, s[28:29]
	v_or_b32_e32 v88, v89, v88
	v_or3_b32 v86, v88, v87, v86
	v_lshlrev_b32_e32 v86, v139, v86
	s_nop 1
	v_or_b32_dpp v86, v86, v86 quad_perm:[1,0,3,2] row_mask:0xf bank_mask:0xf
	s_waitcnt lgkmcnt(0)
	s_nop 1
	v_or_b32_dpp v86, v86, v86 quad_perm:[2,3,0,1] row_mask:0xf bank_mask:0xf
	s_waitcnt lgkmcnt(0)
	s_nop 1
	v_or_b32_dpp v86, v86, v86 row_half_mirror row_mask:0xf bank_mask:0xf
.Lmst_b_10:
	s_mov_b64 s[28:29], exec
	v_readlane_b32 s30, v246, 7
	v_readlane_b32 s31, v246, 8
	s_and_b64 s[30:31], s[28:29], s[30:31]
	s_mov_b64 exec, s[30:31]
	s_cbranch_execz .LBB0_695
	s_waitcnt lgkmcnt(0)
	v_lshl_add_u32 v87, v140, 2, s62
	ds_write_b32 v87, v86 offset:320

.LBB0_697:
	s_cmp_lt_u32 s98, 12
	s_cbranch_scc1 .Lmz_b_12
	v_cmp_eq_u32_e64 s[24:25], v80, v64
	v_cmp_le_i32_e64 s[26:27], v169, v65
	v_cmp_gt_u32_e32 vcc, v80, v64
	s_and_b64 s[24:25], s[24:25], s[26:27]
	s_or_b64 s[24:25], vcc, s[24:25]
	v_cndmask_b32_e64 v80, 0, 1, s[24:25]
	v_cmp_eq_u32_e64 s[24:25], v81, v64
	v_cmp_lt_i32_e64 s[26:27], v169, v65
	v_cmp_gt_u32_e32 vcc, v81, v64
	s_and_b64 s[24:25], s[24:25], s[26:27]
	s_or_b64 s[24:25], vcc, s[24:25]
	v_cndmask_b32_e64 v81, 0, 2, s[24:25]
	v_cmp_eq_u32_e64 s[24:25], v79, v64
	v_cmp_le_i32_e64 s[26:27], v188, v65
	v_cmp_gt_u32_e32 vcc, v79, v64
	s_and_b64 s[24:25], s[24:25], s[26:27]
	s_or_b64 s[24:25], vcc, s[24:25]
	v_cndmask_b32_e64 v79, 0, 4, s[24:25]
	v_cmp_eq_u32_e64 s[24:25], v78, v64
	v_cmp_le_i32_e64 s[26:27], v170, v65
	v_cmp_gt_u32_e32 vcc, v78, v64
	s_and_b64 s[24:25], s[24:25], s[26:27]
	s_or_b64 s[24:25], vcc, s[24:25]
	v_cndmask_b32_e64 v78, 0, 8, s[24:25]
	v_or_b32_e32 v80, v81, v80
	v_or3_b32 v78, v80, v79, v78
	v_lshlrev_b32_e32 v78, v139, v78
	s_nop 1
	v_or_b32_dpp v78, v78, v78 quad_perm:[1,0,3,2] row_mask:0xf bank_mask:0xf
	s_waitcnt lgkmcnt(0)
	s_nop 1
	v_or_b32_dpp v78, v78, v78 quad_perm:[2,3,0,1] row_mask:0xf bank_mask:0xf
	s_waitcnt lgkmcnt(0)
	s_nop 1
	v_or_b32_dpp v78, v78, v78 row_half_mirror row_mask:0xf bank_mask:0xf
.Lmst_b_12:
	s_mov_b64 s[24:25], exec
	v_readlane_b32 s26, v246, 11
	v_readlane_b32 s27, v246, 12
	s_and_b64 s[26:27], s[24:25], s[26:27]
	s_mov_b64 exec, s[26:27]
	s_cbranch_execz .LBB0_699
	s_waitcnt lgkmcnt(0)
	v_lshl_add_u32 v79, v140, 2, s62
	ds_write_b32 v79, v78 offset:384

.LBB0_701:
	s_cmp_lt_u32 s98, 14
	s_cbranch_scc1 .Lmz_b_14
	v_cmp_eq_u32_e64 s[20:21], v72, v64
	v_cmp_le_i32_e64 s[22:23], v173, v65
	v_cmp_gt_u32_e32 vcc, v72, v64
	s_and_b64 s[20:21], s[20:21], s[22:23]
	s_or_b64 s[20:21], vcc, s[20:21]
	v_cndmask_b32_e64 v72, 0, 1, s[20:21]
	v_cmp_eq_u32_e64 s[20:21], v73, v64
	v_cmp_lt_i32_e64 s[22:23], v173, v65
	v_cmp_gt_u32_e32 vcc, v73, v64
	s_and_b64 s[20:21], s[20:21], s[22:23]
	s_or_b64 s[20:21], vcc, s[20:21]
	v_cndmask_b32_e64 v73, 0, 2, s[20:21]
	v_cmp_eq_u32_e64 s[20:21], v71, v64
	v_cmp_le_i32_e64 s[22:23], v190, v65
	v_cmp_gt_u32_e32 vcc, v71, v64
	s_and_b64 s[20:21], s[20:21], s[22:23]
	s_or_b64 s[20:21], vcc, s[20:21]
	v_cndmask_b32_e64 v71, 0, 4, s[20:21]
	v_cmp_eq_u32_e64 s[20:21], v70, v64
	v_cmp_le_i32_e64 s[22:23], v174, v65
	v_cmp_gt_u32_e32 vcc, v70, v64
	s_and_b64 s[20:21], s[20:21], s[22:23]
	s_or_b64 s[20:21], vcc, s[20:21]
	v_cndmask_b32_e64 v70, 0, 8, s[20:21]
	v_or_b32_e32 v72, v73, v72
	v_or3_b32 v70, v72, v71, v70
	v_lshlrev_b32_e32 v70, v139, v70
	s_nop 1
	v_or_b32_dpp v70, v70, v70 quad_perm:[1,0,3,2] row_mask:0xf bank_mask:0xf
	s_waitcnt lgkmcnt(0)
	s_nop 1
	v_or_b32_dpp v70, v70, v70 quad_perm:[2,3,0,1] row_mask:0xf bank_mask:0xf
	s_waitcnt lgkmcnt(0)
	s_nop 1
	v_or_b32_dpp v70, v70, v70 row_half_mirror row_mask:0xf bank_mask:0xf
.Lmst_b_14:
	s_mov_b64 s[20:21], exec
	v_readlane_b32 s22, v246, 15
	v_readlane_b32 s23, v246, 16
	s_and_b64 s[22:23], s[20:21], s[22:23]
	s_mov_b64 exec, s[22:23]
	s_cbranch_execz .LBB0_703
	s_waitcnt lgkmcnt(0)
	v_lshl_add_u32 v71, v140, 2, s62
	ds_write_b32 v71, v70 offset:448

.LBB0_705:
	s_cmp_lt_u32 s98, 1
	s_cbranch_scc1 .Lmz_b_1
	v_cmp_eq_u32_e64 s[48:49], v235, v64
	v_cmp_le_i32_e64 s[50:51], v147, v65
	v_cmp_gt_u32_e32 vcc, v235, v64
	s_and_b64 s[48:49], s[48:49], s[50:51]
	s_or_b64 s[48:49], vcc, s[48:49]
	v_cndmask_b32_e64 v95, 0, 1, s[48:49]
	v_cmp_eq_u32_e64 s[48:49], v236, v64
	v_cmp_lt_i32_e64 s[50:51], v147, v65
	v_cmp_gt_u32_e32 vcc, v236, v64
	s_and_b64 s[48:49], s[48:49], s[50:51]
	s_or_b64 s[48:49], vcc, s[48:49]
	s_waitcnt lgkmcnt(0)
	v_cndmask_b32_e64 v100, 0, 2, s[48:49]
	v_cmp_eq_u32_e64 s[48:49], v234, v64
	v_cmp_le_i32_e64 s[50:51], v177, v65
	v_cmp_gt_u32_e32 vcc, v234, v64
	s_and_b64 s[48:49], s[48:49], s[50:51]
	s_or_b64 s[48:49], vcc, s[48:49]
	v_cndmask_b32_e64 v101, 0, 4, s[48:49]
	v_cmp_eq_u32_e64 s[48:49], v233, v64
	v_cmp_le_i32_e64 s[50:51], v148, v65
	v_cmp_gt_u32_e32 vcc, v233, v64
	s_and_b64 s[48:49], s[48:49], s[50:51]
	s_or_b64 s[48:49], vcc, s[48:49]
	v_cndmask_b32_e64 v102, 0, 8, s[48:49]
	v_or_b32_e32 v95, v100, v95
	v_or3_b32 v95, v95, v101, v102
	v_lshlrev_b32_e32 v95, v139, v95
	s_nop 1
	v_or_b32_dpp v95, v95, v95 quad_perm:[1,0,3,2] row_mask:0xf bank_mask:0xf
	s_waitcnt lgkmcnt(0)
	s_nop 1
	v_or_b32_dpp v95, v95, v95 quad_perm:[2,3,0,1] row_mask:0xf bank_mask:0xf
	s_waitcnt lgkmcnt(0)
	s_nop 1
	v_or_b32_dpp v95, v95, v95 row_half_mirror row_mask:0xf bank_mask:0xf
.Lmst_b_1:
	s_mov_b64 s[48:49], exec
	v_readlane_b32 s50, v247, 53
	v_readlane_b32 s51, v247, 54
	s_and_b64 s[50:51], s[48:49], s[50:51]
	s_mov_b64 exec, s[50:51]
	s_cbranch_execz .LBB0_707
	s_waitcnt lgkmcnt(0)
	v_lshl_add_u32 v100, v140, 2, s62
	ds_write_b32 v100, v95 offset:32

.LBB0_709:
	s_cmp_lt_u32 s98, 3
	s_cbranch_scc1 .Lmz_b_3
	v_cmp_eq_u32_e64 s[44:45], v207, v64
	v_cmp_le_i32_e64 s[46:47], v151, v65
	v_cmp_gt_u32_e32 vcc, v207, v64
	s_and_b64 s[44:45], s[44:45], s[46:47]
	s_or_b64 s[44:45], vcc, s[44:45]
	v_cndmask_b32_e64 v95, 0, 1, s[44:45]
	v_cmp_eq_u32_e64 s[44:45], v210, v64
	v_cmp_lt_i32_e64 s[46:47], v151, v65
	v_cmp_gt_u32_e32 vcc, v210, v64
	s_and_b64 s[44:45], s[44:45], s[46:47]
	s_or_b64 s[44:45], vcc, s[44:45]
	s_waitcnt lgkmcnt(0)
	v_cndmask_b32_e64 v100, 0, 2, s[44:45]
	v_cmp_eq_u32_e64 s[44:45], v206, v64
	v_cmp_le_i32_e64 s[46:47], v179, v65
	v_cmp_gt_u32_e32 vcc, v206, v64
	s_and_b64 s[44:45], s[44:45], s[46:47]
	s_or_b64 s[44:45], vcc, s[44:45]
	v_cndmask_b32_e64 v101, 0, 4, s[44:45]
	v_cmp_eq_u32_e64 s[44:45], v205, v64
	v_cmp_le_i32_e64 s[46:47], v152, v65
	v_cmp_gt_u32_e32 vcc, v205, v64
	s_and_b64 s[44:45], s[44:45], s[46:47]
	s_or_b64 s[44:45], vcc, s[44:45]
	v_cndmask_b32_e64 v102, 0, 8, s[44:45]
	v_or_b32_e32 v95, v100, v95
	v_or3_b32 v95, v95, v101, v102
	v_lshlrev_b32_e32 v95, v139, v95
	s_nop 1
	v_or_b32_dpp v95, v95, v95 quad_perm:[1,0,3,2] row_mask:0xf bank_mask:0xf
	s_waitcnt lgkmcnt(0)
	s_nop 1
	v_or_b32_dpp v95, v95, v95 quad_perm:[2,3,0,1] row_mask:0xf bank_mask:0xf
	s_waitcnt lgkmcnt(0)
	s_nop 1
	v_or_b32_dpp v95, v95, v95 row_half_mirror row_mask:0xf bank_mask:0xf
.Lmst_b_3:
	s_mov_b64 s[44:45], exec
	v_readlane_b32 s46, v247, 57
	v_readlane_b32 s47, v247, 58
	s_and_b64 s[46:47], s[44:45], s[46:47]
	s_mov_b64 exec, s[46:47]
	s_cbranch_execz .LBB0_711
	s_waitcnt lgkmcnt(0)
	v_lshl_add_u32 v100, v140, 2, s62
	ds_write_b32 v100, v95 offset:96

.LBB0_713:
	s_cmp_lt_u32 s98, 5
	s_cbranch_scc1 .Lmz_b_5
	v_cmp_eq_u32_e64 s[40:41], v199, v64
	v_cmp_le_i32_e64 s[42:43], v155, v65
	v_cmp_gt_u32_e32 vcc, v199, v64
	s_and_b64 s[40:41], s[40:41], s[42:43]
	s_or_b64 s[40:41], vcc, s[40:41]
	v_cndmask_b32_e64 v95, 0, 1, s[40:41]
	v_cmp_eq_u32_e64 s[40:41], v200, v64
	v_cmp_lt_i32_e64 s[42:43], v155, v65
	v_cmp_gt_u32_e32 vcc, v200, v64
	s_and_b64 s[40:41], s[40:41], s[42:43]
	s_or_b64 s[40:41], vcc, s[40:41]
	s_waitcnt lgkmcnt(0)
	v_cndmask_b32_e64 v100, 0, 2, s[40:41]
	v_cmp_eq_u32_e64 s[40:41], v198, v64
	v_cmp_le_i32_e64 s[42:43], v181, v65
	v_cmp_gt_u32_e32 vcc, v198, v64
	s_and_b64 s[40:41], s[40:41], s[42:43]
	s_or_b64 s[40:41], vcc, s[40:41]
	v_cndmask_b32_e64 v101, 0, 4, s[40:41]
	v_cmp_eq_u32_e64 s[40:41], v197, v64
	v_cmp_le_i32_e64 s[42:43], v156, v65
	v_cmp_gt_u32_e32 vcc, v197, v64
	s_and_b64 s[40:41], s[40:41], s[42:43]
	s_or_b64 s[40:41], vcc, s[40:41]
	v_cndmask_b32_e64 v102, 0, 8, s[40:41]
	v_or_b32_e32 v95, v100, v95
	v_or3_b32 v95, v95, v101, v102
	v_lshlrev_b32_e32 v95, v139, v95
	s_nop 1
	v_or_b32_dpp v95, v95, v95 quad_perm:[1,0,3,2] row_mask:0xf bank_mask:0xf
	s_waitcnt lgkmcnt(0)
	s_nop 1
	v_or_b32_dpp v95, v95, v95 quad_perm:[2,3,0,1] row_mask:0xf bank_mask:0xf
	s_waitcnt lgkmcnt(0)
	s_nop 1
	v_or_b32_dpp v95, v95, v95 row_half_mirror row_mask:0xf bank_mask:0xf
.Lmst_b_5:
	s_mov_b64 s[40:41], exec
	v_readlane_b32 s42, v247, 61
	v_readlane_b32 s43, v247, 62
	s_and_b64 s[42:43], s[40:41], s[42:43]
	s_mov_b64 exec, s[42:43]
	s_cbranch_execz .LBB0_715
	s_waitcnt lgkmcnt(0)
	v_lshl_add_u32 v100, v140, 2, s62
	ds_write_b32 v100, v95 offset:160

.LBB0_717:
	s_cmp_lt_u32 s98, 7
	s_cbranch_scc1 .Lmz_b_7
	v_cmp_eq_u32_e64 s[36:37], v137, v64
	v_cmp_le_i32_e64 s[38:39], v159, v65
	v_cmp_gt_u32_e32 vcc, v137, v64
	s_and_b64 s[36:37], s[36:37], s[38:39]
	s_or_b64 s[36:37], vcc, s[36:37]
	v_cndmask_b32_e64 v95, 0, 1, s[36:37]
	v_cmp_eq_u32_e64 s[36:37], v192, v64
	v_cmp_lt_i32_e64 s[38:39], v159, v65
	v_cmp_gt_u32_e32 vcc, v192, v64
	s_and_b64 s[36:37], s[36:37], s[38:39]
	s_or_b64 s[36:37], vcc, s[36:37]
	s_waitcnt lgkmcnt(0)
	v_cndmask_b32_e64 v100, 0, 2, s[36:37]
	v_cmp_eq_u32_e64 s[36:37], v136, v64
	v_cmp_le_i32_e64 s[38:39], v183, v65
	v_cmp_gt_u32_e32 vcc, v136, v64
	s_and_b64 s[36:37], s[36:37], s[38:39]
	s_or_b64 s[36:37], vcc, s[36:37]
	v_cndmask_b32_e64 v101, 0, 4, s[36:37]
	v_cmp_eq_u32_e64 s[36:37], v99, v64
	v_cmp_le_i32_e64 s[38:39], v160, v65
	v_cmp_gt_u32_e32 vcc, v99, v64
	s_and_b64 s[36:37], s[36:37], s[38:39]
	s_or_b64 s[36:37], vcc, s[36:37]
	v_cndmask_b32_e64 v99, 0, 8, s[36:37]
	v_or_b32_e32 v95, v100, v95
	v_or3_b32 v95, v95, v101, v99
	v_lshlrev_b32_e32 v95, v139, v95
	s_nop 1
	v_or_b32_dpp v95, v95, v95 quad_perm:[1,0,3,2] row_mask:0xf bank_mask:0xf
	s_waitcnt lgkmcnt(0)
	s_nop 1
	v_or_b32_dpp v95, v95, v95 quad_perm:[2,3,0,1] row_mask:0xf bank_mask:0xf
	s_waitcnt lgkmcnt(0)
	s_nop 1
	v_or_b32_dpp v95, v95, v95 row_half_mirror row_mask:0xf bank_mask:0xf
.Lmst_b_7:
	s_mov_b64 s[36:37], exec
	v_readlane_b32 s38, v246, 1
	v_readlane_b32 s39, v246, 2
	s_and_b64 s[38:39], s[36:37], s[38:39]
	s_mov_b64 exec, s[38:39]
	s_cbranch_execz .LBB0_719
	s_waitcnt lgkmcnt(0)
	v_lshl_add_u32 v99, v140, 2, s62
	ds_write_b32 v99, v95 offset:224

.LBB0_721:
	s_cmp_lt_u32 s98, 9
	s_cbranch_scc1 .Lmz_b_9
	v_cmp_eq_u32_e64 s[30:31], v92, v64
	v_cmp_le_i32_e64 s[34:35], v163, v65
	v_cmp_gt_u32_e32 vcc, v92, v64
	s_and_b64 s[30:31], s[30:31], s[34:35]
	s_or_b64 s[30:31], vcc, s[30:31]
	v_cndmask_b32_e64 v92, 0, 1, s[30:31]
	v_cmp_eq_u32_e64 s[30:31], v93, v64
	v_cmp_lt_i32_e64 s[34:35], v163, v65
	v_cmp_gt_u32_e32 vcc, v93, v64
	s_and_b64 s[30:31], s[30:31], s[34:35]
	s_or_b64 s[30:31], vcc, s[30:31]
	v_cndmask_b32_e64 v93, 0, 2, s[30:31]
	v_cmp_eq_u32_e64 s[30:31], v91, v64
	v_cmp_le_i32_e64 s[34:35], v185, v65
	v_cmp_gt_u32_e32 vcc, v91, v64
	s_and_b64 s[30:31], s[30:31], s[34:35]
	s_or_b64 s[30:31], vcc, s[30:31]
	v_cndmask_b32_e64 v91, 0, 4, s[30:31]
	v_cmp_eq_u32_e64 s[30:31], v90, v64
	v_cmp_le_i32_e64 s[34:35], v164, v65
	v_cmp_gt_u32_e32 vcc, v90, v64
	s_and_b64 s[30:31], s[30:31], s[34:35]
	s_or_b64 s[30:31], vcc, s[30:31]
	v_cndmask_b32_e64 v90, 0, 8, s[30:31]
	v_or_b32_e32 v92, v93, v92
	v_or3_b32 v90, v92, v91, v90
	v_lshlrev_b32_e32 v90, v139, v90
	s_nop 1
	v_or_b32_dpp v90, v90, v90 quad_perm:[1,0,3,2] row_mask:0xf bank_mask:0xf
	s_waitcnt lgkmcnt(0)
	s_nop 1
	v_or_b32_dpp v90, v90, v90 quad_perm:[2,3,0,1] row_mask:0xf bank_mask:0xf
	s_waitcnt lgkmcnt(0)
	s_nop 1
	v_or_b32_dpp v90, v90, v90 row_half_mirror row_mask:0xf bank_mask:0xf
.Lmst_b_9:
	s_mov_b64 s[30:31], exec
	v_readlane_b32 s34, v246, 5
	v_readlane_b32 s35, v246, 6
	s_and_b64 s[34:35], s[30:31], s[34:35]
	s_mov_b64 exec, s[34:35]
	s_cbranch_execz .LBB0_723
	s_waitcnt lgkmcnt(0)
	v_lshl_add_u32 v91, v140, 2, s62
	ds_write_b32 v91, v90 offset:288

.LBB0_725:
	s_cmp_lt_u32 s98, 11
	s_cbranch_scc1 .Lmz_b_11
	v_cmp_eq_u32_e64 s[26:27], v84, v64
	v_cmp_le_i32_e64 s[28:29], v167, v65
	v_cmp_gt_u32_e32 vcc, v84, v64
	s_and_b64 s[26:27], s[26:27], s[28:29]
	s_or_b64 s[26:27], vcc, s[26:27]
	v_cndmask_b32_e64 v84, 0, 1, s[26:27]
	v_cmp_eq_u32_e64 s[26:27], v85, v64
	v_cmp_lt_i32_e64 s[28:29], v167, v65
	v_cmp_gt_u32_e32 vcc, v85, v64
	s_and_b64 s[26:27], s[26:27], s[28:29]
	s_or_b64 s[26:27], vcc, s[26:27]
	v_cndmask_b32_e64 v85, 0, 2, s[26:27]
	v_cmp_eq_u32_e64 s[26:27], v83, v64
	v_cmp_le_i32_e64 s[28:29], v187, v65
	v_cmp_gt_u32_e32 vcc, v83, v64
	s_and_b64 s[26:27], s[26:27], s[28:29]
	s_or_b64 s[26:27], vcc, s[26:27]
	v_cndmask_b32_e64 v83, 0, 4, s[26:27]
	v_cmp_eq_u32_e64 s[26:27], v82, v64
	v_cmp_le_i32_e64 s[28:29], v168, v65
	v_cmp_gt_u32_e32 vcc, v82, v64
	s_and_b64 s[26:27], s[26:27], s[28:29]
	s_or_b64 s[26:27], vcc, s[26:27]
	v_cndmask_b32_e64 v82, 0, 8, s[26:27]
	v_or_b32_e32 v84, v85, v84
	v_or3_b32 v82, v84, v83, v82
	v_lshlrev_b32_e32 v82, v139, v82
	s_nop 1
	v_or_b32_dpp v82, v82, v82 quad_perm:[1,0,3,2] row_mask:0xf bank_mask:0xf
	s_waitcnt lgkmcnt(0)
	s_nop 1
	v_or_b32_dpp v82, v82, v82 quad_perm:[2,3,0,1] row_mask:0xf bank_mask:0xf
	s_waitcnt lgkmcnt(0)
	s_nop 1
	v_or_b32_dpp v82, v82, v82 row_half_mirror row_mask:0xf bank_mask:0xf
.Lmst_b_11:
	s_mov_b64 s[26:27], exec
	v_readlane_b32 s28, v246, 9
	v_readlane_b32 s29, v246, 10
	s_and_b64 s[28:29], s[26:27], s[28:29]
	s_mov_b64 exec, s[28:29]
	s_cbranch_execz .LBB0_727
	s_waitcnt lgkmcnt(0)
	v_lshl_add_u32 v83, v140, 2, s62
	ds_write_b32 v83, v82 offset:352

.LBB0_729:
	s_cmp_lt_u32 s98, 13
	s_cbranch_scc1 .Lmz_b_13
	v_cmp_eq_u32_e64 s[22:23], v76, v64
	v_cmp_le_i32_e64 s[24:25], v171, v65
	v_cmp_gt_u32_e32 vcc, v76, v64
	s_and_b64 s[22:23], s[22:23], s[24:25]
	s_or_b64 s[22:23], vcc, s[22:23]
	v_cndmask_b32_e64 v76, 0, 1, s[22:23]
	v_cmp_eq_u32_e64 s[22:23], v77, v64
	v_cmp_lt_i32_e64 s[24:25], v171, v65
	v_cmp_gt_u32_e32 vcc, v77, v64
	s_and_b64 s[22:23], s[22:23], s[24:25]
	s_or_b64 s[22:23], vcc, s[22:23]
	v_cndmask_b32_e64 v77, 0, 2, s[22:23]
	v_cmp_eq_u32_e64 s[22:23], v75, v64
	v_cmp_le_i32_e64 s[24:25], v189, v65
	v_cmp_gt_u32_e32 vcc, v75, v64
	s_and_b64 s[22:23], s[22:23], s[24:25]
	s_or_b64 s[22:23], vcc, s[22:23]
	v_cndmask_b32_e64 v75, 0, 4, s[22:23]
	v_cmp_eq_u32_e64 s[22:23], v74, v64
	v_cmp_le_i32_e64 s[24:25], v172, v65
	v_cmp_gt_u32_e32 vcc, v74, v64
	s_and_b64 s[22:23], s[22:23], s[24:25]
	s_or_b64 s[22:23], vcc, s[22:23]
	v_cndmask_b32_e64 v74, 0, 8, s[22:23]
	v_or_b32_e32 v76, v77, v76
	v_or3_b32 v74, v76, v75, v74
	v_lshlrev_b32_e32 v74, v139, v74
	s_nop 1
	v_or_b32_dpp v74, v74, v74 quad_perm:[1,0,3,2] row_mask:0xf bank_mask:0xf
	s_waitcnt lgkmcnt(0)
	s_nop 1
	v_or_b32_dpp v74, v74, v74 quad_perm:[2,3,0,1] row_mask:0xf bank_mask:0xf
	s_waitcnt lgkmcnt(0)
	s_nop 1
	v_or_b32_dpp v74, v74, v74 row_half_mirror row_mask:0xf bank_mask:0xf
.Lmst_b_13:
	s_mov_b64 s[22:23], exec
	v_readlane_b32 s24, v246, 13
	v_readlane_b32 s25, v246, 14
	s_and_b64 s[24:25], s[22:23], s[24:25]
	s_mov_b64 exec, s[24:25]
	s_cbranch_execz .LBB0_731
	s_waitcnt lgkmcnt(0)
	v_lshl_add_u32 v75, v140, 2, s62
	ds_write_b32 v75, v74 offset:416

.LBB0_733:
	s_cmp_lt_u32 s98, 15
	s_cbranch_scc1 .Lmz_b_15
	v_cmp_eq_u32_e64 s[18:19], v67, v64
	v_cmp_le_i32_e64 s[20:21], v175, v65
	v_cmp_gt_u32_e32 vcc, v67, v64
	s_and_b64 s[18:19], s[18:19], s[20:21]
	s_or_b64 s[18:19], vcc, s[18:19]
	v_cndmask_b32_e64 v67, 0, 1, s[18:19]
	v_cmp_eq_u32_e64 s[18:19], v68, v64
	v_cmp_lt_i32_e64 s[20:21], v175, v65
	v_cmp_gt_u32_e32 vcc, v68, v64
	s_and_b64 s[18:19], s[18:19], s[20:21]
	s_or_b64 s[18:19], vcc, s[18:19]
	v_cndmask_b32_e64 v68, 0, 2, s[18:19]
	v_cmp_eq_u32_e64 s[18:19], v66, v64
	v_cmp_le_i32_e64 s[20:21], v191, v65
	v_cmp_gt_u32_e32 vcc, v66, v64
	s_and_b64 s[18:19], s[18:19], s[20:21]
	s_or_b64 s[18:19], vcc, s[18:19]
	v_cndmask_b32_e64 v66, 0, 4, s[18:19]
	v_cmp_eq_u32_e64 s[18:19], v69, v64
	v_cmp_le_i32_e64 s[20:21], v176, v65
	v_cmp_gt_u32_e32 vcc, v69, v64
	s_and_b64 s[18:19], s[18:19], s[20:21]
	s_or_b64 s[18:19], vcc, s[18:19]
	v_cndmask_b32_e64 v64, 0, 8, s[18:19]
	v_or_b32_e32 v65, v68, v67
	v_or3_b32 v64, v65, v66, v64
	v_lshlrev_b32_e32 v64, v139, v64
	s_nop 1
	v_or_b32_dpp v64, v64, v64 quad_perm:[1,0,3,2] row_mask:0xf bank_mask:0xf
	s_waitcnt lgkmcnt(0)
	s_nop 1
	v_or_b32_dpp v64, v64, v64 quad_perm:[2,3,0,1] row_mask:0xf bank_mask:0xf
	s_waitcnt lgkmcnt(0)
	s_nop 1
	v_or_b32_dpp v64, v64, v64 row_half_mirror row_mask:0xf bank_mask:0xf
.Lmst_b_15:
	s_mov_b64 s[18:19], exec
	v_readlane_b32 s20, v246, 17
	v_readlane_b32 s21, v246, 18
	s_and_b64 s[20:21], s[18:19], s[20:21]
	s_mov_b64 exec, s[20:21]
	s_cbranch_execz .LBB0_519
	s_waitcnt lgkmcnt(0)
	v_lshl_add_u32 v65, v140, 2, s62
	ds_write_b32 v65, v64 offset:480
	s_branch .LBB0_519
.Lmz_a_2:
	v_mov_b32_e32 v136, 0
	s_branch .Lmst_a_2

.Lmz_b_2:
	v_mov_b32_e32 v95, 0
	s_branch .Lmst_b_2

.Lmz_b_8:
	v_mov_b32_e32 v94, 0
	s_branch .Lmst_b_8
.Lmz_b_10:
	v_mov_b32_e32 v86, 0
	s_branch .Lmst_b_10
.Lmz_b_12:
	v_mov_b32_e32 v78, 0
	s_branch .Lmst_b_12
.Lmz_b_14:
	v_mov_b32_e32 v70, 0
	s_branch .Lmst_b_14

.Lmz_b_9:
	v_mov_b32_e32 v90, 0
	s_branch .Lmst_b_9
.Lmz_b_11:
	v_mov_b32_e32 v82, 0
	s_branch .Lmst_b_11
.Lmz_b_13:
	v_mov_b32_e32 v74, 0
	s_branch .Lmst_b_13
.Lmz_b_15:
	v_mov_b32_e32 v64, 0
	s_branch .Lmst_b_15

; #define PG8_STAGE(bufoff, gbase, voff) do { _Pragma("unroll") for (int _i = 0; _i < 2; ++_i) \
;         __builtin_amdgcn_global_load_lds((const unsigned*)((const char*)(gbase) + (voff)[_i]), (PG8_LAS unsigned*)(lds + (bufoff) + ldsw + _i * 8192), 16, 0, 0); } while (0)
; #define PG8_LDA(dst, b, h) do { _Pragma("unroll") for (int m = 0; m < 4; ++m) _Pragma("unroll") for (int k = 0; k < 2; ++k) dst[m][k] = *(const PG8_LAS bf16x8*)(lds + PG8_SA(b, h) + aoff + m * 2048 + k * 1024); } while (0)
; #define PG8_LDB(dst, b, h) do { _Pragma("unroll") for (int n = 0; n < 2; ++n) _Pragma("unroll") for (int k = 0; k < 2; ++k) dst[n][k] = *(const PG8_LAS bf16x8*)(lds + PG8_SB(b, h) + boff + n * 2048 + k * 1024); } while (0)
; #define PG8_MMA(ai, bj, At, Bt) do { __builtin_amdgcn_s_setprio(1); _Pragma("unroll") for (int m = 0; m < 4; ++m) _Pragma("unroll") for (int n = 0; n < 2; ++n) _Pragma("unroll") for (int k = 0; k < 2; ++k) \
;         acc[ai][bj][m][n] = __builtin_amdgcn_mfma_f32_16x16x32_bf16(Bt[n][k], At[m][k], acc[ai][bj][m][n], 0, 0, 0); __builtin_amdgcn_s_setprio(0); } while (0)
; #define PG8_WAIT_V(n) asm volatile("s_waitcnt vmcnt(" #n ")" ::: "memory")
; #define PG8_WAIT_L(n) asm volatile("s_waitcnt lgkmcnt(" #n ")" ::: "memory")
; #define PG8_BAR __builtin_amdgcn_s_barrier()
; #define PG8_SCHED __builtin_amdgcn_sched_barrier(0)
; template <class Epi, class Sched, bool ALIGN_EPI = false, bool SP2 = false>
; __device__ __forceinline__ void gemm_phase(PG8_LAS unsigned char* lds, const Gemm g, const Sched& S, const Epi& E, const int wv) {
;     ...
;             PG8_LDB(B0, 0, 0); PG8_LDB(B1, 0, 1); PG8_SCHED; PG8_LDA(At, 0, 0); PG8_STAGE(PG8_SA(1, 1), a1 + hstep, voffA);
;             PG8_WAIT_V(8); PG8_WAIT_L(0); PG8_BAR; PG8_MMA(0, 0, At, B0); PG8_MMA(0, 1, At, B1); PG8_BAR; PG8_SCHED;
;             PG8_LDA(At, 0, 1); PG8_STAGE(PG8_SB(0, 0), b2, voffB); PG8_STAGE(PG8_SB(0, 1), b2 + hstep, voffB); PG8_STAGE(PG8_SA(0, 0), a2, voffA);
;             PG8_WAIT_V(8); PG8_WAIT_L(0); PG8_BAR; PG8_MMA(1, 0, At, B0); PG8_MMA(1, 1, At, B1); PG8_BAR; PG8_SCHED;
.LBB0_955:
	ds_read_b128 v[106:109], v203
	ds_read_b128 v[110:113], v203 offset:1024
	ds_read_b128 v[114:117], v203 offset:2048
	ds_read_b128 v[118:121], v203 offset:3072
	ds_read_b128 v[122:125], v204
	ds_read_b128 v[126:129], v204 offset:1024
	ds_read_b128 v[130:133], v204 offset:2048
	ds_read_b128 v[134:137], v204 offset:3072
	s_add_u32 s12, s8, 0xfffc0080
	s_addc_u32 s13, s9, -1
	s_cmp_eq_u32 s20, 12
	s_cselect_b32 s15, s77, s13
	s_cselect_b32 s14, s76, s12
	s_cselect_b32 s13, s11, s19
	s_cselect_b32 s12, s17, s18
	v_lshl_add_u64 v[88:89], s[8:9], 0, v[186:187]
	s_add_i32 m0, s84, 0xc000
	ds_read_b128 v[162:165], v205
	ds_read_b128 v[166:169], v205 offset:1024
	ds_read_b128 v[170:173], v205 offset:2048
	ds_read_b128 v[174:177], v205 offset:3072
	ds_read_b128 v[194:197], v205 offset:4096
	ds_read_b128 v[206:209], v205 offset:5120
	ds_read_b128 v[210:213], v205 offset:6144
	ds_read_b128 v[214:217], v205 offset:7168
	global_load_lds_dwordx4 v[88:89], off
	v_lshl_add_u64 v[88:89], s[8:9], 0, v[188:189]
	s_add_i32 m0, s84, 0xe000
	s_nop 0
	global_load_lds_dwordx4 v[88:89], off
	s_waitcnt vmcnt(8)
	s_waitcnt lgkmcnt(0)
	s_barrier
	s_setprio 1
	s_waitcnt lgkmcnt(0)
	v_mfma_f32_16x16x32_bf16 v[158:161], v[106:109], v[162:165], v[158:161]
	v_mfma_f32_16x16x32_bf16 v[60:63], v[114:117], v[162:165], v[60:63]
	v_mfma_f32_16x16x32_bf16 v[154:157], v[106:109], v[170:173], v[154:157]
	v_mfma_f32_16x16x32_bf16 v[52:55], v[114:117], v[170:173], v[52:55]
	v_mfma_f32_16x16x32_bf16 v[146:149], v[106:109], v[194:197], v[146:149]
	v_mfma_f32_16x16x32_bf16 v[44:47], v[114:117], v[194:197], v[44:47]
	v_mfma_f32_16x16x32_bf16 v[138:141], v[106:109], v[210:213], v[138:141]
	v_mfma_f32_16x16x32_bf16 v[36:39], v[114:117], v[210:213], v[36:39]
	v_mfma_f32_16x16x32_bf16 v[158:161], v[110:113], v[166:169], v[158:161]
	v_mfma_f32_16x16x32_bf16 v[60:63], v[118:121], v[166:169], v[60:63]
	v_mfma_f32_16x16x32_bf16 v[154:157], v[110:113], v[174:177], v[154:157]
	v_mfma_f32_16x16x32_bf16 v[52:55], v[118:121], v[174:177], v[52:55]
	v_mfma_f32_16x16x32_bf16 v[146:149], v[110:113], v[206:209], v[146:149]
	v_mfma_f32_16x16x32_bf16 v[44:47], v[118:121], v[206:209], v[44:47]
	v_mfma_f32_16x16x32_bf16 v[138:141], v[110:113], v[214:217], v[138:141]
	v_mfma_f32_16x16x32_bf16 v[36:39], v[118:121], v[214:217], v[36:39]
	s_setprio 0
	s_setprio 1
	v_mfma_f32_16x16x32_bf16 v[94:97], v[122:125], v[162:165], v[94:97]
	v_mfma_f32_16x16x32_bf16 v[56:59], v[130:133], v[162:165], v[56:59]
	v_mfma_f32_16x16x32_bf16 v[150:153], v[122:125], v[170:173], v[150:153]
	v_mfma_f32_16x16x32_bf16 v[48:51], v[130:133], v[170:173], v[48:51]
	v_mfma_f32_16x16x32_bf16 v[142:145], v[122:125], v[194:197], v[142:145]
	v_mfma_f32_16x16x32_bf16 v[40:43], v[130:133], v[194:197], v[40:43]
	v_mfma_f32_16x16x32_bf16 v[98:101], v[122:125], v[210:213], v[98:101]
	v_mfma_f32_16x16x32_bf16 v[32:35], v[130:133], v[210:213], v[32:35]
	v_mfma_f32_16x16x32_bf16 v[94:97], v[126:129], v[166:169], v[94:97]
	v_mfma_f32_16x16x32_bf16 v[56:59], v[134:137], v[166:169], v[56:59]
	v_mfma_f32_16x16x32_bf16 v[150:153], v[126:129], v[174:177], v[150:153]
	v_mfma_f32_16x16x32_bf16 v[48:51], v[134:137], v[174:177], v[48:51]
	v_mfma_f32_16x16x32_bf16 v[142:145], v[126:129], v[206:209], v[142:145]
	v_mfma_f32_16x16x32_bf16 v[40:43], v[134:137], v[206:209], v[40:43]
	v_mfma_f32_16x16x32_bf16 v[98:101], v[126:129], v[214:217], v[98:101]
	v_mfma_f32_16x16x32_bf16 v[32:35], v[134:137], v[214:217], v[32:35]
	s_setprio 0
	s_barrier
	s_add_i32 s21, s1, s83
	v_lshl_add_u64 v[198:199], s[12:13], 0, v[180:181]
	s_mov_b32 m0, s21
	ds_read_b128 v[162:165], v205 offset:16384
	ds_read_b128 v[166:169], v205 offset:17408
	ds_read_b128 v[170:173], v205 offset:18432
	ds_read_b128 v[174:177], v205 offset:19456
	ds_read_b128 v[194:197], v205 offset:20480
	ds_read_b128 v[206:209], v205 offset:21504
	ds_read_b128 v[210:213], v205 offset:22528
	ds_read_b128 v[214:217], v205 offset:23552
	global_load_lds_dwordx4 v[198:199], off
	s_add_i32 m0, s21, 0x2000
	s_add_u32 s22, s12, 0x40000
	v_lshl_add_u64 v[218:219], s[12:13], 0, v[184:185]
	s_addc_u32 s23, s13, 0
	s_add_i32 s21, s2, s83
	global_load_lds_dwordx4 v[218:219], off
	v_lshl_add_u64 v[88:89], s[22:23], 0, v[180:181]
	s_mov_b32 m0, s21
	v_lshl_add_u64 v[220:221], s[14:15], 0, v[178:179]
	global_load_lds_dwordx4 v[88:89], off
	v_lshl_add_u64 v[88:89], s[22:23], 0, v[184:185]
	s_add_i32 m0, s21, 0x2000
	v_lshl_add_u64 v[222:223], s[14:15], 0, v[182:183]
	global_load_lds_dwordx4 v[88:89], off
	s_mov_b32 m0, s84
	s_nop 0
	global_load_lds_dwordx4 v[220:221], off
	s_mov_b32 m0, s85
	s_nop 0
	global_load_lds_dwordx4 v[222:223], off
	s_waitcnt vmcnt(8)
	s_waitcnt lgkmcnt(0)
	s_barrier
; #define PG8_STAGE(bufoff, gbase, voff) do { _Pragma("unroll") for (int _i = 0; _i < 2; ++_i) \
;         __builtin_amdgcn_global_load_lds((const unsigned*)((const char*)(gbase) + (voff)[_i]), (PG8_LAS unsigned*)(lds + (bufoff) + ldsw + _i * 8192), 16, 0, 0); } while (0)
; #define PG8_LDA(dst, b, h) do { _Pragma("unroll") for (int m = 0; m < 4; ++m) _Pragma("unroll") for (int k = 0; k < 2; ++k) dst[m][k] = *(const PG8_LAS bf16x8*)(lds + PG8_SA(b, h) + aoff + m * 2048 + k * 1024); } while (0)
; #define PG8_LDB(dst, b, h) do { _Pragma("unroll") for (int n = 0; n < 2; ++n) _Pragma("unroll") for (int k = 0; k < 2; ++k) dst[n][k] = *(const PG8_LAS bf16x8*)(lds + PG8_SB(b, h) + boff + n * 2048 + k * 1024); } while (0)
; #define PG8_MMA(ai, bj, At, Bt) do { __builtin_amdgcn_s_setprio(1); _Pragma("unroll") for (int m = 0; m < 4; ++m) _Pragma("unroll") for (int n = 0; n < 2; ++n) _Pragma("unroll") for (int k = 0; k < 2; ++k) \
;         acc[ai][bj][m][n] = __builtin_amdgcn_mfma_f32_16x16x32_bf16(Bt[n][k], At[m][k], acc[ai][bj][m][n], 0, 0, 0); __builtin_amdgcn_s_setprio(0); } while (0)
; #define PG8_WAIT_V(n) asm volatile("s_waitcnt vmcnt(" #n ")" ::: "memory")
; #define PG8_WAIT_L(n) asm volatile("s_waitcnt lgkmcnt(" #n ")" ::: "memory")
; #define PG8_BAR __builtin_amdgcn_s_barrier()
; #define PG8_SCHED __builtin_amdgcn_sched_barrier(0)
; template <class Epi, class Sched, bool ALIGN_EPI = false, bool SP2 = false>
; __device__ __forceinline__ void gemm_phase(PG8_LAS unsigned char* lds, const Gemm g, const Sched& S, const Epi& E, const int wv) {
;     ...
;             PG8_WAIT_V(8); PG8_WAIT_L(0); PG8_BAR; PG8_MMA(1, 0, At, B0); PG8_MMA(1, 1, At, B1); PG8_BAR; PG8_SCHED;
;             PG8_LDB(B0, 1, 0); PG8_LDB(B1, 1, 1); PG8_SCHED; PG8_LDA(At, 1, 0); PG8_STAGE(PG8_SA(0, 1), a2 + hstep, voffA);
;             PG8_WAIT_V(8); PG8_WAIT_L(0); PG8_BAR; PG8_MMA(0, 0, At, B0); PG8_MMA(0, 1, At, B1); PG8_BAR; PG8_SCHED;
	s_setprio 1
	s_waitcnt lgkmcnt(0)
	v_mfma_f32_16x16x32_bf16 v[102:105], v[106:109], v[162:165], v[102:105]
	v_mfma_f32_16x16x32_bf16 v[28:31], v[114:117], v[162:165], v[28:31]
	v_mfma_f32_16x16x32_bf16 v[84:87], v[106:109], v[170:173], v[84:87]
	v_mfma_f32_16x16x32_bf16 v[20:23], v[114:117], v[170:173], v[20:23]
	v_mfma_f32_16x16x32_bf16 v[76:79], v[106:109], v[194:197], v[76:79]
	v_mfma_f32_16x16x32_bf16 v[12:15], v[114:117], v[194:197], v[12:15]
	v_mfma_f32_16x16x32_bf16 v[68:71], v[106:109], v[210:213], v[68:71]
	v_mfma_f32_16x16x32_bf16 v[4:7], v[114:117], v[210:213], v[4:7]
	v_mfma_f32_16x16x32_bf16 v[102:105], v[110:113], v[166:169], v[102:105]
	v_mfma_f32_16x16x32_bf16 v[28:31], v[118:121], v[166:169], v[28:31]
	v_mfma_f32_16x16x32_bf16 v[84:87], v[110:113], v[174:177], v[84:87]
	v_mfma_f32_16x16x32_bf16 v[20:23], v[118:121], v[174:177], v[20:23]
	v_mfma_f32_16x16x32_bf16 v[76:79], v[110:113], v[206:209], v[76:79]
	v_mfma_f32_16x16x32_bf16 v[12:15], v[118:121], v[206:209], v[12:15]
	v_mfma_f32_16x16x32_bf16 v[68:71], v[110:113], v[214:217], v[68:71]
	v_mfma_f32_16x16x32_bf16 v[4:7], v[118:121], v[214:217], v[4:7]
	s_setprio 0
	s_setprio 1
	v_mfma_f32_16x16x32_bf16 v[88:91], v[122:125], v[162:165], v[90:93]
	v_mfma_f32_16x16x32_bf16 v[24:27], v[130:133], v[162:165], v[24:27]
	v_mfma_f32_16x16x32_bf16 v[80:83], v[122:125], v[170:173], v[80:83]
	v_mfma_f32_16x16x32_bf16 v[16:19], v[130:133], v[170:173], v[16:19]
	v_mfma_f32_16x16x32_bf16 v[72:75], v[122:125], v[194:197], v[72:75]
	v_mfma_f32_16x16x32_bf16 v[8:11], v[130:133], v[194:197], v[8:11]
	v_mfma_f32_16x16x32_bf16 v[64:67], v[122:125], v[210:213], v[64:67]
	v_mfma_f32_16x16x32_bf16 v[0:3], v[130:133], v[210:213], v[0:3]
	v_mfma_f32_16x16x32_bf16 v[88:91], v[126:129], v[166:169], v[88:91]
	v_mfma_f32_16x16x32_bf16 v[24:27], v[134:137], v[166:169], v[24:27]
	v_mfma_f32_16x16x32_bf16 v[80:83], v[126:129], v[174:177], v[80:83]
	v_mfma_f32_16x16x32_bf16 v[16:19], v[134:137], v[174:177], v[16:19]
	v_mfma_f32_16x16x32_bf16 v[72:75], v[126:129], v[206:209], v[72:75]
	v_mfma_f32_16x16x32_bf16 v[8:11], v[134:137], v[206:209], v[8:11]
	v_mfma_f32_16x16x32_bf16 v[64:67], v[126:129], v[214:217], v[64:67]
	v_mfma_f32_16x16x32_bf16 v[0:3], v[134:137], v[214:217], v[0:3]
	s_setprio 0
	s_barrier
	s_add_i32 s21, 0, 0x18000
	v_add_u32_e32 v92, s21, v202
	s_add_i32 s22, 0, 0x1c000
	ds_read_b128 v[106:109], v92
	ds_read_b128 v[110:113], v92 offset:1024
	ds_read_b128 v[114:117], v92 offset:2048
	ds_read_b128 v[118:121], v92 offset:3072
	v_add_u32_e32 v92, s22, v202
	ds_read_b128 v[122:125], v92
	ds_read_b128 v[126:129], v92 offset:1024
	ds_read_b128 v[130:133], v92 offset:2048
	ds_read_b128 v[134:137], v92 offset:3072
	s_add_u32 s14, s14, 0x40000
	s_addc_u32 s15, s15, 0
	s_mov_b32 m0, s86
	v_lshl_add_u64 v[92:93], s[14:15], 0, v[178:179]
	ds_read_b128 v[162:165], v205 offset:32768
	ds_read_b128 v[166:169], v205 offset:33792
	ds_read_b128 v[170:173], v205 offset:34816
	ds_read_b128 v[174:177], v205 offset:35840
	ds_read_b128 v[194:197], v205 offset:36864
	ds_read_b128 v[206:209], v205 offset:37888
	ds_read_b128 v[210:213], v205 offset:38912
	ds_read_b128 v[214:217], v205 offset:39936
	global_load_lds_dwordx4 v[92:93], off
	v_lshl_add_u64 v[92:93], s[14:15], 0, v[182:183]
	s_mov_b32 m0, s87
	s_nop 0
	global_load_lds_dwordx4 v[92:93], off
	s_waitcnt vmcnt(8)
	s_waitcnt lgkmcnt(0)
	s_barrier
	s_setprio 1
	s_waitcnt lgkmcnt(0)
	v_mfma_f32_16x16x32_bf16 v[158:161], v[106:109], v[162:165], v[158:161]
	v_mfma_f32_16x16x32_bf16 v[60:63], v[114:117], v[162:165], v[60:63]
	v_mfma_f32_16x16x32_bf16 v[154:157], v[106:109], v[170:173], v[154:157]
	v_mfma_f32_16x16x32_bf16 v[52:55], v[114:117], v[170:173], v[52:55]
	v_mfma_f32_16x16x32_bf16 v[146:149], v[106:109], v[194:197], v[146:149]
	v_mfma_f32_16x16x32_bf16 v[44:47], v[114:117], v[194:197], v[44:47]
	v_mfma_f32_16x16x32_bf16 v[138:141], v[106:109], v[210:213], v[138:141]
	v_mfma_f32_16x16x32_bf16 v[36:39], v[114:117], v[210:213], v[36:39]
	v_mfma_f32_16x16x32_bf16 v[158:161], v[110:113], v[166:169], v[158:161]
	v_mfma_f32_16x16x32_bf16 v[60:63], v[118:121], v[166:169], v[60:63]
	v_mfma_f32_16x16x32_bf16 v[154:157], v[110:113], v[174:177], v[154:157]
	v_mfma_f32_16x16x32_bf16 v[52:55], v[118:121], v[174:177], v[52:55]
	v_mfma_f32_16x16x32_bf16 v[146:149], v[110:113], v[206:209], v[146:149]
	v_mfma_f32_16x16x32_bf16 v[44:47], v[118:121], v[206:209], v[44:47]
	v_mfma_f32_16x16x32_bf16 v[138:141], v[110:113], v[214:217], v[138:141]
	v_mfma_f32_16x16x32_bf16 v[36:39], v[118:121], v[214:217], v[36:39]
	s_setprio 0
	s_setprio 1
	v_mfma_f32_16x16x32_bf16 v[92:95], v[122:125], v[162:165], v[94:97]
	v_mfma_f32_16x16x32_bf16 v[56:59], v[130:133], v[162:165], v[56:59]
	v_mfma_f32_16x16x32_bf16 v[150:153], v[122:125], v[170:173], v[150:153]
	v_mfma_f32_16x16x32_bf16 v[48:51], v[130:133], v[170:173], v[48:51]
	v_mfma_f32_16x16x32_bf16 v[142:145], v[122:125], v[194:197], v[142:145]
	v_mfma_f32_16x16x32_bf16 v[40:43], v[130:133], v[194:197], v[40:43]
	v_mfma_f32_16x16x32_bf16 v[98:101], v[122:125], v[210:213], v[98:101]
	v_mfma_f32_16x16x32_bf16 v[32:35], v[130:133], v[210:213], v[32:35]
	v_mfma_f32_16x16x32_bf16 v[94:97], v[126:129], v[166:169], v[92:95]
	v_mfma_f32_16x16x32_bf16 v[56:59], v[134:137], v[166:169], v[56:59]
	v_mfma_f32_16x16x32_bf16 v[150:153], v[126:129], v[174:177], v[150:153]
	v_mfma_f32_16x16x32_bf16 v[48:51], v[134:137], v[174:177], v[48:51]
	v_mfma_f32_16x16x32_bf16 v[142:145], v[126:129], v[206:209], v[142:145]
	v_mfma_f32_16x16x32_bf16 v[40:43], v[134:137], v[206:209], v[40:43]
	v_mfma_f32_16x16x32_bf16 v[98:101], v[126:129], v[214:217], v[98:101]
	v_mfma_f32_16x16x32_bf16 v[32:35], v[134:137], v[214:217], v[32:35]
	s_setprio 0
	s_barrier
; #define PG8_STAGE(bufoff, gbase, voff) do { _Pragma("unroll") for (int _i = 0; _i < 2; ++_i) \
;         __builtin_amdgcn_global_load_lds((const unsigned*)((const char*)(gbase) + (voff)[_i]), (PG8_LAS unsigned*)(lds + (bufoff) + ldsw + _i * 8192), 16, 0, 0); } while (0)
; #define PG8_LDA(dst, b, h) do { _Pragma("unroll") for (int m = 0; m < 4; ++m) _Pragma("unroll") for (int k = 0; k < 2; ++k) dst[m][k] = *(const PG8_LAS bf16x8*)(lds + PG8_SA(b, h) + aoff + m * 2048 + k * 1024); } while (0)
; #define PG8_WAIT_V(n) asm volatile("s_waitcnt vmcnt(" #n ")" ::: "memory")
; #define PG8_WAIT_L(n) asm volatile("s_waitcnt lgkmcnt(" #n ")" ::: "memory")
; template <class Epi, class Sched, bool ALIGN_EPI = false, bool SP2 = false>
; __device__ __forceinline__ void gemm_phase(PG8_LAS unsigned char* lds, const Gemm g, const Sched& S, const Epi& E, const int wv) {
;     ...
;             PG8_LDA(At, 1, 1); PG8_STAGE(PG8_SB(1, 0), b3, voffB); PG8_STAGE(PG8_SB(1, 1), b3 + hstep, voffB); PG8_STAGE(PG8_SA(1, 0), a3, voffA);
;             PG8_WAIT_V(8); PG8_WAIT_L(0); PG8_BAR; PG8_MMA(1, 0, At, B0); PG8_MMA(1, 1, At, B1); PG8_BAR; PG8_SCHED;
;     __device__ __forceinline__ void operator()(const f32x4 (&acc)[2][2][4][2], const Unit& u, int wr, int wc, int fr_, int fq_) const {
;         int fr = fr_, fq = fq_; asm volatile("" : "+v"(fr), "+v"(fq));
;         if (fr >= 14) {
; #pragma unroll
;             for (int ai = 0; ai < 2; ++ai)
; #pragma unroll
;                 for (int bj = 0; bj < 2; ++bj)
; #pragma unroll
;                     for (int n = 0; n < 2; ++n) *(LAS f32x4*)(halo + ((2 * ai + wr) * 2 + (fr - 14)) * 256 + 128 * bj + 32 * wc + 8 * fq + 4 * n) = acc[ai][bj][3][n];
;         }
;         asm volatile("s_waitcnt lgkmcnt(0)" ::: "memory"); __builtin_amdgcn_s_barrier(); asm volatile("" ::: "memory");
;         const int R0 = u.pm * 254 - 2;
;         u32x2 keep[2][4];
; #pragma unroll
;         for (int n = 0; n < 2; ++n) {
;             const int cr = u.pn * 128 + wc * 32 + 8 * fq + 4 * n;
;             const f32x4 g0 = *(const f32x4*)(cw + cr), g1 = *(const f32x4*)(cw + NUP + cr), g2 = *(const f32x4*)(cw + 2 * NUP + cr), gb = *(const f32x4*)(cb + cr);
;             const f32x4 v0 = *(const f32x4*)(cw + DFF + cr), v1 = *(const f32x4*)(cw + NUP + DFF + cr), v2 = *(const f32x4*)(cw + 2 * NUP + DFF + cr), vb = *(const f32x4*)(cb + DFF + cr);
	s_add_i32 s14, s21, s83
	v_lshl_add_u64 v[92:93], v[198:199], 0, s[66:67]
	s_mov_b32 m0, s14
	ds_read_b128 v[162:165], v205 offset:49152
	ds_read_b128 v[166:169], v205 offset:50176
	ds_read_b128 v[170:173], v205 offset:51200
	ds_read_b128 v[174:177], v205 offset:52224
	ds_read_b128 v[194:197], v205 offset:53248
	ds_read_b128 v[206:209], v205 offset:54272
	ds_read_b128 v[210:213], v205 offset:55296
	ds_read_b128 v[214:217], v205 offset:56320
	global_load_lds_dwordx4 v[92:93], off
	s_add_i32 m0, s14, 0x2000
	s_add_u32 s12, s12, 0x40080
	v_lshl_add_u64 v[92:93], v[218:219], 0, s[66:67]
	s_addc_u32 s13, s13, 0
	s_add_i32 s14, s22, s83
	global_load_lds_dwordx4 v[92:93], off
	v_lshl_add_u64 v[92:93], s[12:13], 0, v[180:181]
	s_mov_b32 m0, s14
	s_nop 0
	global_load_lds_dwordx4 v[92:93], off
	v_lshl_add_u64 v[92:93], s[12:13], 0, v[184:185]
	s_add_i32 m0, s14, 0x2000
	s_nop 0
	global_load_lds_dwordx4 v[92:93], off
	v_lshl_add_u64 v[92:93], v[220:221], 0, s[66:67]
	s_mov_b32 m0, s92
	s_nop 0
	global_load_lds_dwordx4 v[92:93], off
	v_lshl_add_u64 v[92:93], v[222:223], 0, s[66:67]
	s_mov_b32 m0, s93
	s_nop 0
	global_load_lds_dwordx4 v[92:93], off
	s_waitcnt vmcnt(8)
	s_waitcnt lgkmcnt(0)
	s_barrier
	s_setprio 1
	s_waitcnt lgkmcnt(0)
	v_mfma_f32_16x16x32_bf16 v[102:105], v[106:109], v[162:165], v[102:105]
	v_mfma_f32_16x16x32_bf16 v[28:31], v[114:117], v[162:165], v[28:31]
	v_mfma_f32_16x16x32_bf16 v[84:87], v[106:109], v[170:173], v[84:87]
	v_mfma_f32_16x16x32_bf16 v[20:23], v[114:117], v[170:173], v[20:23]
	v_mfma_f32_16x16x32_bf16 v[76:79], v[106:109], v[194:197], v[76:79]
	v_mfma_f32_16x16x32_bf16 v[12:15], v[114:117], v[194:197], v[12:15]
	v_mfma_f32_16x16x32_bf16 v[68:71], v[106:109], v[210:213], v[68:71]
	v_mfma_f32_16x16x32_bf16 v[4:7], v[114:117], v[210:213], v[4:7]
	v_mfma_f32_16x16x32_bf16 v[102:105], v[110:113], v[166:169], v[102:105]
	v_mfma_f32_16x16x32_bf16 v[28:31], v[118:121], v[166:169], v[28:31]
	v_mfma_f32_16x16x32_bf16 v[84:87], v[110:113], v[174:177], v[84:87]
	v_mfma_f32_16x16x32_bf16 v[20:23], v[118:121], v[174:177], v[20:23]
	v_mfma_f32_16x16x32_bf16 v[76:79], v[110:113], v[206:209], v[76:79]
	v_mfma_f32_16x16x32_bf16 v[12:15], v[118:121], v[206:209], v[12:15]
	v_mfma_f32_16x16x32_bf16 v[68:71], v[110:113], v[214:217], v[68:71]
	v_mfma_f32_16x16x32_bf16 v[4:7], v[118:121], v[214:217], v[4:7]
	s_setprio 0
	s_setprio 1
	v_mfma_f32_16x16x32_bf16 v[88:91], v[122:125], v[162:165], v[88:91]
	v_mfma_f32_16x16x32_bf16 v[24:27], v[130:133], v[162:165], v[24:27]
	v_mfma_f32_16x16x32_bf16 v[80:83], v[122:125], v[170:173], v[80:83]
	v_mfma_f32_16x16x32_bf16 v[16:19], v[130:133], v[170:173], v[16:19]
	v_mfma_f32_16x16x32_bf16 v[72:75], v[122:125], v[194:197], v[72:75]
	v_mfma_f32_16x16x32_bf16 v[8:11], v[130:133], v[194:197], v[8:11]
	v_mfma_f32_16x16x32_bf16 v[64:67], v[122:125], v[210:213], v[64:67]
	v_mfma_f32_16x16x32_bf16 v[0:3], v[130:133], v[210:213], v[0:3]
	v_mfma_f32_16x16x32_bf16 v[90:93], v[126:129], v[166:169], v[88:91]
	v_mfma_f32_16x16x32_bf16 v[24:27], v[134:137], v[166:169], v[24:27]
	v_mfma_f32_16x16x32_bf16 v[80:83], v[126:129], v[174:177], v[80:83]
	v_mfma_f32_16x16x32_bf16 v[16:19], v[134:137], v[174:177], v[16:19]
	v_mfma_f32_16x16x32_bf16 v[72:75], v[126:129], v[206:209], v[72:75]
	v_mfma_f32_16x16x32_bf16 v[8:11], v[134:137], v[206:209], v[8:11]
	v_mfma_f32_16x16x32_bf16 v[64:67], v[126:129], v[214:217], v[64:67]
	v_mfma_f32_16x16x32_bf16 v[0:3], v[134:137], v[214:217], v[0:3]
	s_setprio 0
	s_barrier
	s_add_i32 s20, s20, 2
	s_add_u32 s8, s8, 0x100
	s_addc_u32 s9, s9, 0
	s_add_u32 s18, s18, 0x100
	s_addc_u32 s19, s19, 0
	s_cmp_gt_u32 s20, 13
	s_cbranch_scc0 .LBB0_955
	s_lshl_b32 s8, s10, 7
	s_or_b32 s8, s8, s91
	v_lshlrev_b32_e32 v209, 3, v201
	v_add_u32_e32 v194, s8, v209
	v_ashrrev_i32_e32 v195, 31, v194
	v_lshlrev_b64 v[118:119], 2, v[194:195]
	v_lshl_add_u64 v[198:199], s[52:53], 0, v[118:119]
	v_lshl_add_u64 v[106:107], s[50:51], 0, v[118:119]
	v_lshl_add_u64 v[108:109], s[56:57], 0, v[118:119]
	global_load_dwordx4 v[130:133], v[198:199], off
	global_load_dwordx4 v[126:129], v[106:107], off
	global_load_dwordx4 v[122:125], v[108:109], off
	v_lshl_add_u64 v[196:197], s[54:55], 0, v[118:119]
	v_lshl_add_u64 v[106:107], s[58:59], 0, v[118:119]
	v_lshl_add_u64 v[108:109], s[60:61], 0, v[118:119]
	v_lshl_add_u64 v[110:111], s[62:63], 0, v[118:119]
	v_lshl_add_u64 v[118:119], s[64:65], 0, v[118:119]
	global_load_dwordx4 v[134:137], v[196:197], off
	global_load_dwordx4 v[114:117], v[106:107], off
	s_nop 0
	global_load_dwordx4 v[106:109], v[108:109], off
	global_load_dwordx4 v[110:113], v[110:111], off
	global_load_dwordx4 v[118:121], v[118:119], off
	s_and_b64 vcc, exec, s[68:69]
	s_cbranch_vccz .LBB0_958
	s_barrier
.LBB0_958:
	v_mov_b32_e32 v88, v200
	v_mov_b32_e32 v89, v201
	s_nop 0
	v_cmp_lt_i32_e32 vcc, 13, v88
	s_and_saveexec_b64 s[8:9], vcc
	s_cbranch_execz .LBB0_960
	v_readlane_b32 s11, v247, 47
	v_lshlrev_b32_e32 v210, 5, v89
	s_nop 0
	v_add_lshl_u32 v211, s11, v88, 10
	v_readlane_b32 s11, v247, 53
	v_add3_u32 v212, s96, v211, v210
	ds_write_b128 v212, v[138:141]
	ds_write_b128 v212, v[36:39] offset:16
	ds_write_b128 v212, v[98:101] offset:512
	ds_write_b128 v212, v[32:35] offset:528
	v_add3_u32 v210, s11, v211, v210
	ds_write_b128 v210, v[68:71]
	ds_write_b128 v212, v[4:7] offset:4112
	ds_write_b128 v212, v[64:67] offset:4608
	ds_write_b128 v212, v[0:3] offset:4624
.LBB0_960:
	s_or_b64 exec, exec, s[8:9]
	s_waitcnt lgkmcnt(0)
	s_barrier
	v_lshlrev_b32_e32 v162, 8, v88
	v_and_b32_e32 v208, 0x100, v162
	v_lshl_add_u32 v89, v89, 5, s0
	v_cndmask_b32_e64 v162, 0, 1, s[70:71]
	v_cmp_ne_u32_e64 s[28:29], 1, v162
	s_andn2_b64 vcc, exec, s[70:71]
	v_lshl_add_u32 v166, v208, 2, v89
	s_cbranch_vccnz .LBB0_963
	ds_read_b128 v[174:177], v89 offset:1024
	ds_read_b128 v[170:173], v166
	s_and_b64 vcc, exec, s[28:29]
	s_cbranch_vccnz .LBB0_964

; #define LAS __attribute__((address_space(3)))
;     __device__ __forceinline__ void operator()(const f32x4 (&acc)[2][2][4][2], const Unit& u, int wr, int wc, int fr_, int fq_) const {
;     ...
;         for (int n = 0; n < 2; ++n) {
;             const int cr = u.pn * 128 + wc * 32 + 8 * fq + 4 * n;
;             const f32x4 g0 = *(const f32x4*)(cw + cr), g1 = *(const f32x4*)(cw + NUP + cr), g2 = *(const f32x4*)(cw + 2 * NUP + cr), gb = *(const f32x4*)(cb + cr);
;             const f32x4 v0 = *(const f32x4*)(cw + DFF + cr), v1 = *(const f32x4*)(cw + NUP + DFF + cr), v2 = *(const f32x4*)(cw + 2 * NUP + DFF + cr), vb = *(const f32x4*)(cb + DFF + cr);
; #pragma unroll
;             for (int ai = 0; ai < 2; ++ai) {
;                 const int seg = 2 * ai + wr;
;                 f32x4 pr1[2], pr2[2];
; #pragma unroll
;                 for (int bj = 0; bj < 2; ++bj) {
;                     pr1[bj] = (f32x4){0.f, 0.f, 0.f, 0.f}; pr2[bj] = (f32x4){0.f, 0.f, 0.f, 0.f};
;                     if (seg > 0) { const LAS float* hp = halo + ((seg - 1) * 2) * 256 + 128 * bj + 32 * wc + 8 * fq + 4 * n;
;                         pr1[bj] = *(const LAS f32x4*)(hp + 256); pr2[bj] = *(const LAS f32x4*)(hp + ((fr & 1) ? 256 : 0)); }
;                 }
; #pragma unroll
;                 for (int m = 0; m < 4; ++m) {
;                     const int r = 128 * ai + 64 * wr + 16 * m + fr, R = R0 + r, t = R & (SEQ - 1);
;                     f32x4 y[2];
; #pragma unroll
;                     for (int bj = 0; bj < 2; ++bj) {
;                         const f32x4 X = acc[ai][bj][m][n]; const f32x4 r1 = dpp_ror(X, 1), r2 = dpp_ror(X, 2);
;                         f32x4 p1 = (fr == 0) ? pr1[bj] : r1, p2 = (fr < 2) ? pr2[bj] : r2;
;                         pr1[bj] = r1; pr2[bj] = r2;
;                         if (t == 0) p1 = (f32x4){0.f, 0.f, 0.f, 0.f};
;                         if (t <= 1) p2 = (f32x4){0.f, 0.f, 0.f, 0.f};
;                         y[bj] = bj == 0 ? (gb + g0 * p2 + g1 * p1 + g2 * X) : (vb + v0 * p2 + v1 * p1 + v2 * X);
.LBB0_965:
	s_mul_i32 s46, s16, 0xfe
	s_add_i32 s46, s46, -2
	v_add_u32_e32 v207, s90, v88
	v_add_u32_e32 v206, s46, v207
	v_cmp_eq_u32_e64 s[10:11], 0, v88
	v_cmp_gt_i32_e64 s[8:9], 2, v88
	v_and_b32_e32 v88, 0xfff, v206
	v_mov_b32_dpp v210, v158 row_ror:1 row_mask:0xf bank_mask:0xf
	v_mov_b32_dpp v211, v159 row_ror:1 row_mask:0xf bank_mask:0xf
	v_mov_b32_dpp v212, v160 row_ror:1 row_mask:0xf bank_mask:0xf
	v_mov_b32_dpp v213, v161 row_ror:1 row_mask:0xf bank_mask:0xf
	v_mov_b32_dpp v214, v158 row_ror:2 row_mask:0xf bank_mask:0xf
	v_mov_b32_dpp v215, v159 row_ror:2 row_mask:0xf bank_mask:0xf
	v_mov_b32_dpp v216, v160 row_ror:2 row_mask:0xf bank_mask:0xf
	v_mov_b32_dpp v217, v161 row_ror:2 row_mask:0xf bank_mask:0xf
	v_cmp_eq_u32_e64 s[18:19], 0, v88
	v_cmp_gt_u32_e64 s[16:17], 2, v88
	s_waitcnt lgkmcnt(0)
	v_cndmask_b32_e64 v174, v210, v174, s[10:11]
	v_cndmask_b32_e64 v175, v211, v175, s[10:11]
	v_cndmask_b32_e64 v88, v212, v176, s[10:11]
	v_cndmask_b32_e64 v89, v213, v177, s[10:11]
	v_cndmask_b32_e64 v176, v216, v172, s[8:9]
	v_cndmask_b32_e64 v177, v217, v173, s[8:9]
	v_cndmask_b32_e64 v172, v214, v170, s[8:9]
	v_cndmask_b32_e64 v173, v215, v171, s[8:9]
	v_cndmask_b32_e64 v171, v175, 0, s[18:19]
	v_cndmask_b32_e64 v170, v174, 0, s[18:19]
	v_cndmask_b32_e64 v173, v173, 0, s[16:17]
	v_cndmask_b32_e64 v172, v172, 0, s[16:17]
	v_cndmask_b32_e64 v175, v177, 0, s[16:17]
	v_cndmask_b32_e64 v174, v176, 0, s[16:17]
	v_cndmask_b32_e64 v89, v89, 0, s[18:19]
	v_cndmask_b32_e64 v88, v88, 0, s[18:19]
	s_waitcnt vmcnt(0)
	v_pk_fma_f32 v[174:175], v[132:133], v[174:175], v[136:137]
	v_pk_fma_f32 v[172:173], v[130:131], v[172:173], v[134:135]
	v_pk_fma_f32 v[170:171], v[126:127], v[170:171], v[172:173]
	v_pk_fma_f32 v[88:89], v[128:129], v[88:89], v[174:175]
	v_mov_b32_dpp v176, v96 row_ror:2 row_mask:0xf bank_mask:0xf
	v_mov_b32_dpp v177, v97 row_ror:2 row_mask:0xf bank_mask:0xf
	v_mov_b32_dpp v172, v96 row_ror:1 row_mask:0xf bank_mask:0xf
	v_mov_b32_dpp v173, v97 row_ror:1 row_mask:0xf bank_mask:0xf
	v_mov_b32_dpp v174, v94 row_ror:2 row_mask:0xf bank_mask:0xf
	v_mov_b32_dpp v175, v95 row_ror:2 row_mask:0xf bank_mask:0xf
	v_cndmask_b32_e64 v168, v176, v168, s[8:9]
	v_cndmask_b32_e64 v169, v177, v169, s[8:9]
	v_pk_fma_f32 v[88:89], v[160:161], v[124:125], v[88:89]
	v_cndmask_b32_e64 v160, v172, v164, s[10:11]
	v_cndmask_b32_e64 v161, v173, v165, s[10:11]
	v_cndmask_b32_e64 v164, v174, v166, s[8:9]
	v_cndmask_b32_e64 v165, v175, v167, s[8:9]
	v_cndmask_b32_e64 v167, v169, 0, s[16:17]
	v_cndmask_b32_e64 v166, v168, 0, s[16:17]
	v_cndmask_b32_e64 v161, v161, 0, s[18:19]
	v_cndmask_b32_e64 v160, v160, 0, s[18:19]
	v_pk_fma_f32 v[166:167], v[116:117], v[166:167], v[120:121]
	v_pk_fma_f32 v[158:159], v[158:159], v[122:123], v[170:171]
	v_pk_fma_f32 v[160:161], v[108:109], v[160:161], v[166:167]
	v_pk_fma_f32 v[96:97], v[96:97], v[112:113], v[160:161]
	v_mul_f32_e32 v160, 0xbfb8aa3b, v158
	v_exp_f32_e32 v160, v160
	v_mov_b32_dpp v170, v94 row_ror:1 row_mask:0xf bank_mask:0xf
	v_cndmask_b32_e64 v162, v170, v162, s[10:11]
	v_add_f32_e32 v160, 1.0, v160
	v_mov_b32_dpp v171, v95 row_ror:1 row_mask:0xf bank_mask:0xf
	v_rcp_f32_e32 v160, v160
	v_cndmask_b32_e64 v163, v171, v163, s[10:11]
	v_cndmask_b32_e64 v165, v165, 0, s[16:17]
	v_cndmask_b32_e64 v164, v164, 0, s[16:17]
	v_cndmask_b32_e64 v163, v163, 0, s[18:19]
	v_cndmask_b32_e64 v162, v162, 0, s[18:19]
	v_pk_fma_f32 v[164:165], v[114:115], v[164:165], v[118:119]
	v_mul_f32_e32 v158, v158, v160
	v_pk_fma_f32 v[162:163], v[106:107], v[162:163], v[164:165]
	v_pk_fma_f32 v[94:95], v[94:95], v[110:111], v[162:163]
	v_mul_f32_e32 v94, v158, v94
	v_mul_f32_e32 v158, 0xbfb8aa3b, v159
	v_exp_f32_e32 v158, v158
	s_nop 0
	v_add_f32_e32 v158, 1.0, v158
	v_rcp_f32_e32 v158, v158
	s_nop 0
	v_mul_f32_e32 v158, v159, v158
	v_mul_f32_e32 v95, v158, v95
	v_mul_f32_e32 v158, 0xbfb8aa3b, v88
	v_exp_f32_e32 v158, v158
	v_add_u32_e32 v159, 16, v207
	v_mov_b32_dpp v168, v154 row_ror:2 row_mask:0xf bank_mask:0xf
	v_mov_b32_dpp v169, v155 row_ror:2 row_mask:0xf bank_mask:0xf
	v_add_f32_e32 v158, 1.0, v158
	v_rcp_f32_e32 v158, v158
	v_mov_b32_dpp v218, v156 row_ror:2 row_mask:0xf bank_mask:0xf
	v_mov_b32_dpp v219, v157 row_ror:2 row_mask:0xf bank_mask:0xf
	v_mov_b32_dpp v164, v154 row_ror:1 row_mask:0xf bank_mask:0xf
	v_mul_f32_e32 v88, v88, v158
	v_mul_f32_e32 v88, v88, v96
	v_mul_f32_e32 v96, 0xbfb8aa3b, v89
	v_exp_f32_e32 v96, v96
	v_add_u32_e32 v158, s46, v159
	v_mov_b32_dpp v165, v155 row_ror:1 row_mask:0xf bank_mask:0xf
	v_mov_b32_dpp v166, v156 row_ror:1 row_mask:0xf bank_mask:0xf
	v_add_f32_e32 v96, 1.0, v96
	v_rcp_f32_e32 v96, v96
	v_mov_b32_dpp v167, v157 row_ror:1 row_mask:0xf bank_mask:0xf
	v_cndmask_b32_e64 v162, v218, v216, s[8:9]
	v_cndmask_b32_e64 v163, v219, v217, s[8:9]
	v_mul_f32_e32 v89, v89, v96
	v_mul_f32_e32 v89, v89, v97
	v_cvt_pk_bf16_f32 v96, v94, v95
	v_cvt_pk_bf16_f32 v97, v88, v89
	v_and_b32_e32 v88, 0xfff, v158
	v_cmp_gt_u32_e64 s[24:25], 2, v88
	v_cndmask_b32_e64 v160, v168, v214, s[8:9]
	v_cndmask_b32_e64 v161, v169, v215, s[8:9]
	v_cmp_eq_u32_e64 s[26:27], 0, v88
	v_cndmask_b32_e64 v94, v164, v210, s[10:11]
	v_cndmask_b32_e64 v95, v165, v211, s[10:11]
	v_cndmask_b32_e64 v88, v166, v212, s[10:11]
	v_cndmask_b32_e64 v89, v167, v213, s[10:11]
	v_cndmask_b32_e64 v161, v161, 0, s[24:25]
	v_cndmask_b32_e64 v160, v160, 0, s[24:25]
	v_cndmask_b32_e64 v163, v163, 0, s[24:25]
	v_cndmask_b32_e64 v162, v162, 0, s[24:25]
	v_cndmask_b32_e64 v89, v89, 0, s[26:27]
	v_cndmask_b32_e64 v88, v88, 0, s[26:27]
	v_cndmask_b32_e64 v95, v95, 0, s[26:27]
	v_cndmask_b32_e64 v94, v94, 0, s[26:27]
; #define LAS __attribute__((address_space(3)))
;     __device__ __forceinline__ void operator()(const f32x4 (&acc)[2][2][4][2], const Unit& u, int wr, int wc, int fr_, int fq_) const {
;     ...
;         for (int n = 0; n < 2; ++n) {
;             const int cr = u.pn * 128 + wc * 32 + 8 * fq + 4 * n;
;             const f32x4 g0 = *(const f32x4*)(cw + cr), g1 = *(const f32x4*)(cw + NUP + cr), g2 = *(const f32x4*)(cw + 2 * NUP + cr), gb = *(const f32x4*)(cb + cr);
;             const f32x4 v0 = *(const f32x4*)(cw + DFF + cr), v1 = *(const f32x4*)(cw + NUP + DFF + cr), v2 = *(const f32x4*)(cw + 2 * NUP + DFF + cr), vb = *(const f32x4*)(cb + DFF + cr);
; #pragma unroll
;             for (int ai = 0; ai < 2; ++ai) {
;                 const int seg = 2 * ai + wr;
;                 f32x4 pr1[2], pr2[2];
; #pragma unroll
;                 for (int bj = 0; bj < 2; ++bj) {
;                     pr1[bj] = (f32x4){0.f, 0.f, 0.f, 0.f}; pr2[bj] = (f32x4){0.f, 0.f, 0.f, 0.f};
;                     if (seg > 0) { const LAS float* hp = halo + ((seg - 1) * 2) * 256 + 128 * bj + 32 * wc + 8 * fq + 4 * n;
;                         pr1[bj] = *(const LAS f32x4*)(hp + 256); pr2[bj] = *(const LAS f32x4*)(hp + ((fr & 1) ? 256 : 0)); }
;                 }
; #pragma unroll
;                 for (int m = 0; m < 4; ++m) {
;                     const int r = 128 * ai + 64 * wr + 16 * m + fr, R = R0 + r, t = R & (SEQ - 1);
;                     f32x4 y[2];
; #pragma unroll
;                     for (int bj = 0; bj < 2; ++bj) {
;                         const f32x4 X = acc[ai][bj][m][n]; const f32x4 r1 = dpp_ror(X, 1), r2 = dpp_ror(X, 2);
;                         f32x4 p1 = (fr == 0) ? pr1[bj] : r1, p2 = (fr < 2) ? pr2[bj] : r2;
;                         pr1[bj] = r1; pr2[bj] = r2;
;                         if (t == 0) p1 = (f32x4){0.f, 0.f, 0.f, 0.f};
;                         if (t <= 1) p2 = (f32x4){0.f, 0.f, 0.f, 0.f};
;                         y[bj] = bj == 0 ? (gb + g0 * p2 + g1 * p1 + g2 * X) : (vb + v0 * p2 + v1 * p1 + v2 * X);
;                     }
;                     f32x4 o;
;                     o.x = y[0].x * __builtin_amdgcn_rcpf(1.f + __builtin_amdgcn_exp2f(-LOG2E * y[0].x)) * y[1].x; o.y = y[0].y * __builtin_amdgcn_rcpf(1.f + __builtin_amdgcn_exp2f(-LOG2E * y[0].y)) * y[1].y;
	v_pk_fma_f32 v[162:163], v[132:133], v[162:163], v[136:137]
	v_pk_fma_f32 v[160:161], v[130:131], v[160:161], v[134:135]
	v_mov_b32_dpp v216, v152 row_ror:2 row_mask:0xf bank_mask:0xf
	v_mov_b32_dpp v217, v153 row_ror:2 row_mask:0xf bank_mask:0xf
	v_pk_fma_f32 v[94:95], v[126:127], v[94:95], v[160:161]
	v_pk_fma_f32 v[88:89], v[128:129], v[88:89], v[162:163]
	v_mov_b32_dpp v212, v152 row_ror:1 row_mask:0xf bank_mask:0xf
	v_mov_b32_dpp v213, v153 row_ror:1 row_mask:0xf bank_mask:0xf
	v_cndmask_b32_e64 v162, v216, v176, s[8:9]
	v_cndmask_b32_e64 v163, v217, v177, s[8:9]
	v_pk_fma_f32 v[94:95], v[154:155], v[122:123], v[94:95]
	v_cndmask_b32_e64 v154, v212, v172, s[10:11]
	v_cndmask_b32_e64 v155, v213, v173, s[10:11]
	v_cndmask_b32_e64 v163, v163, 0, s[24:25]
	v_cndmask_b32_e64 v162, v162, 0, s[24:25]
	v_cndmask_b32_e64 v155, v155, 0, s[26:27]
	v_cndmask_b32_e64 v154, v154, 0, s[26:27]
	v_pk_fma_f32 v[162:163], v[116:117], v[162:163], v[120:121]
	v_pk_fma_f32 v[154:155], v[108:109], v[154:155], v[162:163]
	v_pk_fma_f32 v[152:153], v[152:153], v[112:113], v[154:155]
	v_mul_f32_e32 v154, 0xbfb8aa3b, v94
	v_exp_f32_e32 v154, v154
	v_mov_b32_dpp v214, v150 row_ror:2 row_mask:0xf bank_mask:0xf
	v_mov_b32_dpp v215, v151 row_ror:2 row_mask:0xf bank_mask:0xf
	v_add_f32_e32 v154, 1.0, v154
	v_mov_b32_dpp v210, v150 row_ror:1 row_mask:0xf bank_mask:0xf
	v_mov_b32_dpp v211, v151 row_ror:1 row_mask:0xf bank_mask:0xf
	v_cndmask_b32_e64 v160, v214, v174, s[8:9]
	v_cndmask_b32_e64 v161, v215, v175, s[8:9]
	v_rcp_f32_e32 v154, v154
	v_pk_fma_f32 v[88:89], v[156:157], v[124:125], v[88:89]
	v_cndmask_b32_e64 v156, v210, v170, s[10:11]
	v_cndmask_b32_e64 v157, v211, v171, s[10:11]
	v_cndmask_b32_e64 v161, v161, 0, s[24:25]
	v_cndmask_b32_e64 v160, v160, 0, s[24:25]
	v_cndmask_b32_e64 v157, v157, 0, s[26:27]
	v_cndmask_b32_e64 v156, v156, 0, s[26:27]
	v_pk_fma_f32 v[160:161], v[114:115], v[160:161], v[118:119]
	v_mul_f32_e32 v94, v94, v154
	v_pk_fma_f32 v[156:157], v[106:107], v[156:157], v[160:161]
	v_add_u32_e32 v155, 32, v207
	v_pk_fma_f32 v[150:151], v[150:151], v[110:111], v[156:157]
	v_add_u32_e32 v154, s46, v155
	v_mul_f32_e32 v94, v94, v150
	v_mul_f32_e32 v150, 0xbfb8aa3b, v95
	v_exp_f32_e32 v150, v150
	s_nop 0
	v_add_f32_e32 v150, 1.0, v150
	v_rcp_f32_e32 v150, v150
	v_mov_b32_dpp v172, v148 row_ror:2 row_mask:0xf bank_mask:0xf
	v_mov_b32_dpp v173, v149 row_ror:2 row_mask:0xf bank_mask:0xf
	v_mul_f32_e32 v95, v95, v150
	v_mul_f32_e32 v150, 0xbfb8aa3b, v88
	v_exp_f32_e32 v150, v150
	v_mul_f32_e32 v95, v95, v151
	v_cvt_pk_bf16_f32 v94, v94, v95
	v_mov_b32_dpp v162, v148 row_ror:1 row_mask:0xf bank_mask:0xf
	v_add_f32_e32 v150, 1.0, v150
	v_rcp_f32_e32 v150, v150
	v_mov_b32_dpp v163, v149 row_ror:1 row_mask:0xf bank_mask:0xf
	v_mul_f32_e32 v88, v88, v150
	v_mul_f32_e32 v150, 0xbfb8aa3b, v89
	v_exp_f32_e32 v150, v150
	v_mul_f32_e32 v88, v88, v152
	v_cndmask_b32_e64 v156, v172, v218, s[8:9]
	v_cndmask_b32_e64 v157, v173, v219, s[8:9]
	v_add_f32_e32 v150, 1.0, v150
	v_rcp_f32_e32 v150, v150
	v_mov_b32_dpp v170, v146 row_ror:2 row_mask:0xf bank_mask:0xf
	v_mul_f32_e32 v89, v89, v150
	v_mul_f32_e32 v89, v89, v153
	v_cvt_pk_bf16_f32 v95, v88, v89
	v_and_b32_e32 v88, 0xfff, v154
	v_cmp_gt_u32_e64 s[20:21], 2, v88
	v_cmp_eq_u32_e64 s[22:23], 0, v88
	v_mov_b32_dpp v171, v147 row_ror:2 row_mask:0xf bank_mask:0xf
	v_cndmask_b32_e64 v88, v162, v166, s[10:11]
	v_cndmask_b32_e64 v89, v163, v167, s[10:11]
	v_cndmask_b32_e64 v157, v157, 0, s[20:21]
	v_cndmask_b32_e64 v156, v156, 0, s[20:21]
	v_mov_b32_dpp v160, v146 row_ror:1 row_mask:0xf bank_mask:0xf
	v_mov_b32_dpp v161, v147 row_ror:1 row_mask:0xf bank_mask:0xf
	v_cndmask_b32_e64 v152, v170, v168, s[8:9]
	v_cndmask_b32_e64 v153, v171, v169, s[8:9]
	v_cndmask_b32_e64 v89, v89, 0, s[22:23]
	v_cndmask_b32_e64 v88, v88, 0, s[22:23]
	v_pk_fma_f32 v[156:157], v[132:133], v[156:157], v[136:137]
	v_mov_b32_dpp v174, v144 row_ror:2 row_mask:0xf bank_mask:0xf
	v_mov_b32_dpp v175, v145 row_ror:2 row_mask:0xf bank_mask:0xf
	v_cndmask_b32_e64 v150, v160, v164, s[10:11]
	v_cndmask_b32_e64 v151, v161, v165, s[10:11]
	v_cndmask_b32_e64 v153, v153, 0, s[20:21]
	v_cndmask_b32_e64 v152, v152, 0, s[20:21]
	v_pk_fma_f32 v[88:89], v[128:129], v[88:89], v[156:157]
	v_mov_b32_dpp v166, v144 row_ror:1 row_mask:0xf bank_mask:0xf
	v_mov_b32_dpp v167, v145 row_ror:1 row_mask:0xf bank_mask:0xf
	v_cndmask_b32_e64 v156, v174, v216, s[8:9]
	v_cndmask_b32_e64 v157, v175, v217, s[8:9]
	v_cndmask_b32_e64 v151, v151, 0, s[22:23]
	v_cndmask_b32_e64 v150, v150, 0, s[22:23]
	v_pk_fma_f32 v[152:153], v[130:131], v[152:153], v[134:135]
	v_pk_fma_f32 v[88:89], v[148:149], v[124:125], v[88:89]
	v_cndmask_b32_e64 v148, v166, v212, s[10:11]
	v_cndmask_b32_e64 v149, v167, v213, s[10:11]
	v_cndmask_b32_e64 v157, v157, 0, s[20:21]
	v_cndmask_b32_e64 v156, v156, 0, s[20:21]
	v_pk_fma_f32 v[150:151], v[126:127], v[150:151], v[152:153]
	v_cndmask_b32_e64 v149, v149, 0, s[22:23]
	v_cndmask_b32_e64 v148, v148, 0, s[22:23]
	v_pk_fma_f32 v[156:157], v[116:117], v[156:157], v[120:121]
	v_pk_fma_f32 v[146:147], v[146:147], v[122:123], v[150:151]
	v_pk_fma_f32 v[148:149], v[108:109], v[148:149], v[156:157]
	v_pk_fma_f32 v[144:145], v[144:145], v[112:113], v[148:149]
	v_mul_f32_e32 v148, 0xbfb8aa3b, v146
	v_exp_f32_e32 v148, v148
	v_mov_b32_dpp v168, v142 row_ror:2 row_mask:0xf bank_mask:0xf
	v_mov_b32_dpp v169, v143 row_ror:2 row_mask:0xf bank_mask:0xf
	v_add_f32_e32 v148, 1.0, v148
	v_mov_b32_dpp v164, v142 row_ror:1 row_mask:0xf bank_mask:0xf
	v_mov_b32_dpp v165, v143 row_ror:1 row_mask:0xf bank_mask:0xf
	v_cndmask_b32_e64 v152, v168, v214, s[8:9]
; __device__ __forceinline__ unsigned cvt_pk_bf16(float lo, float hi) { unsigned r; asm volatile("v_cvt_pk_bf16_f32 %0, %1, %2" : "=v"(r) : "v"(lo), "v"(hi)); return r; }
;     __device__ __forceinline__ void operator()(const f32x4 (&acc)[2][2][4][2], const Unit& u, int wr, int wc, int fr_, int fq_) const {
;     ...
;                         const f32x4 X = acc[ai][bj][m][n]; const f32x4 r1 = dpp_ror(X, 1), r2 = dpp_ror(X, 2);
;                         f32x4 p1 = (fr == 0) ? pr1[bj] : r1, p2 = (fr < 2) ? pr2[bj] : r2;
;                         pr1[bj] = r1; pr2[bj] = r2;
;                         if (t == 0) p1 = (f32x4){0.f, 0.f, 0.f, 0.f};
;                         if (t <= 1) p2 = (f32x4){0.f, 0.f, 0.f, 0.f};
;                         y[bj] = bj == 0 ? (gb + g0 * p2 + g1 * p1 + g2 * X) : (vb + v0 * p2 + v1 * p1 + v2 * X);
;                     }
;                     f32x4 o;
;                     o.x = y[0].x * __builtin_amdgcn_rcpf(1.f + __builtin_amdgcn_exp2f(-LOG2E * y[0].x)) * y[1].x; o.y = y[0].y * __builtin_amdgcn_rcpf(1.f + __builtin_amdgcn_exp2f(-LOG2E * y[0].y)) * y[1].y;
;                     o.z = y[0].z * __builtin_amdgcn_rcpf(1.f + __builtin_amdgcn_exp2f(-LOG2E * y[0].z)) * y[1].z; o.w = y[0].w * __builtin_amdgcn_rcpf(1.f + __builtin_amdgcn_exp2f(-LOG2E * y[0].w)) * y[1].w;
;                     { u32x2 w; w.x = cvt_pk_bf16(o.x, o.y); w.y = cvt_pk_bf16(o.z, o.w);
;                       if (n == 0) keep[ai][m] = w;
;                       else if (r >= 2 && R < MTOK) { u32x4 w4; w4.x = keep[ai][m].x; w4.y = keep[ai][m].y; w4.z = w.x; w4.w = w.y; *(u32x4*)(Gout + (size_t)R * DFF + cr - 4) = w4; } }
	v_cndmask_b32_e64 v153, v169, v215, s[8:9]
	v_rcp_f32_e32 v148, v148
	v_cndmask_b32_e64 v150, v164, v210, s[10:11]
	v_cndmask_b32_e64 v151, v165, v211, s[10:11]
	v_cndmask_b32_e64 v153, v153, 0, s[20:21]
	v_cndmask_b32_e64 v152, v152, 0, s[20:21]
	v_cndmask_b32_e64 v151, v151, 0, s[22:23]
	v_cndmask_b32_e64 v150, v150, 0, s[22:23]
	v_pk_fma_f32 v[152:153], v[114:115], v[152:153], v[118:119]
	v_mul_f32_e32 v146, v146, v148
	v_pk_fma_f32 v[150:151], v[106:107], v[150:151], v[152:153]
	v_add_u32_e32 v157, 48, v207
	v_pk_fma_f32 v[142:143], v[142:143], v[110:111], v[150:151]
	v_add_u32_e32 v156, s46, v157
	v_mul_f32_e32 v142, v146, v142
	v_mul_f32_e32 v146, 0xbfb8aa3b, v147
	v_exp_f32_e32 v146, v146
	s_andn2_b64 vcc, exec, s[72:73]
	v_add_f32_e32 v146, 1.0, v146
	v_rcp_f32_e32 v146, v146
	v_mov_b32_dpp v148, v140 row_ror:2 row_mask:0xf bank_mask:0xf
	v_mov_b32_dpp v149, v141 row_ror:2 row_mask:0xf bank_mask:0xf
	v_cndmask_b32_e64 v148, v148, v172, s[8:9]
	v_mul_f32_e32 v146, v147, v146
	v_mul_f32_e32 v143, v146, v143
	v_mul_f32_e32 v146, 0xbfb8aa3b, v88
	v_exp_f32_e32 v146, v146
	v_cndmask_b32_e64 v149, v149, v173, s[8:9]
	v_add_f32_e32 v146, 1.0, v146
	v_rcp_f32_e32 v146, v146
	v_mov_b32_dpp v147, v139 row_ror:2 row_mask:0xf bank_mask:0xf
	v_cndmask_b32_e64 v147, v147, v171, s[8:9]
	v_mul_f32_e32 v88, v88, v146
	v_mul_f32_e32 v144, v88, v144
	v_mul_f32_e32 v88, 0xbfb8aa3b, v89
	v_exp_f32_e32 v88, v88
	s_nop 0
	v_add_f32_e32 v88, 1.0, v88
	v_rcp_f32_e32 v88, v88
	v_mov_b32_dpp v146, v138 row_ror:2 row_mask:0xf bank_mask:0xf
	v_cndmask_b32_e64 v146, v146, v170, s[8:9]
	v_mul_f32_e32 v88, v89, v88
	v_mul_f32_e32 v89, v88, v145
	v_cvt_pk_bf16_f32 v88, v142, v143
	v_and_b32_e32 v142, 0xfff, v156
	v_cvt_pk_bf16_f32 v89, v144, v89
	v_cmp_eq_u32_e64 s[14:15], 0, v142
	v_cmp_gt_u32_e64 s[12:13], 2, v142
	v_mov_b32_dpp v142, v138 row_ror:1 row_mask:0xf bank_mask:0xf
	v_mov_b32_dpp v143, v139 row_ror:1 row_mask:0xf bank_mask:0xf
	v_mov_b32_dpp v144, v140 row_ror:1 row_mask:0xf bank_mask:0xf
	v_mov_b32_dpp v145, v141 row_ror:1 row_mask:0xf bank_mask:0xf
	v_cndmask_b32_e64 v150, v142, v160, s[10:11]
	v_cndmask_b32_e64 v151, v143, v161, s[10:11]
	v_cndmask_b32_e64 v142, v144, v162, s[10:11]
	v_cndmask_b32_e64 v143, v145, v163, s[10:11]
	v_cndmask_b32_e64 v147, v147, 0, s[12:13]
	v_cndmask_b32_e64 v146, v146, 0, s[12:13]
	v_cndmask_b32_e64 v149, v149, 0, s[12:13]
	v_cndmask_b32_e64 v148, v148, 0, s[12:13]
	v_cndmask_b32_e64 v143, v143, 0, s[14:15]
	v_cndmask_b32_e64 v142, v142, 0, s[14:15]
	v_cndmask_b32_e64 v145, v151, 0, s[14:15]
	v_cndmask_b32_e64 v144, v150, 0, s[14:15]
	v_pk_fma_f32 v[148:149], v[132:133], v[148:149], v[136:137]
	v_pk_fma_f32 v[146:147], v[130:131], v[146:147], v[134:135]
	v_pk_fma_f32 v[142:143], v[128:129], v[142:143], v[148:149]
	v_pk_fma_f32 v[144:145], v[126:127], v[144:145], v[146:147]
	v_pk_fma_f32 v[140:141], v[140:141], v[124:125], v[142:143]
	v_pk_fma_f32 v[138:139], v[138:139], v[122:123], v[144:145]
	v_mov_b32_dpp v148, v100 row_ror:2 row_mask:0xf bank_mask:0xf
	v_mov_b32_dpp v149, v101 row_ror:2 row_mask:0xf bank_mask:0xf
	v_mov_b32_dpp v142, v98 row_ror:1 row_mask:0xf bank_mask:0xf
	v_mov_b32_dpp v143, v99 row_ror:1 row_mask:0xf bank_mask:0xf
	v_mov_b32_dpp v144, v100 row_ror:1 row_mask:0xf bank_mask:0xf
	v_mov_b32_dpp v145, v101 row_ror:1 row_mask:0xf bank_mask:0xf
	v_cndmask_b32_e64 v148, v148, v174, s[8:9]
	v_cndmask_b32_e64 v149, v149, v175, s[8:9]
	v_cndmask_b32_e64 v150, v142, v164, s[10:11]
	v_cndmask_b32_e64 v151, v143, v165, s[10:11]
	v_cndmask_b32_e64 v142, v144, v166, s[10:11]
	v_cndmask_b32_e64 v143, v145, v167, s[10:11]
	v_cndmask_b32_e64 v149, v149, 0, s[12:13]
	v_cndmask_b32_e64 v148, v148, 0, s[12:13]
	v_cndmask_b32_e64 v143, v143, 0, s[14:15]
	v_cndmask_b32_e64 v142, v142, 0, s[14:15]
	v_pk_fma_f32 v[148:149], v[116:117], v[148:149], v[120:121]
	v_pk_fma_f32 v[142:143], v[108:109], v[142:143], v[148:149]
	v_pk_fma_f32 v[100:101], v[100:101], v[112:113], v[142:143]
	v_mul_f32_e32 v142, 0xbfb8aa3b, v138
	v_exp_f32_e32 v142, v142
	v_mov_b32_dpp v146, v98 row_ror:2 row_mask:0xf bank_mask:0xf
	v_mov_b32_dpp v147, v99 row_ror:2 row_mask:0xf bank_mask:0xf
	v_cndmask_b32_e64 v146, v146, v168, s[8:9]
	v_add_f32_e32 v142, 1.0, v142
	v_cndmask_b32_e64 v147, v147, v169, s[8:9]
	v_rcp_f32_e32 v142, v142
	v_cndmask_b32_e64 v147, v147, 0, s[12:13]
	v_cndmask_b32_e64 v146, v146, 0, s[12:13]
	v_cndmask_b32_e64 v145, v151, 0, s[14:15]
	v_cndmask_b32_e64 v144, v150, 0, s[14:15]
	v_pk_fma_f32 v[146:147], v[114:115], v[146:147], v[118:119]
	v_mul_f32_e32 v138, v138, v142
	v_pk_fma_f32 v[144:145], v[106:107], v[144:145], v[146:147]
	v_lshl_add_u32 v162, v209, 2, s97
	v_pk_fma_f32 v[98:99], v[98:99], v[110:111], v[144:145]
	v_lshl_add_u32 v163, v208, 2, v162
	v_mul_f32_e32 v98, v138, v98
	v_mul_f32_e32 v138, 0xbfb8aa3b, v139
	v_exp_f32_e32 v138, v138
	s_nop 0
	v_add_f32_e32 v138, 1.0, v138
	v_rcp_f32_e32 v138, v138
	s_nop 0
	v_mul_f32_e32 v138, v139, v138
	v_mul_f32_e32 v99, v138, v99
	v_mul_f32_e32 v138, 0xbfb8aa3b, v140
	v_exp_f32_e32 v138, v138
	s_nop 0
	v_add_f32_e32 v138, 1.0, v138
	v_rcp_f32_e32 v138, v138
	s_nop 0
	v_mul_f32_e32 v138, v140, v138
	v_mul_f32_e32 v138, v138, v100
	v_mul_f32_e32 v100, 0xbfb8aa3b, v141
	v_exp_f32_e32 v100, v100
	s_nop 0
	v_add_f32_e32 v100, 1.0, v100
	v_rcp_f32_e32 v100, v100
	s_nop 0
	v_mul_f32_e32 v100, v141, v100
	v_mul_f32_e32 v101, v100, v101
	v_cvt_pk_bf16_f32 v100, v98, v99
	v_cndmask_b32_e64 v98, 0, 1, s[72:73]
	v_cmp_ne_u32_e64 s[36:37], 1, v98
	v_cvt_pk_bf16_f32 v101, v138, v101
	s_cbranch_vccnz .LBB0_967
	ds_read_b128 v[150:153], v162 offset:3072
	ds_read_b128 v[146:149], v163 offset:2048
	s_branch .LBB0_968

; __device__ __forceinline__ unsigned cvt_pk_bf16(float lo, float hi) { unsigned r; asm volatile("v_cvt_pk_bf16_f32 %0, %1, %2" : "=v"(r) : "v"(lo), "v"(hi)); return r; }
;     __device__ __forceinline__ void operator()(const f32x4 (&acc)[2][2][4][2], const Unit& u, int wr, int wc, int fr_, int fq_) const {
;     ...
;                 for (int m = 0; m < 4; ++m) {
;                     const int r = 128 * ai + 64 * wr + 16 * m + fr, R = R0 + r, t = R & (SEQ - 1);
;                     f32x4 y[2];
; #pragma unroll
;                     for (int bj = 0; bj < 2; ++bj) {
;                         const f32x4 X = acc[ai][bj][m][n]; const f32x4 r1 = dpp_ror(X, 1), r2 = dpp_ror(X, 2);
;                         f32x4 p1 = (fr == 0) ? pr1[bj] : r1, p2 = (fr < 2) ? pr2[bj] : r2;
;                         pr1[bj] = r1; pr2[bj] = r2;
;                         if (t == 0) p1 = (f32x4){0.f, 0.f, 0.f, 0.f};
;                         if (t <= 1) p2 = (f32x4){0.f, 0.f, 0.f, 0.f};
;                         y[bj] = bj == 0 ? (gb + g0 * p2 + g1 * p1 + g2 * X) : (vb + v0 * p2 + v1 * p1 + v2 * X);
;                     }
;                     f32x4 o;
;                     o.x = y[0].x * __builtin_amdgcn_rcpf(1.f + __builtin_amdgcn_exp2f(-LOG2E * y[0].x)) * y[1].x; o.y = y[0].y * __builtin_amdgcn_rcpf(1.f + __builtin_amdgcn_exp2f(-LOG2E * y[0].y)) * y[1].y;
;                     o.z = y[0].z * __builtin_amdgcn_rcpf(1.f + __builtin_amdgcn_exp2f(-LOG2E * y[0].z)) * y[1].z; o.w = y[0].w * __builtin_amdgcn_rcpf(1.f + __builtin_amdgcn_exp2f(-LOG2E * y[0].w)) * y[1].w;
;                     { u32x2 w; w.x = cvt_pk_bf16(o.x, o.y); w.y = cvt_pk_bf16(o.z, o.w);
;                       if (n == 0) keep[ai][m] = w;
;                       else if (r >= 2 && R < MTOK) { u32x4 w4; w4.x = keep[ai][m].x; w4.y = keep[ai][m].y; w4.z = w.x; w4.w = w.y; *(u32x4*)(Gout + (size_t)R * DFF + cr - 4) = w4; } }
.LBB0_970:
	v_add_u32_e32 v161, 0x80, v207
	v_add_u32_e32 v160, s46, v161
	v_and_b32_e32 v98, 0xfff, v160
	v_mov_b32_dpp v166, v104 row_ror:1 row_mask:0xf bank_mask:0xf
	v_mov_b32_dpp v167, v105 row_ror:1 row_mask:0xf bank_mask:0xf
	v_mov_b32_dpp v168, v102 row_ror:2 row_mask:0xf bank_mask:0xf
	v_mov_b32_dpp v169, v103 row_ror:2 row_mask:0xf bank_mask:0xf
	v_mov_b32_dpp v170, v104 row_ror:2 row_mask:0xf bank_mask:0xf
	v_mov_b32_dpp v171, v105 row_ror:2 row_mask:0xf bank_mask:0xf
	v_cmp_eq_u32_e64 s[34:35], 0, v98
	v_cmp_gt_u32_e64 s[30:31], 2, v98
	v_mov_b32_dpp v164, v102 row_ror:1 row_mask:0xf bank_mask:0xf
	v_mov_b32_dpp v165, v103 row_ror:1 row_mask:0xf bank_mask:0xf
	s_waitcnt lgkmcnt(1)
	v_cndmask_b32_e64 v98, v166, v152, s[10:11]
	v_cndmask_b32_e64 v99, v167, v153, s[10:11]
	s_waitcnt lgkmcnt(0)
	v_cndmask_b32_e64 v152, v170, v148, s[8:9]
	v_cndmask_b32_e64 v153, v171, v149, s[8:9]
	v_cndmask_b32_e64 v148, v168, v146, s[8:9]
	v_cndmask_b32_e64 v149, v169, v147, s[8:9]
	v_cndmask_b32_e64 v150, v164, v150, s[10:11]
	v_cndmask_b32_e64 v151, v165, v151, s[10:11]
	v_cndmask_b32_e64 v149, v149, 0, s[30:31]
	v_cndmask_b32_e64 v148, v148, 0, s[30:31]
	v_cndmask_b32_e64 v147, v151, 0, s[34:35]
	v_cndmask_b32_e64 v146, v150, 0, s[34:35]
	v_pk_fma_f32 v[148:149], v[130:131], v[148:149], v[134:135]
	v_cndmask_b32_e64 v151, v153, 0, s[30:31]
	v_cndmask_b32_e64 v150, v152, 0, s[30:31]
	v_pk_fma_f32 v[146:147], v[126:127], v[146:147], v[148:149]
	v_cndmask_b32_e64 v99, v99, 0, s[34:35]
	v_cndmask_b32_e64 v98, v98, 0, s[34:35]
	v_pk_fma_f32 v[150:151], v[132:133], v[150:151], v[136:137]
	v_pk_fma_f32 v[102:103], v[102:103], v[122:123], v[146:147]
	v_pk_fma_f32 v[98:99], v[128:129], v[98:99], v[150:151]
	v_mov_b32_dpp v146, v90 row_ror:1 row_mask:0xf bank_mask:0xf
	v_mov_b32_dpp v147, v91 row_ror:1 row_mask:0xf bank_mask:0xf
	v_mov_b32_dpp v148, v92 row_ror:1 row_mask:0xf bank_mask:0xf
	v_mov_b32_dpp v149, v93 row_ror:1 row_mask:0xf bank_mask:0xf
	v_mov_b32_dpp v152, v92 row_ror:2 row_mask:0xf bank_mask:0xf
	v_mov_b32_dpp v153, v93 row_ror:2 row_mask:0xf bank_mask:0xf
	v_pk_fma_f32 v[98:99], v[104:105], v[124:125], v[98:99]
	v_mov_b32_dpp v150, v90 row_ror:2 row_mask:0xf bank_mask:0xf
	v_mov_b32_dpp v151, v91 row_ror:2 row_mask:0xf bank_mask:0xf
	v_cndmask_b32_e64 v142, v146, v142, s[10:11]
	v_cndmask_b32_e64 v143, v147, v143, s[10:11]
	v_cndmask_b32_e64 v104, v148, v144, s[10:11]
	v_cndmask_b32_e64 v105, v149, v145, s[10:11]
	v_cndmask_b32_e64 v144, v152, v140, s[8:9]
	v_cndmask_b32_e64 v145, v153, v141, s[8:9]
	v_cndmask_b32_e64 v140, v150, v138, s[8:9]
	v_cndmask_b32_e64 v141, v151, v139, s[8:9]
	v_cndmask_b32_e64 v139, v143, 0, s[34:35]
	v_cndmask_b32_e64 v138, v142, 0, s[34:35]
	v_cndmask_b32_e64 v143, v145, 0, s[30:31]
	v_cndmask_b32_e64 v142, v144, 0, s[30:31]
	v_cndmask_b32_e64 v105, v105, 0, s[34:35]
	v_cndmask_b32_e64 v104, v104, 0, s[34:35]
	v_pk_fma_f32 v[142:143], v[116:117], v[142:143], v[120:121]
	v_cndmask_b32_e64 v141, v141, 0, s[30:31]
	v_pk_fma_f32 v[104:105], v[108:109], v[104:105], v[142:143]
	v_cndmask_b32_e64 v140, v140, 0, s[30:31]
	v_pk_fma_f32 v[92:93], v[92:93], v[112:113], v[104:105]
	v_mul_f32_e32 v104, 0xbfb8aa3b, v102
	v_exp_f32_e32 v104, v104
	v_pk_fma_f32 v[140:141], v[114:115], v[140:141], v[118:119]
	v_pk_fma_f32 v[138:139], v[106:107], v[138:139], v[140:141]
	v_add_f32_e32 v104, 1.0, v104
	v_rcp_f32_e32 v104, v104
	v_pk_fma_f32 v[90:91], v[90:91], v[110:111], v[138:139]
	v_add_u32_e32 v141, 0x90, v207
	v_add_u32_e32 v140, s46, v141
	v_mul_f32_e32 v102, v102, v104
	v_mul_f32_e32 v90, v102, v90
	v_mul_f32_e32 v102, 0xbfb8aa3b, v103
	v_exp_f32_e32 v102, v102
	s_nop 0
	v_add_f32_e32 v102, 1.0, v102
	v_rcp_f32_e32 v102, v102
	v_mov_b32_dpp v174, v86 row_ror:2 row_mask:0xf bank_mask:0xf
	v_mov_b32_dpp v175, v87 row_ror:2 row_mask:0xf bank_mask:0xf
	v_mov_b32_dpp v144, v86 row_ror:1 row_mask:0xf bank_mask:0xf
	v_mul_f32_e32 v102, v103, v102
	v_mul_f32_e32 v91, v102, v91
	v_mul_f32_e32 v102, 0xbfb8aa3b, v98
	v_exp_f32_e32 v102, v102
	v_mov_b32_dpp v145, v87 row_ror:1 row_mask:0xf bank_mask:0xf
	v_add_f32_e32 v102, 1.0, v102
	v_rcp_f32_e32 v102, v102
	v_cndmask_b32_e64 v104, v174, v170, s[8:9]
	v_cndmask_b32_e64 v105, v175, v171, s[8:9]
	v_mul_f32_e32 v98, v98, v102
	v_mul_f32_e32 v98, v98, v92
	v_mul_f32_e32 v92, 0xbfb8aa3b, v99
	v_exp_f32_e32 v92, v92
	v_mov_b32_dpp v172, v84 row_ror:2 row_mask:0xf bank_mask:0xf
	v_mov_b32_dpp v173, v85 row_ror:2 row_mask:0xf bank_mask:0xf
	v_add_f32_e32 v92, 1.0, v92
	v_rcp_f32_e32 v92, v92
	v_mov_b32_dpp v138, v84 row_ror:1 row_mask:0xf bank_mask:0xf
	v_mul_f32_e32 v92, v99, v92
	v_mul_f32_e32 v93, v92, v93
	v_cvt_pk_bf16_f32 v92, v90, v91
	v_and_b32_e32 v90, 0xfff, v140
	v_cmp_gt_u32_e64 s[38:39], 2, v90
	v_cmp_eq_u32_e64 s[40:41], 0, v90
	v_cndmask_b32_e64 v90, v144, v166, s[10:11]
	v_cndmask_b32_e64 v91, v145, v167, s[10:11]
	v_cndmask_b32_e64 v105, v105, 0, s[38:39]
	v_cndmask_b32_e64 v104, v104, 0, s[38:39]
	v_mov_b32_dpp v139, v85 row_ror:1 row_mask:0xf bank_mask:0xf
	v_cndmask_b32_e64 v102, v172, v168, s[8:9]
	v_cndmask_b32_e64 v103, v173, v169, s[8:9]
	v_cndmask_b32_e64 v91, v91, 0, s[40:41]
	v_cndmask_b32_e64 v90, v90, 0, s[40:41]
	v_pk_fma_f32 v[104:105], v[132:133], v[104:105], v[136:137]
	v_mov_b32_dpp v170, v82 row_ror:2 row_mask:0xf bank_mask:0xf
	v_mov_b32_dpp v171, v83 row_ror:2 row_mask:0xf bank_mask:0xf
	v_cvt_pk_bf16_f32 v93, v98, v93
	v_cndmask_b32_e64 v98, v138, v164, s[10:11]
	v_cndmask_b32_e64 v99, v139, v165, s[10:11]
	v_cndmask_b32_e64 v103, v103, 0, s[38:39]
	v_cndmask_b32_e64 v102, v102, 0, s[38:39]
	v_pk_fma_f32 v[90:91], v[128:129], v[90:91], v[104:105]
; __device__ __forceinline__ unsigned cvt_pk_bf16(float lo, float hi) { unsigned r; asm volatile("v_cvt_pk_bf16_f32 %0, %1, %2" : "=v"(r) : "v"(lo), "v"(hi)); return r; }
;     __device__ __forceinline__ void operator()(const f32x4 (&acc)[2][2][4][2], const Unit& u, int wr, int wc, int fr_, int fq_) const {
;     ...
;                 for (int m = 0; m < 4; ++m) {
;                     const int r = 128 * ai + 64 * wr + 16 * m + fr, R = R0 + r, t = R & (SEQ - 1);
;                     f32x4 y[2];
; #pragma unroll
;                     for (int bj = 0; bj < 2; ++bj) {
;                         const f32x4 X = acc[ai][bj][m][n]; const f32x4 r1 = dpp_ror(X, 1), r2 = dpp_ror(X, 2);
;                         f32x4 p1 = (fr == 0) ? pr1[bj] : r1, p2 = (fr < 2) ? pr2[bj] : r2;
;                         pr1[bj] = r1; pr2[bj] = r2;
;                         if (t == 0) p1 = (f32x4){0.f, 0.f, 0.f, 0.f};
;                         if (t <= 1) p2 = (f32x4){0.f, 0.f, 0.f, 0.f};
;                         y[bj] = bj == 0 ? (gb + g0 * p2 + g1 * p1 + g2 * X) : (vb + v0 * p2 + v1 * p1 + v2 * X);
;                     }
;                     f32x4 o;
;                     o.x = y[0].x * __builtin_amdgcn_rcpf(1.f + __builtin_amdgcn_exp2f(-LOG2E * y[0].x)) * y[1].x; o.y = y[0].y * __builtin_amdgcn_rcpf(1.f + __builtin_amdgcn_exp2f(-LOG2E * y[0].y)) * y[1].y;
;                     o.z = y[0].z * __builtin_amdgcn_rcpf(1.f + __builtin_amdgcn_exp2f(-LOG2E * y[0].z)) * y[1].z; o.w = y[0].w * __builtin_amdgcn_rcpf(1.f + __builtin_amdgcn_exp2f(-LOG2E * y[0].w)) * y[1].w;
;                     { u32x2 w; w.x = cvt_pk_bf16(o.x, o.y); w.y = cvt_pk_bf16(o.z, o.w);
;                       if (n == 0) keep[ai][m] = w;
;                       else if (r >= 2 && R < MTOK) { u32x4 w4; w4.x = keep[ai][m].x; w4.y = keep[ai][m].y; w4.z = w.x; w4.w = w.y; *(u32x4*)(Gout + (size_t)R * DFF + cr - 4) = w4; } }
	v_mov_b32_dpp v166, v82 row_ror:1 row_mask:0xf bank_mask:0xf
	v_mov_b32_dpp v167, v83 row_ror:1 row_mask:0xf bank_mask:0xf
	v_cndmask_b32_e64 v104, v170, v152, s[8:9]
	v_cndmask_b32_e64 v105, v171, v153, s[8:9]
	v_cndmask_b32_e64 v99, v99, 0, s[40:41]
	v_cndmask_b32_e64 v98, v98, 0, s[40:41]
	v_pk_fma_f32 v[102:103], v[130:131], v[102:103], v[134:135]
	v_pk_fma_f32 v[86:87], v[86:87], v[124:125], v[90:91]
	v_cndmask_b32_e64 v90, v166, v148, s[10:11]
	v_cndmask_b32_e64 v91, v167, v149, s[10:11]
	v_cndmask_b32_e64 v105, v105, 0, s[38:39]
	v_cndmask_b32_e64 v104, v104, 0, s[38:39]
	v_pk_fma_f32 v[98:99], v[126:127], v[98:99], v[102:103]
	v_cndmask_b32_e64 v91, v91, 0, s[40:41]
	v_cndmask_b32_e64 v90, v90, 0, s[40:41]
	v_pk_fma_f32 v[104:105], v[116:117], v[104:105], v[120:121]
	v_pk_fma_f32 v[84:85], v[84:85], v[122:123], v[98:99]
	v_pk_fma_f32 v[90:91], v[108:109], v[90:91], v[104:105]
	v_pk_fma_f32 v[82:83], v[82:83], v[112:113], v[90:91]
	v_mul_f32_e32 v90, 0xbfb8aa3b, v84
	v_exp_f32_e32 v90, v90
	v_mov_b32_dpp v168, v80 row_ror:2 row_mask:0xf bank_mask:0xf
	v_mov_b32_dpp v169, v81 row_ror:2 row_mask:0xf bank_mask:0xf
	v_add_f32_e32 v90, 1.0, v90
	v_mov_b32_dpp v164, v80 row_ror:1 row_mask:0xf bank_mask:0xf
	v_mov_b32_dpp v165, v81 row_ror:1 row_mask:0xf bank_mask:0xf
	v_cndmask_b32_e64 v102, v168, v150, s[8:9]
	v_cndmask_b32_e64 v103, v169, v151, s[8:9]
	v_rcp_f32_e32 v90, v90
	v_cndmask_b32_e64 v98, v164, v146, s[10:11]
	v_cndmask_b32_e64 v99, v165, v147, s[10:11]
	v_cndmask_b32_e64 v103, v103, 0, s[38:39]
	v_cndmask_b32_e64 v102, v102, 0, s[38:39]
	v_cndmask_b32_e64 v99, v99, 0, s[40:41]
	v_cndmask_b32_e64 v98, v98, 0, s[40:41]
	v_pk_fma_f32 v[102:103], v[114:115], v[102:103], v[118:119]
	v_mul_f32_e32 v84, v84, v90
	v_pk_fma_f32 v[98:99], v[106:107], v[98:99], v[102:103]
	v_add_u32_e32 v143, 0xa0, v207
	v_pk_fma_f32 v[80:81], v[80:81], v[110:111], v[98:99]
	v_add_u32_e32 v142, s46, v143
	v_mul_f32_e32 v80, v84, v80
	v_mul_f32_e32 v84, 0xbfb8aa3b, v85
	v_exp_f32_e32 v84, v84
	s_nop 0
	v_add_f32_e32 v84, 1.0, v84
	v_rcp_f32_e32 v84, v84
	v_mov_b32_dpp v146, v78 row_ror:2 row_mask:0xf bank_mask:0xf
	v_mov_b32_dpp v147, v79 row_ror:2 row_mask:0xf bank_mask:0xf
	v_mul_f32_e32 v84, v85, v84
	v_mul_f32_e32 v81, v84, v81
	v_mul_f32_e32 v84, 0xbfb8aa3b, v86
	v_exp_f32_e32 v84, v84
	v_cvt_pk_bf16_f32 v80, v80, v81
	v_mov_b32_dpp v102, v78 row_ror:1 row_mask:0xf bank_mask:0xf
	v_mov_b32_dpp v103, v79 row_ror:1 row_mask:0xf bank_mask:0xf
	v_add_f32_e32 v84, 1.0, v84
	v_rcp_f32_e32 v84, v84
	v_cndmask_b32_e64 v90, v146, v174, s[8:9]
	v_mul_f32_e32 v84, v86, v84
	v_mul_f32_e32 v82, v84, v82
	v_mul_f32_e32 v84, 0xbfb8aa3b, v87
	v_exp_f32_e32 v84, v84
	v_cndmask_b32_e64 v91, v147, v175, s[8:9]
	v_add_f32_e32 v84, 1.0, v84
	v_rcp_f32_e32 v84, v84
	v_mov_b32_dpp v104, v76 row_ror:2 row_mask:0xf bank_mask:0xf
	v_mov_b32_dpp v105, v77 row_ror:2 row_mask:0xf bank_mask:0xf
	v_mul_f32_e32 v84, v87, v84
	v_mul_f32_e32 v83, v84, v83
	v_cvt_pk_bf16_f32 v81, v82, v83
	v_and_b32_e32 v82, 0xfff, v142
	v_cmp_gt_u32_e64 s[42:43], 2, v82
	v_cmp_eq_u32_e64 s[44:45], 0, v82
	v_cndmask_b32_e64 v82, v102, v144, s[10:11]
	v_cndmask_b32_e64 v83, v103, v145, s[10:11]
	v_cndmask_b32_e64 v91, v91, 0, s[42:43]
	v_cndmask_b32_e64 v90, v90, 0, s[42:43]
	v_mov_b32_dpp v98, v76 row_ror:1 row_mask:0xf bank_mask:0xf
	v_mov_b32_dpp v99, v77 row_ror:1 row_mask:0xf bank_mask:0xf
	v_cndmask_b32_e64 v86, v104, v172, s[8:9]
	v_cndmask_b32_e64 v87, v105, v173, s[8:9]
	v_cndmask_b32_e64 v83, v83, 0, s[44:45]
	v_cndmask_b32_e64 v82, v82, 0, s[44:45]
	v_pk_fma_f32 v[90:91], v[132:133], v[90:91], v[136:137]
	v_mov_b32_dpp v152, v74 row_ror:2 row_mask:0xf bank_mask:0xf
	v_mov_b32_dpp v153, v75 row_ror:2 row_mask:0xf bank_mask:0xf
	v_cndmask_b32_e64 v84, v98, v138, s[10:11]
	v_cndmask_b32_e64 v85, v99, v139, s[10:11]
	v_cndmask_b32_e64 v87, v87, 0, s[42:43]
	v_cndmask_b32_e64 v86, v86, 0, s[42:43]
	v_pk_fma_f32 v[82:83], v[128:129], v[82:83], v[90:91]
	v_mov_b32_dpp v148, v74 row_ror:1 row_mask:0xf bank_mask:0xf
	v_mov_b32_dpp v149, v75 row_ror:1 row_mask:0xf bank_mask:0xf
	v_cndmask_b32_e64 v90, v152, v170, s[8:9]
	v_cndmask_b32_e64 v91, v153, v171, s[8:9]
	v_cndmask_b32_e64 v85, v85, 0, s[44:45]
	v_cndmask_b32_e64 v84, v84, 0, s[44:45]
	v_pk_fma_f32 v[86:87], v[130:131], v[86:87], v[134:135]
	v_pk_fma_f32 v[78:79], v[78:79], v[124:125], v[82:83]
	v_cndmask_b32_e64 v82, v148, v166, s[10:11]
	v_cndmask_b32_e64 v83, v149, v167, s[10:11]
	v_cndmask_b32_e64 v91, v91, 0, s[42:43]
	v_cndmask_b32_e64 v90, v90, 0, s[42:43]
	v_pk_fma_f32 v[84:85], v[126:127], v[84:85], v[86:87]
	v_cndmask_b32_e64 v83, v83, 0, s[44:45]
	v_cndmask_b32_e64 v82, v82, 0, s[44:45]
	v_pk_fma_f32 v[90:91], v[116:117], v[90:91], v[120:121]
	v_pk_fma_f32 v[76:77], v[76:77], v[122:123], v[84:85]
	v_pk_fma_f32 v[82:83], v[108:109], v[82:83], v[90:91]
	v_pk_fma_f32 v[74:75], v[74:75], v[112:113], v[82:83]
	v_mul_f32_e32 v82, 0xbfb8aa3b, v76
	v_exp_f32_e32 v82, v82
	v_mov_b32_dpp v150, v72 row_ror:2 row_mask:0xf bank_mask:0xf
	v_mov_b32_dpp v151, v73 row_ror:2 row_mask:0xf bank_mask:0xf
	v_add_f32_e32 v82, 1.0, v82
	v_mov_b32_dpp v138, v72 row_ror:1 row_mask:0xf bank_mask:0xf
	v_mov_b32_dpp v139, v73 row_ror:1 row_mask:0xf bank_mask:0xf
	v_cndmask_b32_e64 v86, v150, v168, s[8:9]
	v_cndmask_b32_e64 v87, v151, v169, s[8:9]
	v_rcp_f32_e32 v82, v82
	v_cndmask_b32_e64 v84, v138, v164, s[10:11]
	v_cndmask_b32_e64 v85, v139, v165, s[10:11]
	v_cndmask_b32_e64 v87, v87, 0, s[42:43]
	v_cndmask_b32_e64 v86, v86, 0, s[42:43]
	v_cndmask_b32_e64 v85, v85, 0, s[44:45]
	v_cndmask_b32_e64 v84, v84, 0, s[44:45]
	v_pk_fma_f32 v[86:87], v[114:115], v[86:87], v[118:119]
;     __device__ __forceinline__ void operator()(const f32x4 (&acc)[2][2][4][2], const Unit& u, int wr, int wc, int fr_, int fq_) const {
;     ...
;             const int cr = u.pn * 128 + wc * 32 + 8 * fq + 4 * n;
;             const f32x4 g0 = *(const f32x4*)(cw + cr), g1 = *(const f32x4*)(cw + NUP + cr), g2 = *(const f32x4*)(cw + 2 * NUP + cr), gb = *(const f32x4*)(cb + cr);
;             const f32x4 v0 = *(const f32x4*)(cw + DFF + cr), v1 = *(const f32x4*)(cw + NUP + DFF + cr), v2 = *(const f32x4*)(cw + 2 * NUP + DFF + cr), vb = *(const f32x4*)(cb + DFF + cr);
; #pragma unroll
;             for (int ai = 0; ai < 2; ++ai) {
;                 const int seg = 2 * ai + wr;
;                 f32x4 pr1[2], pr2[2];
; #pragma unroll
;                 for (int bj = 0; bj < 2; ++bj) {
;     ...
;                 for (int m = 0; m < 4; ++m) {
;                     const int r = 128 * ai + 64 * wr + 16 * m + fr, R = R0 + r, t = R & (SEQ - 1);
;                     f32x4 y[2];
; #pragma unroll
;                     for (int bj = 0; bj < 2; ++bj) {
;                         const f32x4 X = acc[ai][bj][m][n]; const f32x4 r1 = dpp_ror(X, 1), r2 = dpp_ror(X, 2);
;                         f32x4 p1 = (fr == 0) ? pr1[bj] : r1, p2 = (fr < 2) ? pr2[bj] : r2;
;                         pr1[bj] = r1; pr2[bj] = r2;
;                         if (t == 0) p1 = (f32x4){0.f, 0.f, 0.f, 0.f};
;                         if (t <= 1) p2 = (f32x4){0.f, 0.f, 0.f, 0.f};
;                         y[bj] = bj == 0 ? (gb + g0 * p2 + g1 * p1 + g2 * X) : (vb + v0 * p2 + v1 * p1 + v2 * X);
;                     }
;                     f32x4 o;
;                     o.x = y[0].x * __builtin_amdgcn_rcpf(1.f + __builtin_amdgcn_exp2f(-LOG2E * y[0].x)) * y[1].x; o.y = y[0].y * __builtin_amdgcn_rcpf(1.f + __builtin_amdgcn_exp2f(-LOG2E * y[0].y)) * y[1].y;
;                     o.z = y[0].z * __builtin_amdgcn_rcpf(1.f + __builtin_amdgcn_exp2f(-LOG2E * y[0].z)) * y[1].z; o.w = y[0].w * __builtin_amdgcn_rcpf(1.f + __builtin_amdgcn_exp2f(-LOG2E * y[0].w)) * y[1].w;
;                     { u32x2 w; w.x = cvt_pk_bf16(o.x, o.y); w.y = cvt_pk_bf16(o.z, o.w);
;                       if (n == 0) keep[ai][m] = w;
;                       else if (r >= 2 && R < MTOK) { u32x4 w4; w4.x = keep[ai][m].x; w4.y = keep[ai][m].y; w4.z = w.x; w4.w = w.y; *(u32x4*)(Gout + (size_t)R * DFF + cr - 4) = w4; } }
	v_mul_f32_e32 v76, v76, v82
	v_pk_fma_f32 v[84:85], v[106:107], v[84:85], v[86:87]
	v_add_u32_e32 v145, 0xb0, v207
	v_pk_fma_f32 v[72:73], v[72:73], v[110:111], v[84:85]
	v_add_u32_e32 v144, s46, v145
	v_mul_f32_e32 v72, v76, v72
	v_mul_f32_e32 v76, 0xbfb8aa3b, v77
	v_exp_f32_e32 v76, v76
	s_and_b64 vcc, exec, s[28:29]
	v_add_f32_e32 v76, 1.0, v76
	v_rcp_f32_e32 v76, v76
	v_mov_b32_dpp v82, v70 row_ror:2 row_mask:0xf bank_mask:0xf
	v_mov_b32_dpp v83, v71 row_ror:2 row_mask:0xf bank_mask:0xf
	v_cndmask_b32_e64 v82, v82, v146, s[8:9]
	v_mul_f32_e32 v76, v77, v76
	v_mul_f32_e32 v73, v76, v73
	v_mul_f32_e32 v76, 0xbfb8aa3b, v78
	v_exp_f32_e32 v76, v76
	v_cvt_pk_bf16_f32 v72, v72, v73
	v_cndmask_b32_e64 v83, v83, v147, s[8:9]
	v_add_f32_e32 v76, 1.0, v76
	v_rcp_f32_e32 v76, v76
	v_mov_b32_dpp v77, v71 row_ror:1 row_mask:0xf bank_mask:0xf
	v_mul_f32_e32 v76, v78, v76
	v_mul_f32_e32 v74, v76, v74
	v_mul_f32_e32 v76, 0xbfb8aa3b, v79
	v_exp_f32_e32 v76, v76
	s_nop 0
	v_add_f32_e32 v76, 1.0, v76
	v_rcp_f32_e32 v76, v76
	v_mov_b32_dpp v78, v68 row_ror:2 row_mask:0xf bank_mask:0xf
	v_cndmask_b32_e64 v78, v78, v104, s[8:9]
	v_mul_f32_e32 v76, v79, v76
	v_mul_f32_e32 v75, v76, v75
	v_cvt_pk_bf16_f32 v73, v74, v75
	v_and_b32_e32 v74, 0xfff, v144
	v_cmp_eq_u32_e64 s[48:49], 0, v74
	v_cmp_gt_u32_e64 s[46:47], 2, v74
	v_mov_b32_dpp v79, v69 row_ror:2 row_mask:0xf bank_mask:0xf
	v_mov_b32_dpp v74, v68 row_ror:1 row_mask:0xf bank_mask:0xf
	v_mov_b32_dpp v75, v69 row_ror:1 row_mask:0xf bank_mask:0xf
	v_mov_b32_dpp v76, v70 row_ror:1 row_mask:0xf bank_mask:0xf
	v_cndmask_b32_e64 v79, v79, v105, s[8:9]
	v_cndmask_b32_e64 v84, v74, v98, s[10:11]
	v_cndmask_b32_e64 v85, v75, v99, s[10:11]
	v_cndmask_b32_e64 v74, v76, v102, s[10:11]
	v_cndmask_b32_e64 v75, v77, v103, s[10:11]
	v_cndmask_b32_e64 v79, v79, 0, s[46:47]
	v_cndmask_b32_e64 v78, v78, 0, s[46:47]
	v_cndmask_b32_e64 v83, v83, 0, s[46:47]
	v_cndmask_b32_e64 v82, v82, 0, s[46:47]
	v_cndmask_b32_e64 v75, v75, 0, s[48:49]
	v_cndmask_b32_e64 v74, v74, 0, s[48:49]
	v_cndmask_b32_e64 v77, v85, 0, s[48:49]
	v_cndmask_b32_e64 v76, v84, 0, s[48:49]
	v_pk_fma_f32 v[82:83], v[132:133], v[82:83], v[136:137]
	v_pk_fma_f32 v[78:79], v[130:131], v[78:79], v[134:135]
	v_pk_fma_f32 v[74:75], v[128:129], v[74:75], v[82:83]
	v_pk_fma_f32 v[76:77], v[126:127], v[76:77], v[78:79]
	v_pk_fma_f32 v[70:71], v[70:71], v[124:125], v[74:75]
	v_pk_fma_f32 v[68:69], v[68:69], v[122:123], v[76:77]
	v_mov_b32_dpp v82, v66 row_ror:2 row_mask:0xf bank_mask:0xf
	v_mov_b32_dpp v83, v67 row_ror:2 row_mask:0xf bank_mask:0xf
	v_mov_b32_dpp v74, v64 row_ror:1 row_mask:0xf bank_mask:0xf
	v_mov_b32_dpp v75, v65 row_ror:1 row_mask:0xf bank_mask:0xf
	v_mov_b32_dpp v76, v66 row_ror:1 row_mask:0xf bank_mask:0xf
	v_mov_b32_dpp v77, v67 row_ror:1 row_mask:0xf bank_mask:0xf
	v_cndmask_b32_e64 v82, v82, v152, s[8:9]
	v_cndmask_b32_e64 v83, v83, v153, s[8:9]
	v_cndmask_b32_e64 v84, v74, v138, s[10:11]
	v_cndmask_b32_e64 v85, v75, v139, s[10:11]
	v_cndmask_b32_e64 v74, v76, v148, s[10:11]
	v_cndmask_b32_e64 v75, v77, v149, s[10:11]
	v_cndmask_b32_e64 v83, v83, 0, s[46:47]
	v_cndmask_b32_e64 v82, v82, 0, s[46:47]
	v_cndmask_b32_e64 v75, v75, 0, s[48:49]
	v_cndmask_b32_e64 v74, v74, 0, s[48:49]
	v_pk_fma_f32 v[82:83], v[116:117], v[82:83], v[120:121]
	v_pk_fma_f32 v[74:75], v[108:109], v[74:75], v[82:83]
	v_pk_fma_f32 v[66:67], v[66:67], v[112:113], v[74:75]
	v_mul_f32_e32 v74, 0xbfb8aa3b, v68
	v_exp_f32_e32 v74, v74
	v_mov_b32_dpp v78, v64 row_ror:2 row_mask:0xf bank_mask:0xf
	v_mov_b32_dpp v79, v65 row_ror:2 row_mask:0xf bank_mask:0xf
	v_cndmask_b32_e64 v78, v78, v150, s[8:9]
	v_add_f32_e32 v74, 1.0, v74
	v_cndmask_b32_e64 v79, v79, v151, s[8:9]
	v_rcp_f32_e32 v74, v74
	v_cndmask_b32_e64 v79, v79, 0, s[46:47]
	v_cndmask_b32_e64 v78, v78, 0, s[46:47]
	v_cndmask_b32_e64 v77, v85, 0, s[48:49]
	v_cndmask_b32_e64 v76, v84, 0, s[48:49]
	v_pk_fma_f32 v[78:79], v[114:115], v[78:79], v[118:119]
	v_mul_f32_e32 v68, v68, v74
	v_pk_fma_f32 v[76:77], v[106:107], v[76:77], v[78:79]
	s_nop 0
	v_pk_fma_f32 v[64:65], v[64:65], v[110:111], v[76:77]
	s_nop 0
	v_mul_f32_e32 v64, v68, v64
	v_mul_f32_e32 v68, 0xbfb8aa3b, v69
	v_exp_f32_e32 v68, v68
	s_nop 0
	v_add_f32_e32 v68, 1.0, v68
	v_rcp_f32_e32 v68, v68
	s_nop 0
	v_mul_f32_e32 v68, v69, v68
	v_mul_f32_e32 v65, v68, v65
	v_mul_f32_e32 v68, 0xbfb8aa3b, v70
	v_exp_f32_e32 v68, v68
	v_cvt_pk_bf16_f32 v64, v64, v65
	s_nop 0
	v_add_f32_e32 v68, 1.0, v68
	v_rcp_f32_e32 v68, v68
	s_nop 0
	v_mul_f32_e32 v68, v70, v68
	v_mul_f32_e32 v66, v68, v66
	v_mul_f32_e32 v68, 0xbfb8aa3b, v71
	v_exp_f32_e32 v68, v68
	s_nop 0
	v_add_f32_e32 v68, 1.0, v68
	v_rcp_f32_e32 v68, v68
	s_nop 0
	v_mul_f32_e32 v68, v71, v68
	v_mul_f32_e32 v67, v68, v67
	v_cvt_pk_bf16_f32 v65, v66, v67
	v_or_b32_e32 v66, 4, v194
	v_ashrrev_i32_e32 v67, 31, v66
	v_lshlrev_b64 v[70:71], 2, v[66:67]
	v_lshl_add_u64 v[66:67], s[50:51], 0, v[70:71]
	global_load_dwordx4 v[112:115], v[198:199], off offset:16
	global_load_dwordx4 v[108:111], v[66:67], off
	v_lshl_add_u64 v[66:67], s[56:57], 0, v[70:71]
	global_load_dwordx4 v[116:119], v[66:67], off
	global_load_dwordx4 v[120:123], v[196:197], off offset:16
	v_lshl_add_u64 v[66:67], s[58:59], 0, v[70:71]
	global_load_dwordx4 v[84:87], v[66:67], off
	v_lshl_add_u64 v[66:67], s[60:61], 0, v[70:71]
	global_load_dwordx4 v[76:79], v[66:67], off
	v_lshl_add_u64 v[66:67], s[62:63], 0, v[70:71]
	v_lshl_add_u64 v[70:71], s[64:65], 0, v[70:71]
	global_load_dwordx4 v[66:69], v[66:67], off
	s_nop 0
	global_load_dwordx4 v[104:107], v[70:71], off
	v_lshlrev_b32_e32 v70, 2, v208
	s_cbranch_vccnz .LBB0_973
	v_add_u32_e32 v71, 0xfffffc10, v162
	s_movk_i32 s75, 0xf810
	v_add3_u32 v74, v162, v70, s75
	ds_read_b128 v[136:139], v71
	ds_read_b128 v[132:135], v74
	s_and_b64 vcc, exec, s[28:29]
	s_cbranch_vccnz .LBB0_974

; __device__ __forceinline__ unsigned cvt_pk_bf16(float lo, float hi) { unsigned r; asm volatile("v_cvt_pk_bf16_f32 %0, %1, %2" : "=v"(r) : "v"(lo), "v"(hi)); return r; }
;     __device__ __forceinline__ void operator()(const f32x4 (&acc)[2][2][4][2], const Unit& u, int wr, int wc, int fr_, int fq_) const {
;     ...
;                         const f32x4 X = acc[ai][bj][m][n]; const f32x4 r1 = dpp_ror(X, 1), r2 = dpp_ror(X, 2);
;                         f32x4 p1 = (fr == 0) ? pr1[bj] : r1, p2 = (fr < 2) ? pr2[bj] : r2;
;                         pr1[bj] = r1; pr2[bj] = r2;
;                         if (t == 0) p1 = (f32x4){0.f, 0.f, 0.f, 0.f};
;                         if (t <= 1) p2 = (f32x4){0.f, 0.f, 0.f, 0.f};
;                         y[bj] = bj == 0 ? (gb + g0 * p2 + g1 * p1 + g2 * X) : (vb + v0 * p2 + v1 * p1 + v2 * X);
;                     }
;                     f32x4 o;
;                     o.x = y[0].x * __builtin_amdgcn_rcpf(1.f + __builtin_amdgcn_exp2f(-LOG2E * y[0].x)) * y[1].x; o.y = y[0].y * __builtin_amdgcn_rcpf(1.f + __builtin_amdgcn_exp2f(-LOG2E * y[0].y)) * y[1].y;
;                     o.z = y[0].z * __builtin_amdgcn_rcpf(1.f + __builtin_amdgcn_exp2f(-LOG2E * y[0].z)) * y[1].z; o.w = y[0].w * __builtin_amdgcn_rcpf(1.f + __builtin_amdgcn_exp2f(-LOG2E * y[0].w)) * y[1].w;
;                     { u32x2 w; w.x = cvt_pk_bf16(o.x, o.y); w.y = cvt_pk_bf16(o.z, o.w);
;                       if (n == 0) keep[ai][m] = w;
;                       else if (r >= 2 && R < MTOK) { u32x4 w4; w4.x = keep[ai][m].x; w4.y = keep[ai][m].y; w4.z = w.x; w4.w = w.y; *(u32x4*)(Gout + (size_t)R * DFF + cr - 4) = w4; } }
.LBB0_975:
	v_mov_b32_dpp v75, v60 row_ror:2 row_mask:0xf bank_mask:0xf
	v_mov_b32_dpp v83, v61 row_ror:2 row_mask:0xf bank_mask:0xf
	v_mov_b32_dpp v90, v62 row_ror:2 row_mask:0xf bank_mask:0xf
	v_mov_b32_dpp v91, v63 row_ror:2 row_mask:0xf bank_mask:0xf
	v_mov_b32_dpp v70, v60 row_ror:1 row_mask:0xf bank_mask:0xf
	v_mov_b32_dpp v71, v61 row_ror:1 row_mask:0xf bank_mask:0xf
	v_mov_b32_dpp v74, v62 row_ror:1 row_mask:0xf bank_mask:0xf
	v_mov_b32_dpp v82, v63 row_ror:1 row_mask:0xf bank_mask:0xf
	s_waitcnt lgkmcnt(0)
	v_cndmask_b32_e64 v134, v90, v134, s[8:9]
	v_cndmask_b32_e64 v135, v91, v135, s[8:9]
	v_cndmask_b32_e64 v132, v75, v132, s[8:9]
	v_cndmask_b32_e64 v133, v83, v133, s[8:9]
	v_cndmask_b32_e64 v102, v70, v136, s[10:11]
	v_cndmask_b32_e64 v103, v71, v137, s[10:11]
	v_cndmask_b32_e64 v98, v74, v138, s[10:11]
	v_cndmask_b32_e64 v99, v82, v139, s[10:11]
	v_cndmask_b32_e64 v133, v133, 0, s[16:17]
	v_cndmask_b32_e64 v132, v132, 0, s[16:17]
	v_cndmask_b32_e64 v135, v135, 0, s[16:17]
	v_cndmask_b32_e64 v134, v134, 0, s[16:17]
	v_cndmask_b32_e64 v99, v99, 0, s[18:19]
	v_cndmask_b32_e64 v98, v98, 0, s[18:19]
	v_cndmask_b32_e64 v103, v103, 0, s[18:19]
	v_cndmask_b32_e64 v102, v102, 0, s[18:19]
	s_waitcnt vmcnt(4)
	v_pk_fma_f32 v[134:135], v[114:115], v[134:135], v[122:123]
	v_pk_fma_f32 v[132:133], v[112:113], v[132:133], v[120:121]
	v_pk_fma_f32 v[98:99], v[110:111], v[98:99], v[134:135]
	v_pk_fma_f32 v[102:103], v[108:109], v[102:103], v[132:133]
	v_pk_fma_f32 v[98:99], v[62:63], v[118:119], v[98:99]
	v_pk_fma_f32 v[134:135], v[60:61], v[116:117], v[102:103]
	v_mov_b32_dpp v62, v58 row_ror:1 row_mask:0xf bank_mask:0xf
	v_mov_b32_dpp v102, v59 row_ror:1 row_mask:0xf bank_mask:0xf
	v_mov_b32_dpp v132, v58 row_ror:2 row_mask:0xf bank_mask:0xf
	v_mov_b32_dpp v133, v59 row_ror:2 row_mask:0xf bank_mask:0xf
	v_mov_b32_dpp v63, v56 row_ror:2 row_mask:0xf bank_mask:0xf
	v_mov_b32_dpp v103, v57 row_ror:2 row_mask:0xf bank_mask:0xf
	v_cndmask_b32_e64 v130, v62, v130, s[10:11]
	v_cndmask_b32_e64 v131, v102, v131, s[10:11]
	v_cndmask_b32_e64 v136, v132, v126, s[8:9]
	v_cndmask_b32_e64 v137, v133, v127, s[8:9]
	v_cndmask_b32_e64 v138, v63, v124, s[8:9]
	v_cndmask_b32_e64 v139, v103, v125, s[8:9]
	v_cndmask_b32_e64 v125, v131, 0, s[18:19]
	v_cndmask_b32_e64 v124, v130, 0, s[18:19]
	v_cndmask_b32_e64 v131, v137, 0, s[16:17]
	v_cndmask_b32_e64 v130, v136, 0, s[16:17]
	s_waitcnt vmcnt(0)
	v_pk_fma_f32 v[130:131], v[86:87], v[130:131], v[106:107]
	v_pk_fma_f32 v[124:125], v[78:79], v[124:125], v[130:131]
	v_pk_fma_f32 v[58:59], v[58:59], v[68:69], v[124:125]
	v_mul_f32_e32 v124, 0xbfb8aa3b, v134
	v_exp_f32_e32 v124, v124
	v_mov_b32_dpp v60, v56 row_ror:1 row_mask:0xf bank_mask:0xf
	v_mov_b32_dpp v61, v57 row_ror:1 row_mask:0xf bank_mask:0xf
	v_cndmask_b32_e64 v128, v60, v128, s[10:11]
	v_add_f32_e32 v124, 1.0, v124
	v_cndmask_b32_e64 v129, v61, v129, s[10:11]
	v_rcp_f32_e32 v124, v124
	v_cndmask_b32_e64 v127, v129, 0, s[18:19]
	v_cndmask_b32_e64 v126, v128, 0, s[18:19]
	v_cndmask_b32_e64 v129, v139, 0, s[16:17]
	v_cndmask_b32_e64 v128, v138, 0, s[16:17]
	v_pk_fma_f32 v[128:129], v[84:85], v[128:129], v[104:105]
	v_mul_f32_e32 v124, v134, v124
	v_pk_fma_f32 v[126:127], v[76:77], v[126:127], v[128:129]
	v_cmp_lt_i32_e32 vcc, 1, v207
	v_pk_fma_f32 v[56:57], v[56:57], v[66:67], v[126:127]
	v_cmp_gt_i32_e64 s[16:17], s89, v206
	v_mul_f32_e32 v56, v124, v56
	v_mul_f32_e32 v124, 0xbfb8aa3b, v135
	v_exp_f32_e32 v124, v124
	s_and_b64 s[18:19], vcc, s[16:17]
	v_add_f32_e32 v124, 1.0, v124
	v_rcp_f32_e32 v124, v124
	s_nop 0
	v_mul_f32_e32 v124, v135, v124
	v_mul_f32_e32 v57, v124, v57
	v_mul_f32_e32 v124, 0xbfb8aa3b, v98
	v_exp_f32_e32 v124, v124
	s_nop 0
	v_add_f32_e32 v124, 1.0, v124
	v_rcp_f32_e32 v124, v124
	s_nop 0
	v_mul_f32_e32 v98, v98, v124
	v_mul_f32_e32 v58, v98, v58
	v_mul_f32_e32 v98, 0xbfb8aa3b, v99
	v_exp_f32_e32 v98, v98
	s_nop 0
	v_add_f32_e32 v98, 1.0, v98
	v_rcp_f32_e32 v98, v98
	s_nop 0
	v_mul_f32_e32 v98, v99, v98
	v_mul_f32_e32 v59, v98, v59
	v_cvt_pk_bf16_f32 v98, v56, v57
	v_cvt_pk_bf16_f32 v99, v58, v59
	s_and_saveexec_b64 s[16:17], s[18:19]
	s_cbranch_execz .LBB0_977
	v_mov_b64_e32 v[56:57], s[4:5]
	v_mad_i64_i32 v[56:57], s[18:19], v206, s3, v[56:57]
	v_lshl_add_u64 v[56:57], v[194:195], 1, v[56:57]
	global_store_dwordx4 v[56:57], v[96:99], off
; __device__ __forceinline__ unsigned cvt_pk_bf16(float lo, float hi) { unsigned r; asm volatile("v_cvt_pk_bf16_f32 %0, %1, %2" : "=v"(r) : "v"(lo), "v"(hi)); return r; }
;     __device__ __forceinline__ void operator()(const f32x4 (&acc)[2][2][4][2], const Unit& u, int wr, int wc, int fr_, int fq_) const {
;     ...
;                         const f32x4 X = acc[ai][bj][m][n]; const f32x4 r1 = dpp_ror(X, 1), r2 = dpp_ror(X, 2);
;                         f32x4 p1 = (fr == 0) ? pr1[bj] : r1, p2 = (fr < 2) ? pr2[bj] : r2;
;                         pr1[bj] = r1; pr2[bj] = r2;
;                         if (t == 0) p1 = (f32x4){0.f, 0.f, 0.f, 0.f};
;                         if (t <= 1) p2 = (f32x4){0.f, 0.f, 0.f, 0.f};
;                         y[bj] = bj == 0 ? (gb + g0 * p2 + g1 * p1 + g2 * X) : (vb + v0 * p2 + v1 * p1 + v2 * X);
;                     }
;                     f32x4 o;
;                     o.x = y[0].x * __builtin_amdgcn_rcpf(1.f + __builtin_amdgcn_exp2f(-LOG2E * y[0].x)) * y[1].x; o.y = y[0].y * __builtin_amdgcn_rcpf(1.f + __builtin_amdgcn_exp2f(-LOG2E * y[0].y)) * y[1].y;
;                     o.z = y[0].z * __builtin_amdgcn_rcpf(1.f + __builtin_amdgcn_exp2f(-LOG2E * y[0].z)) * y[1].z; o.w = y[0].w * __builtin_amdgcn_rcpf(1.f + __builtin_amdgcn_exp2f(-LOG2E * y[0].w)) * y[1].w;
;                     { u32x2 w; w.x = cvt_pk_bf16(o.x, o.y); w.y = cvt_pk_bf16(o.z, o.w);
;                       if (n == 0) keep[ai][m] = w;
;                       else if (r >= 2 && R < MTOK) { u32x4 w4; w4.x = keep[ai][m].x; w4.y = keep[ai][m].y; w4.z = w.x; w4.w = w.y; *(u32x4*)(Gout + (size_t)R * DFF + cr - 4) = w4; } }
.LBB0_977:
	s_or_b64 exec, exec, s[16:17]
	v_mov_b32_dpp v124, v54 row_ror:1 row_mask:0xf bank_mask:0xf
	v_mov_b32_dpp v126, v55 row_ror:1 row_mask:0xf bank_mask:0xf
	v_mov_b32_dpp v128, v54 row_ror:2 row_mask:0xf bank_mask:0xf
	v_mov_b32_dpp v129, v55 row_ror:2 row_mask:0xf bank_mask:0xf
	v_mov_b32_dpp v98, v52 row_ror:1 row_mask:0xf bank_mask:0xf
	v_mov_b32_dpp v99, v53 row_ror:1 row_mask:0xf bank_mask:0xf
	v_mov_b32_dpp v125, v52 row_ror:2 row_mask:0xf bank_mask:0xf
	v_mov_b32_dpp v127, v53 row_ror:2 row_mask:0xf bank_mask:0xf
	v_cndmask_b32_e64 v56, v124, v74, s[10:11]
	v_cndmask_b32_e64 v57, v126, v82, s[10:11]
	v_cndmask_b32_e64 v74, v128, v90, s[8:9]
	v_cndmask_b32_e64 v82, v129, v91, s[8:9]
	v_cndmask_b32_e64 v58, v98, v70, s[10:11]
	v_cndmask_b32_e64 v59, v99, v71, s[10:11]
	v_cndmask_b32_e64 v70, v125, v75, s[8:9]
	v_cndmask_b32_e64 v71, v127, v83, s[8:9]
	v_cndmask_b32_e64 v75, v82, 0, s[24:25]
	v_cndmask_b32_e64 v74, v74, 0, s[24:25]
	v_cndmask_b32_e64 v57, v57, 0, s[26:27]
	v_cndmask_b32_e64 v56, v56, 0, s[26:27]
	v_cndmask_b32_e64 v71, v71, 0, s[24:25]
	v_cndmask_b32_e64 v70, v70, 0, s[24:25]
	v_pk_fma_f32 v[74:75], v[114:115], v[74:75], v[122:123]
	v_cndmask_b32_e64 v59, v59, 0, s[26:27]
	v_cndmask_b32_e64 v58, v58, 0, s[26:27]
	v_pk_fma_f32 v[70:71], v[112:113], v[70:71], v[120:121]
	v_pk_fma_f32 v[56:57], v[110:111], v[56:57], v[74:75]
	v_pk_fma_f32 v[58:59], v[108:109], v[58:59], v[70:71]
	v_pk_fma_f32 v[82:83], v[54:55], v[118:119], v[56:57]
	v_pk_fma_f32 v[52:53], v[52:53], v[116:117], v[58:59]
	v_mov_b32_dpp v54, v48 row_ror:1 row_mask:0xf bank_mask:0xf
	v_cndmask_b32_e64 v55, v54, v60, s[10:11]
	v_mov_b32_dpp v58, v50 row_ror:1 row_mask:0xf bank_mask:0xf
	v_cndmask_b32_e64 v60, v58, v62, s[10:11]
	v_cndmask_b32_e64 v62, v55, 0, s[26:27]
	v_mul_f32_e32 v55, 0xbfb8aa3b, v52
	v_exp_f32_e32 v55, v55
	v_mov_b32_dpp v59, v48 row_ror:2 row_mask:0xf bank_mask:0xf
	v_mov_b32_dpp v71, v49 row_ror:2 row_mask:0xf bank_mask:0xf
	v_add_f32_e32 v55, 1.0, v55
	v_mov_b32_dpp v56, v49 row_ror:1 row_mask:0xf bank_mask:0xf
	v_cndmask_b32_e64 v90, v59, v63, s[8:9]
	v_cndmask_b32_e64 v91, v71, v103, s[8:9]
	v_rcp_f32_e32 v55, v55
	v_cndmask_b32_e64 v57, v56, v61, s[10:11]
	v_cndmask_b32_e64 v91, v91, 0, s[24:25]
	v_cndmask_b32_e64 v90, v90, 0, s[24:25]
	v_cndmask_b32_e64 v63, v57, 0, s[26:27]
	v_pk_fma_f32 v[90:91], v[84:85], v[90:91], v[104:105]
	v_mul_f32_e32 v52, v52, v55
	v_pk_fma_f32 v[62:63], v[76:77], v[62:63], v[90:91]
	v_pk_fma_f32 v[48:49], v[48:49], v[66:67], v[62:63]
	v_mul_f32_e32 v48, v52, v48
	v_mul_f32_e32 v52, 0xbfb8aa3b, v53
	v_exp_f32_e32 v52, v52
	v_mov_b32_dpp v74, v50 row_ror:2 row_mask:0xf bank_mask:0xf
	v_mov_b32_dpp v75, v51 row_ror:2 row_mask:0xf bank_mask:0xf
	v_add_f32_e32 v52, 1.0, v52
	v_rcp_f32_e32 v52, v52
	v_mov_b32_dpp v70, v51 row_ror:1 row_mask:0xf bank_mask:0xf
	v_cndmask_b32_e64 v96, v74, v132, s[8:9]
	v_cndmask_b32_e64 v97, v75, v133, s[8:9]
	v_mul_f32_e32 v52, v53, v52
	v_mul_f32_e32 v49, v52, v49
	v_mul_f32_e32 v52, 0xbfb8aa3b, v82
	v_exp_f32_e32 v52, v52
	v_cndmask_b32_e64 v61, v70, v102, s[10:11]
	v_cndmask_b32_e64 v97, v97, 0, s[24:25]
	v_cndmask_b32_e64 v96, v96, 0, s[24:25]
	v_add_f32_e32 v52, 1.0, v52
	v_rcp_f32_e32 v52, v52
	v_cndmask_b32_e64 v61, v61, 0, s[26:27]
	v_cndmask_b32_e64 v60, v60, 0, s[26:27]
	v_pk_fma_f32 v[96:97], v[86:87], v[96:97], v[106:107]
	v_mul_f32_e32 v52, v82, v52
	v_pk_fma_f32 v[60:61], v[78:79], v[60:61], v[96:97]
	v_cmp_lt_i32_e32 vcc, 1, v159
	v_pk_fma_f32 v[50:51], v[50:51], v[68:69], v[60:61]
	v_cmp_gt_i32_e64 s[16:17], s89, v158
	v_mul_f32_e32 v50, v52, v50
	v_mul_f32_e32 v52, 0xbfb8aa3b, v83
	v_exp_f32_e32 v52, v52
	s_and_b64 s[18:19], vcc, s[16:17]
	v_cvt_pk_bf16_f32 v96, v48, v49
	v_add_f32_e32 v52, 1.0, v52
	v_rcp_f32_e32 v52, v52
	s_nop 0
	v_mul_f32_e32 v52, v83, v52
	v_mul_f32_e32 v51, v52, v51
	v_cvt_pk_bf16_f32 v97, v50, v51
	s_and_saveexec_b64 s[16:17], s[18:19]
	s_cbranch_execz .LBB0_979
	v_mov_b64_e32 v[48:49], s[4:5]
	v_mad_i64_i32 v[48:49], s[18:19], v158, s3, v[48:49]
	v_lshl_add_u64 v[48:49], v[194:195], 1, v[48:49]
	global_store_dwordx4 v[48:49], v[94:97], off
.LBB0_979:
	s_or_b64 exec, exec, s[16:17]
	v_mov_b32_dpp v51, v44 row_ror:2 row_mask:0xf bank_mask:0xf
	v_mov_b32_dpp v53, v45 row_ror:2 row_mask:0xf bank_mask:0xf
	v_mov_b32_dpp v55, v46 row_ror:2 row_mask:0xf bank_mask:0xf
	v_mov_b32_dpp v57, v47 row_ror:2 row_mask:0xf bank_mask:0xf
	v_mov_b32_dpp v48, v44 row_ror:1 row_mask:0xf bank_mask:0xf
	v_mov_b32_dpp v49, v45 row_ror:1 row_mask:0xf bank_mask:0xf
	v_mov_b32_dpp v50, v46 row_ror:1 row_mask:0xf bank_mask:0xf
	v_mov_b32_dpp v52, v47 row_ror:1 row_mask:0xf bank_mask:0xf
	v_cndmask_b32_e64 v90, v55, v128, s[8:9]
	v_cndmask_b32_e64 v91, v57, v129, s[8:9]
	v_cndmask_b32_e64 v82, v51, v125, s[8:9]
	v_cndmask_b32_e64 v83, v53, v127, s[8:9]
	v_cndmask_b32_e64 v62, v48, v98, s[10:11]
	v_cndmask_b32_e64 v63, v49, v99, s[10:11]
	v_cndmask_b32_e64 v60, v50, v124, s[10:11]
	v_cndmask_b32_e64 v61, v52, v126, s[10:11]
	v_cndmask_b32_e64 v83, v83, 0, s[20:21]
	v_cndmask_b32_e64 v82, v82, 0, s[20:21]
	v_cndmask_b32_e64 v91, v91, 0, s[20:21]
	v_cndmask_b32_e64 v90, v90, 0, s[20:21]
	v_cndmask_b32_e64 v61, v61, 0, s[22:23]
	v_cndmask_b32_e64 v60, v60, 0, s[22:23]
	v_cndmask_b32_e64 v63, v63, 0, s[22:23]
	v_cndmask_b32_e64 v62, v62, 0, s[22:23]
	v_pk_fma_f32 v[90:91], v[114:115], v[90:91], v[122:123]
	v_pk_fma_f32 v[82:83], v[112:113], v[82:83], v[120:121]
	v_pk_fma_f32 v[60:61], v[110:111], v[60:61], v[90:91]
	v_pk_fma_f32 v[62:63], v[108:109], v[62:63], v[82:83]
	v_pk_fma_f32 v[82:83], v[46:47], v[118:119], v[60:61]
	v_pk_fma_f32 v[90:91], v[44:45], v[116:117], v[62:63]
; __device__ __forceinline__ unsigned cvt_pk_bf16(float lo, float hi) { unsigned r; asm volatile("v_cvt_pk_bf16_f32 %0, %1, %2" : "=v"(r) : "v"(lo), "v"(hi)); return r; }
;     __device__ __forceinline__ void operator()(const f32x4 (&acc)[2][2][4][2], const Unit& u, int wr, int wc, int fr_, int fq_) const {
;     ...
;                         const f32x4 X = acc[ai][bj][m][n]; const f32x4 r1 = dpp_ror(X, 1), r2 = dpp_ror(X, 2);
;                         f32x4 p1 = (fr == 0) ? pr1[bj] : r1, p2 = (fr < 2) ? pr2[bj] : r2;
;                         pr1[bj] = r1; pr2[bj] = r2;
;                         if (t == 0) p1 = (f32x4){0.f, 0.f, 0.f, 0.f};
;                         if (t <= 1) p2 = (f32x4){0.f, 0.f, 0.f, 0.f};
;                         y[bj] = bj == 0 ? (gb + g0 * p2 + g1 * p1 + g2 * X) : (vb + v0 * p2 + v1 * p1 + v2 * X);
;                     }
;                     f32x4 o;
;                     o.x = y[0].x * __builtin_amdgcn_rcpf(1.f + __builtin_amdgcn_exp2f(-LOG2E * y[0].x)) * y[1].x; o.y = y[0].y * __builtin_amdgcn_rcpf(1.f + __builtin_amdgcn_exp2f(-LOG2E * y[0].y)) * y[1].y;
;                     o.z = y[0].z * __builtin_amdgcn_rcpf(1.f + __builtin_amdgcn_exp2f(-LOG2E * y[0].z)) * y[1].z; o.w = y[0].w * __builtin_amdgcn_rcpf(1.f + __builtin_amdgcn_exp2f(-LOG2E * y[0].w)) * y[1].w;
;                     { u32x2 w; w.x = cvt_pk_bf16(o.x, o.y); w.y = cvt_pk_bf16(o.z, o.w);
;                       if (n == 0) keep[ai][m] = w;
;                       else if (r >= 2 && R < MTOK) { u32x4 w4; w4.x = keep[ai][m].x; w4.y = keep[ai][m].y; w4.z = w.x; w4.w = w.y; *(u32x4*)(Gout + (size_t)R * DFF + cr - 4) = w4; } }
	v_mov_b32_dpp v44, v40 row_ror:1 row_mask:0xf bank_mask:0xf
	v_mov_b32_dpp v60, v43 row_ror:1 row_mask:0xf bank_mask:0xf
	v_mov_b32_dpp v47, v40 row_ror:2 row_mask:0xf bank_mask:0xf
	v_cndmask_b32_e64 v54, v44, v54, s[10:11]
	v_mov_b32_dpp v62, v42 row_ror:2 row_mask:0xf bank_mask:0xf
	v_cndmask_b32_e64 v70, v60, v70, s[10:11]
	v_cndmask_b32_e64 v94, v62, v74, s[8:9]
	v_cndmask_b32_e64 v74, v47, v59, s[8:9]
	v_cndmask_b32_e64 v59, v70, 0, s[22:23]
	v_cndmask_b32_e64 v70, v54, 0, s[22:23]
	v_mul_f32_e32 v54, 0xbfb8aa3b, v90
	v_exp_f32_e32 v54, v54
	v_mov_b32_dpp v61, v41 row_ror:2 row_mask:0xf bank_mask:0xf
	v_mov_b32_dpp v63, v43 row_ror:2 row_mask:0xf bank_mask:0xf
	v_add_f32_e32 v54, 1.0, v54
	v_mov_b32_dpp v45, v41 row_ror:1 row_mask:0xf bank_mask:0xf
	v_cndmask_b32_e64 v95, v63, v75, s[8:9]
	v_cndmask_b32_e64 v75, v61, v71, s[8:9]
	v_rcp_f32_e32 v54, v54
	v_cndmask_b32_e64 v56, v45, v56, s[10:11]
	v_cndmask_b32_e64 v75, v75, 0, s[20:21]
	v_cndmask_b32_e64 v74, v74, 0, s[20:21]
	v_cndmask_b32_e64 v71, v56, 0, s[22:23]
	v_pk_fma_f32 v[74:75], v[84:85], v[74:75], v[104:105]
	v_mul_f32_e32 v54, v90, v54
	v_pk_fma_f32 v[70:71], v[76:77], v[70:71], v[74:75]
	v_pk_fma_f32 v[40:41], v[40:41], v[66:67], v[70:71]
	v_cndmask_b32_e64 v95, v95, 0, s[20:21]
	v_mul_f32_e32 v40, v54, v40
	v_mul_f32_e32 v54, 0xbfb8aa3b, v91
	v_exp_f32_e32 v54, v54
	v_mov_b32_dpp v46, v42 row_ror:1 row_mask:0xf bank_mask:0xf
	v_cndmask_b32_e64 v58, v46, v58, s[10:11]
	v_cndmask_b32_e64 v94, v94, 0, s[20:21]
	v_add_f32_e32 v54, 1.0, v54
	v_rcp_f32_e32 v54, v54
	v_cndmask_b32_e64 v58, v58, 0, s[22:23]
	v_pk_fma_f32 v[94:95], v[86:87], v[94:95], v[106:107]
	v_cmp_lt_i32_e32 vcc, 1, v155
	v_mul_f32_e32 v54, v91, v54
	v_mul_f32_e32 v41, v54, v41
	v_mul_f32_e32 v54, 0xbfb8aa3b, v82
	v_exp_f32_e32 v54, v54
	v_pk_fma_f32 v[58:59], v[78:79], v[58:59], v[94:95]
	v_cmp_gt_i32_e64 s[16:17], s89, v154
	v_pk_fma_f32 v[42:43], v[42:43], v[68:69], v[58:59]
	v_add_f32_e32 v54, 1.0, v54
	v_rcp_f32_e32 v54, v54
	s_and_b64 s[18:19], vcc, s[16:17]
	v_cvt_pk_bf16_f32 v90, v40, v41
	v_mul_f32_e32 v54, v82, v54
	v_mul_f32_e32 v42, v54, v42
	v_mul_f32_e32 v54, 0xbfb8aa3b, v83
	v_exp_f32_e32 v54, v54
	s_nop 0
	v_add_f32_e32 v54, 1.0, v54
	v_rcp_f32_e32 v54, v54
	s_nop 0
	v_mul_f32_e32 v54, v83, v54
	v_mul_f32_e32 v43, v54, v43
	v_cvt_pk_bf16_f32 v91, v42, v43
	s_and_saveexec_b64 s[16:17], s[18:19]
	s_cbranch_execz .LBB0_981
	v_mov_b64_e32 v[40:41], s[4:5]
	v_mad_i64_i32 v[40:41], s[18:19], v154, s3, v[40:41]
	v_lshl_add_u64 v[40:41], v[194:195], 1, v[40:41]
	global_store_dwordx4 v[40:41], v[88:91], off
.LBB0_981:
	s_or_b64 exec, exec, s[16:17]
	v_mov_b32_dpp v40, v36 row_ror:1 row_mask:0xf bank_mask:0xf
	v_mov_b32_dpp v41, v37 row_ror:1 row_mask:0xf bank_mask:0xf
	v_mov_b32_dpp v42, v38 row_ror:1 row_mask:0xf bank_mask:0xf
	v_mov_b32_dpp v43, v39 row_ror:1 row_mask:0xf bank_mask:0xf
	v_mov_b32_dpp v54, v36 row_ror:2 row_mask:0xf bank_mask:0xf
	v_mov_b32_dpp v58, v38 row_ror:2 row_mask:0xf bank_mask:0xf
	v_mov_b32_dpp v59, v39 row_ror:2 row_mask:0xf bank_mask:0xf
	v_mov_b32_dpp v56, v37 row_ror:2 row_mask:0xf bank_mask:0xf
	v_cndmask_b32_e64 v48, v40, v48, s[10:11]
	v_cndmask_b32_e64 v49, v41, v49, s[10:11]
	v_cndmask_b32_e64 v40, v42, v50, s[10:11]
	v_cndmask_b32_e64 v41, v43, v52, s[10:11]
	v_cndmask_b32_e64 v50, v58, v55, s[8:9]
	v_cndmask_b32_e64 v52, v59, v57, s[8:9]
	v_cndmask_b32_e64 v51, v54, v51, s[8:9]
	v_cndmask_b32_e64 v53, v56, v53, s[8:9]
	v_cndmask_b32_e64 v42, v48, 0, s[14:15]
	v_cndmask_b32_e64 v48, v51, 0, s[12:13]
	v_cndmask_b32_e64 v51, v52, 0, s[12:13]
	v_cndmask_b32_e64 v50, v50, 0, s[12:13]
	v_cndmask_b32_e64 v41, v41, 0, s[14:15]
	v_cndmask_b32_e64 v40, v40, 0, s[14:15]
	v_cndmask_b32_e64 v43, v49, 0, s[14:15]
	v_cndmask_b32_e64 v49, v53, 0, s[12:13]
	v_pk_fma_f32 v[50:51], v[114:115], v[50:51], v[122:123]
	v_pk_fma_f32 v[48:49], v[112:113], v[48:49], v[120:121]
	v_pk_fma_f32 v[40:41], v[110:111], v[40:41], v[50:51]
	v_pk_fma_f32 v[42:43], v[108:109], v[42:43], v[48:49]
	v_pk_fma_f32 v[38:39], v[38:39], v[118:119], v[40:41]
	v_pk_fma_f32 v[36:37], v[36:37], v[116:117], v[42:43]
	v_mov_b32_dpp v41, v33 row_ror:1 row_mask:0xf bank_mask:0xf
	v_mov_b32_dpp v48, v32 row_ror:2 row_mask:0xf bank_mask:0xf
	v_mov_b32_dpp v49, v33 row_ror:2 row_mask:0xf bank_mask:0xf
	v_mov_b32_dpp v43, v35 row_ror:1 row_mask:0xf bank_mask:0xf
	v_cndmask_b32_e64 v45, v41, v45, s[10:11]
	v_cndmask_b32_e64 v47, v48, v47, s[8:9]
	v_cndmask_b32_e64 v48, v49, v61, s[8:9]
	v_mov_b32_dpp v40, v32 row_ror:1 row_mask:0xf bank_mask:0xf
	v_mov_b32_dpp v42, v34 row_ror:1 row_mask:0xf bank_mask:0xf
	v_mov_b32_dpp v50, v34 row_ror:2 row_mask:0xf bank_mask:0xf
	v_mov_b32_dpp v51, v35 row_ror:2 row_mask:0xf bank_mask:0xf
	v_cndmask_b32_e64 v41, v43, v60, s[10:11]
	v_cndmask_b32_e64 v43, v45, 0, s[14:15]
	v_cndmask_b32_e64 v45, v48, 0, s[12:13]
	v_mul_f32_e32 v48, 0xbfb8aa3b, v36
	v_cndmask_b32_e64 v44, v40, v44, s[10:11]
	v_cndmask_b32_e64 v40, v42, v46, s[10:11]
	v_cndmask_b32_e64 v46, v50, v62, s[8:9]
	v_cndmask_b32_e64 v50, v51, v63, s[8:9]
	v_exp_f32_e32 v48, v48
	v_cndmask_b32_e64 v42, v44, 0, s[14:15]
	v_cndmask_b32_e64 v44, v47, 0, s[12:13]
	v_cndmask_b32_e64 v47, v50, 0, s[12:13]
	v_cndmask_b32_e64 v46, v46, 0, s[12:13]
	v_cndmask_b32_e64 v41, v41, 0, s[14:15]
	v_cndmask_b32_e64 v40, v40, 0, s[14:15]
	v_pk_fma_f32 v[46:47], v[86:87], v[46:47], v[106:107]
	v_pk_fma_f32 v[44:45], v[84:85], v[44:45], v[104:105]
	v_pk_fma_f32 v[40:41], v[78:79], v[40:41], v[46:47]
	v_pk_fma_f32 v[42:43], v[76:77], v[42:43], v[44:45]
	v_pk_fma_f32 v[34:35], v[34:35], v[68:69], v[40:41]
	v_add_f32_e32 v40, 1.0, v48
	v_rcp_f32_e32 v40, v40
	v_mul_f32_e32 v41, 0xbfb8aa3b, v37
	v_exp_f32_e32 v41, v41
	v_pk_fma_f32 v[32:33], v[32:33], v[66:67], v[42:43]
	v_mul_f32_e32 v36, v36, v40
	v_mul_f32_e32 v32, v36, v32
	v_add_f32_e32 v36, 1.0, v41
	v_mul_f32_e32 v40, 0xbfb8aa3b, v38
	v_rcp_f32_e32 v36, v36
	v_exp_f32_e32 v40, v40
	v_mul_f32_e32 v41, 0xbfb8aa3b, v39
	v_exp_f32_e32 v41, v41
	v_mul_f32_e32 v36, v37, v36
	v_add_f32_e32 v37, 1.0, v40
	v_rcp_f32_e32 v37, v37
	v_add_f32_e32 v40, 1.0, v41
	v_rcp_f32_e32 v40, v40
	v_mul_f32_e32 v33, v36, v33
	v_mul_f32_e32 v36, v38, v37
	v_cmp_lt_i32_e32 vcc, 1, v157
	v_cmp_gt_i32_e64 s[12:13], s89, v156
	v_mul_f32_e32 v34, v36, v34
	v_mul_f32_e32 v36, v39, v40
	s_and_b64 s[14:15], vcc, s[12:13]
	v_mul_f32_e32 v35, v36, v35
	v_cvt_pk_bf16_f32 v102, v32, v33
	v_cvt_pk_bf16_f32 v103, v34, v35
	s_and_saveexec_b64 s[12:13], s[14:15]
	s_cbranch_execz .LBB0_983
	v_mov_b64_e32 v[32:33], s[4:5]
	v_mad_i64_i32 v[32:33], s[14:15], v156, s3, v[32:33]
	v_lshl_add_u64 v[32:33], v[194:195], 1, v[32:33]
	global_store_dwordx4 v[32:33], v[100:103], off

; __device__ __forceinline__ unsigned cvt_pk_bf16(float lo, float hi) { unsigned r; asm volatile("v_cvt_pk_bf16_f32 %0, %1, %2" : "=v"(r) : "v"(lo), "v"(hi)); return r; }
;     __device__ __forceinline__ void operator()(const f32x4 (&acc)[2][2][4][2], const Unit& u, int wr, int wc, int fr_, int fq_) const {
;     ...
;                         const f32x4 X = acc[ai][bj][m][n]; const f32x4 r1 = dpp_ror(X, 1), r2 = dpp_ror(X, 2);
;                         f32x4 p1 = (fr == 0) ? pr1[bj] : r1, p2 = (fr < 2) ? pr2[bj] : r2;
;                         pr1[bj] = r1; pr2[bj] = r2;
;                         if (t == 0) p1 = (f32x4){0.f, 0.f, 0.f, 0.f};
;                         if (t <= 1) p2 = (f32x4){0.f, 0.f, 0.f, 0.f};
;                         y[bj] = bj == 0 ? (gb + g0 * p2 + g1 * p1 + g2 * X) : (vb + v0 * p2 + v1 * p1 + v2 * X);
;                     }
;                     f32x4 o;
;                     o.x = y[0].x * __builtin_amdgcn_rcpf(1.f + __builtin_amdgcn_exp2f(-LOG2E * y[0].x)) * y[1].x; o.y = y[0].y * __builtin_amdgcn_rcpf(1.f + __builtin_amdgcn_exp2f(-LOG2E * y[0].y)) * y[1].y;
;                     o.z = y[0].z * __builtin_amdgcn_rcpf(1.f + __builtin_amdgcn_exp2f(-LOG2E * y[0].z)) * y[1].z; o.w = y[0].w * __builtin_amdgcn_rcpf(1.f + __builtin_amdgcn_exp2f(-LOG2E * y[0].w)) * y[1].w;
;                     { u32x2 w; w.x = cvt_pk_bf16(o.x, o.y); w.y = cvt_pk_bf16(o.z, o.w);
;                       if (n == 0) keep[ai][m] = w;
;                       else if (r >= 2 && R < MTOK) { u32x4 w4; w4.x = keep[ai][m].x; w4.y = keep[ai][m].y; w4.z = w.x; w4.w = w.y; *(u32x4*)(Gout + (size_t)R * DFF + cr - 4) = w4; } }
.LBB0_988:
	v_mov_b32_dpp v48, v28 row_ror:1 row_mask:0xf bank_mask:0xf
	v_mov_b32_dpp v49, v29 row_ror:1 row_mask:0xf bank_mask:0xf
	v_mov_b32_dpp v50, v30 row_ror:1 row_mask:0xf bank_mask:0xf
	v_mov_b32_dpp v52, v31 row_ror:1 row_mask:0xf bank_mask:0xf
	v_mov_b32_dpp v51, v28 row_ror:2 row_mask:0xf bank_mask:0xf
	v_mov_b32_dpp v53, v29 row_ror:2 row_mask:0xf bank_mask:0xf
	v_mov_b32_dpp v54, v30 row_ror:2 row_mask:0xf bank_mask:0xf
	v_mov_b32_dpp v55, v31 row_ror:2 row_mask:0xf bank_mask:0xf
	s_waitcnt lgkmcnt(1)
	v_cndmask_b32_e64 v44, v48, v44, s[10:11]
	v_cndmask_b32_e64 v45, v49, v45, s[10:11]
	v_cndmask_b32_e64 v46, v50, v46, s[10:11]
	v_cndmask_b32_e64 v47, v52, v47, s[10:11]
	s_waitcnt lgkmcnt(0)
	v_cndmask_b32_e64 v56, v54, v42, s[8:9]
	v_cndmask_b32_e64 v57, v55, v43, s[8:9]
	v_cndmask_b32_e64 v58, v51, v40, s[8:9]
	v_cndmask_b32_e64 v59, v53, v41, s[8:9]
	v_cndmask_b32_e64 v41, v47, 0, s[34:35]
	v_cndmask_b32_e64 v40, v46, 0, s[34:35]
	v_cndmask_b32_e64 v43, v45, 0, s[34:35]
	v_cndmask_b32_e64 v42, v44, 0, s[34:35]
	v_cndmask_b32_e64 v45, v59, 0, s[30:31]
	v_cndmask_b32_e64 v44, v58, 0, s[30:31]
	v_cndmask_b32_e64 v47, v57, 0, s[30:31]
	v_cndmask_b32_e64 v46, v56, 0, s[30:31]
	v_pk_fma_f32 v[46:47], v[114:115], v[46:47], v[122:123]
	v_pk_fma_f32 v[44:45], v[112:113], v[44:45], v[120:121]
	v_pk_fma_f32 v[40:41], v[110:111], v[40:41], v[46:47]
	v_pk_fma_f32 v[42:43], v[108:109], v[42:43], v[44:45]
	v_pk_fma_f32 v[44:45], v[30:31], v[118:119], v[40:41]
	v_pk_fma_f32 v[46:47], v[28:29], v[116:117], v[42:43]
	v_mov_b32_dpp v30, v26 row_ror:1 row_mask:0xf bank_mask:0xf
	v_mov_b32_dpp v42, v26 row_ror:2 row_mask:0xf bank_mask:0xf
	v_mov_b32_dpp v31, v24 row_ror:2 row_mask:0xf bank_mask:0xf
	v_cndmask_b32_e64 v38, v30, v38, s[10:11]
	v_cndmask_b32_e64 v56, v42, v34, s[8:9]
	v_mov_b32_dpp v40, v27 row_ror:1 row_mask:0xf bank_mask:0xf
	v_mov_b32_dpp v43, v27 row_ror:2 row_mask:0xf bank_mask:0xf
	v_cndmask_b32_e64 v58, v31, v32, s[8:9]
	v_cndmask_b32_e64 v32, v38, 0, s[34:35]
	v_cndmask_b32_e64 v38, v56, 0, s[30:31]
	v_mul_f32_e32 v56, 0xbfb8aa3b, v46
	v_mov_b32_dpp v41, v25 row_ror:2 row_mask:0xf bank_mask:0xf
	v_cndmask_b32_e64 v39, v40, v39, s[10:11]
	v_cndmask_b32_e64 v57, v43, v35, s[8:9]
	v_exp_f32_e32 v56, v56
	v_cndmask_b32_e64 v59, v41, v33, s[8:9]
	v_cndmask_b32_e64 v33, v39, 0, s[34:35]
	v_cndmask_b32_e64 v39, v57, 0, s[30:31]
	v_pk_fma_f32 v[38:39], v[86:87], v[38:39], v[106:107]
	v_pk_fma_f32 v[32:33], v[78:79], v[32:33], v[38:39]
	v_mov_b32_dpp v28, v24 row_ror:1 row_mask:0xf bank_mask:0xf
	v_mov_b32_dpp v29, v25 row_ror:1 row_mask:0xf bank_mask:0xf
	v_pk_fma_f32 v[26:27], v[26:27], v[68:69], v[32:33]
	v_add_f32_e32 v32, 1.0, v56
	v_cndmask_b32_e64 v36, v28, v36, s[10:11]
	v_cndmask_b32_e64 v37, v29, v37, s[10:11]
	v_rcp_f32_e32 v32, v32
	v_mul_f32_e32 v33, 0xbfb8aa3b, v47
	v_cndmask_b32_e64 v35, v37, 0, s[34:35]
	v_cndmask_b32_e64 v34, v36, 0, s[34:35]
	v_cndmask_b32_e64 v37, v59, 0, s[30:31]
	v_cndmask_b32_e64 v36, v58, 0, s[30:31]
	v_exp_f32_e32 v33, v33
	v_pk_fma_f32 v[36:37], v[84:85], v[36:37], v[104:105]
	v_mul_f32_e32 v32, v46, v32
	v_pk_fma_f32 v[34:35], v[76:77], v[34:35], v[36:37]
	v_cmp_lt_i32_e32 vcc, 1, v161
	v_pk_fma_f32 v[24:25], v[24:25], v[66:67], v[34:35]
	v_mul_f32_e32 v34, 0xbfb8aa3b, v45
	v_mul_f32_e32 v24, v32, v24
	v_add_f32_e32 v32, 1.0, v33
	v_mul_f32_e32 v33, 0xbfb8aa3b, v44
	v_exp_f32_e32 v33, v33
	v_exp_f32_e32 v34, v34
	v_rcp_f32_e32 v32, v32
	v_cmp_gt_i32_e64 s[12:13], s89, v160
	v_add_f32_e32 v33, 1.0, v33
	v_rcp_f32_e32 v33, v33
	v_add_f32_e32 v34, 1.0, v34
	v_rcp_f32_e32 v34, v34
	v_mul_f32_e32 v32, v47, v32
	v_mul_f32_e32 v25, v32, v25
	v_mul_f32_e32 v32, v44, v33
	v_mul_f32_e32 v26, v32, v26
	v_mul_f32_e32 v32, v45, v34
	s_and_b64 s[14:15], vcc, s[12:13]
	v_mul_f32_e32 v27, v32, v27
	v_cvt_pk_bf16_f32 v94, v24, v25
	v_cvt_pk_bf16_f32 v95, v26, v27
	s_and_saveexec_b64 s[12:13], s[14:15]
	s_cbranch_execz .LBB0_990
	v_mov_b64_e32 v[24:25], s[4:5]
	v_mad_i64_i32 v[24:25], s[14:15], v160, s3, v[24:25]
	v_lshl_add_u64 v[24:25], v[194:195], 1, v[24:25]
	global_store_dwordx4 v[24:25], v[92:95], off
.LBB0_990:
	s_or_b64 exec, exec, s[12:13]
	v_mov_b32_dpp v46, v22 row_ror:2 row_mask:0xf bank_mask:0xf
	v_mov_b32_dpp v47, v23 row_ror:2 row_mask:0xf bank_mask:0xf
	v_mov_b32_dpp v34, v20 row_ror:1 row_mask:0xf bank_mask:0xf
	v_mov_b32_dpp v36, v21 row_ror:1 row_mask:0xf bank_mask:0xf
	v_mov_b32_dpp v38, v22 row_ror:1 row_mask:0xf bank_mask:0xf
	v_mov_b32_dpp v44, v23 row_ror:1 row_mask:0xf bank_mask:0xf
	v_mov_b32_dpp v39, v20 row_ror:2 row_mask:0xf bank_mask:0xf
	v_mov_b32_dpp v45, v21 row_ror:2 row_mask:0xf bank_mask:0xf
	v_cndmask_b32_e64 v35, v46, v54, s[8:9]
	v_cndmask_b32_e64 v37, v47, v55, s[8:9]
	v_cndmask_b32_e64 v26, v34, v48, s[10:11]
	v_cndmask_b32_e64 v27, v36, v49, s[10:11]
	v_cndmask_b32_e64 v24, v38, v50, s[10:11]
	v_cndmask_b32_e64 v25, v44, v52, s[10:11]
	v_cndmask_b32_e64 v32, v39, v51, s[8:9]
	v_cndmask_b32_e64 v33, v45, v53, s[8:9]
	v_cndmask_b32_e64 v49, v37, 0, s[38:39]
	v_cndmask_b32_e64 v48, v35, 0, s[38:39]
	v_cndmask_b32_e64 v25, v25, 0, s[40:41]
	v_cndmask_b32_e64 v24, v24, 0, s[40:41]
	v_cndmask_b32_e64 v33, v33, 0, s[38:39]
	v_cndmask_b32_e64 v32, v32, 0, s[38:39]
	v_pk_fma_f32 v[48:49], v[114:115], v[48:49], v[122:123]
	v_cndmask_b32_e64 v27, v27, 0, s[40:41]
	v_cndmask_b32_e64 v26, v26, 0, s[40:41]
	v_pk_fma_f32 v[32:33], v[112:113], v[32:33], v[120:121]
	v_pk_fma_f32 v[24:25], v[110:111], v[24:25], v[48:49]
	v_pk_fma_f32 v[26:27], v[108:109], v[26:27], v[32:33]
	v_pk_fma_f32 v[48:49], v[22:23], v[118:119], v[24:25]
	v_pk_fma_f32 v[20:21], v[20:21], v[116:117], v[26:27]
; __device__ __forceinline__ unsigned cvt_pk_bf16(float lo, float hi) { unsigned r; asm volatile("v_cvt_pk_bf16_f32 %0, %1, %2" : "=v"(r) : "v"(lo), "v"(hi)); return r; }
;     __device__ __forceinline__ void operator()(const f32x4 (&acc)[2][2][4][2], const Unit& u, int wr, int wc, int fr_, int fq_) const {
;     ...
;                         const f32x4 X = acc[ai][bj][m][n]; const f32x4 r1 = dpp_ror(X, 1), r2 = dpp_ror(X, 2);
;                         f32x4 p1 = (fr == 0) ? pr1[bj] : r1, p2 = (fr < 2) ? pr2[bj] : r2;
;                         pr1[bj] = r1; pr2[bj] = r2;
;                         if (t == 0) p1 = (f32x4){0.f, 0.f, 0.f, 0.f};
;                         if (t <= 1) p2 = (f32x4){0.f, 0.f, 0.f, 0.f};
;                         y[bj] = bj == 0 ? (gb + g0 * p2 + g1 * p1 + g2 * X) : (vb + v0 * p2 + v1 * p1 + v2 * X);
;                     }
;                     f32x4 o;
;                     o.x = y[0].x * __builtin_amdgcn_rcpf(1.f + __builtin_amdgcn_exp2f(-LOG2E * y[0].x)) * y[1].x; o.y = y[0].y * __builtin_amdgcn_rcpf(1.f + __builtin_amdgcn_exp2f(-LOG2E * y[0].y)) * y[1].y;
;                     o.z = y[0].z * __builtin_amdgcn_rcpf(1.f + __builtin_amdgcn_exp2f(-LOG2E * y[0].z)) * y[1].z; o.w = y[0].w * __builtin_amdgcn_rcpf(1.f + __builtin_amdgcn_exp2f(-LOG2E * y[0].w)) * y[1].w;
;                     { u32x2 w; w.x = cvt_pk_bf16(o.x, o.y); w.y = cvt_pk_bf16(o.z, o.w);
;                       if (n == 0) keep[ai][m] = w;
;                       else if (r >= 2 && R < MTOK) { u32x4 w4; w4.x = keep[ai][m].x; w4.y = keep[ai][m].y; w4.z = w.x; w4.w = w.y; *(u32x4*)(Gout + (size_t)R * DFF + cr - 4) = w4; } }
	v_mov_b32_dpp v22, v16 row_ror:1 row_mask:0xf bank_mask:0xf
	v_cndmask_b32_e64 v23, v22, v28, s[10:11]
	v_mov_b32_dpp v26, v18 row_ror:1 row_mask:0xf bank_mask:0xf
	v_cndmask_b32_e64 v28, v26, v30, s[10:11]
	v_cndmask_b32_e64 v30, v23, 0, s[40:41]
	v_mul_f32_e32 v23, 0xbfb8aa3b, v20
	v_exp_f32_e32 v23, v23
	v_mov_b32_dpp v24, v17 row_ror:1 row_mask:0xf bank_mask:0xf
	v_mov_b32_dpp v32, v19 row_ror:1 row_mask:0xf bank_mask:0xf
	v_mov_b32_dpp v27, v16 row_ror:2 row_mask:0xf bank_mask:0xf
	v_mov_b32_dpp v33, v17 row_ror:2 row_mask:0xf bank_mask:0xf
	v_cndmask_b32_e64 v25, v24, v29, s[10:11]
	v_add_f32_e32 v23, 1.0, v23
	v_cndmask_b32_e64 v29, v32, v40, s[10:11]
	v_cndmask_b32_e64 v40, v27, v31, s[8:9]
	v_cndmask_b32_e64 v41, v33, v41, s[8:9]
	v_cndmask_b32_e64 v31, v25, 0, s[40:41]
	v_rcp_f32_e32 v23, v23
	v_mul_f32_e32 v25, 0xbfb8aa3b, v21
	v_cndmask_b32_e64 v41, v41, 0, s[38:39]
	v_cndmask_b32_e64 v40, v40, 0, s[38:39]
	v_exp_f32_e32 v25, v25
	v_pk_fma_f32 v[40:41], v[84:85], v[40:41], v[104:105]
	v_mul_f32_e32 v20, v20, v23
	v_pk_fma_f32 v[30:31], v[76:77], v[30:31], v[40:41]
	v_mul_f32_e32 v23, 0xbfb8aa3b, v48
	v_pk_fma_f32 v[16:17], v[16:17], v[66:67], v[30:31]
	v_exp_f32_e32 v23, v23
	v_mul_f32_e32 v16, v20, v16
	v_add_f32_e32 v20, 1.0, v25
	v_rcp_f32_e32 v20, v20
	v_mul_f32_e32 v25, 0xbfb8aa3b, v49
	v_exp_f32_e32 v25, v25
	v_mul_f32_e32 v20, v21, v20
	v_mov_b32_dpp v35, v18 row_ror:2 row_mask:0xf bank_mask:0xf
	v_mov_b32_dpp v37, v19 row_ror:2 row_mask:0xf bank_mask:0xf
	v_add_f32_e32 v21, 1.0, v23
	v_cndmask_b32_e64 v42, v35, v42, s[8:9]
	v_cndmask_b32_e64 v43, v37, v43, s[8:9]
	v_rcp_f32_e32 v21, v21
	v_add_f32_e32 v23, 1.0, v25
	v_cndmask_b32_e64 v43, v43, 0, s[38:39]
	v_cndmask_b32_e64 v42, v42, 0, s[38:39]
	v_rcp_f32_e32 v23, v23
	v_cndmask_b32_e64 v29, v29, 0, s[40:41]
	v_cndmask_b32_e64 v28, v28, 0, s[40:41]
	v_pk_fma_f32 v[42:43], v[86:87], v[42:43], v[106:107]
	v_mul_f32_e32 v17, v20, v17
	v_pk_fma_f32 v[28:29], v[78:79], v[28:29], v[42:43]
	v_mul_f32_e32 v20, v48, v21
	v_pk_fma_f32 v[18:19], v[18:19], v[68:69], v[28:29]
	v_cmp_lt_i32_e32 vcc, 1, v141
	v_cmp_gt_i32_e64 s[12:13], s89, v140
	v_mul_f32_e32 v18, v20, v18
	v_mul_f32_e32 v20, v49, v23
	s_and_b64 s[14:15], vcc, s[12:13]
	v_mul_f32_e32 v19, v20, v19
	v_cvt_pk_bf16_f32 v82, v16, v17
	v_cvt_pk_bf16_f32 v83, v18, v19
	s_and_saveexec_b64 s[12:13], s[14:15]
	s_cbranch_execz .LBB0_992
	v_mov_b64_e32 v[16:17], s[4:5]
	v_mad_i64_i32 v[16:17], s[14:15], v140, s3, v[16:17]
	v_lshl_add_u64 v[16:17], v[194:195], 1, v[16:17]
	global_store_dwordx4 v[16:17], v[80:83], off
.LBB0_992:
	s_or_b64 exec, exec, s[12:13]
	v_mov_b32_dpp v16, v12 row_ror:1 row_mask:0xf bank_mask:0xf
	v_mov_b32_dpp v17, v13 row_ror:1 row_mask:0xf bank_mask:0xf
	v_mov_b32_dpp v18, v14 row_ror:1 row_mask:0xf bank_mask:0xf
	v_mov_b32_dpp v19, v12 row_ror:2 row_mask:0xf bank_mask:0xf
	v_mov_b32_dpp v21, v13 row_ror:2 row_mask:0xf bank_mask:0xf
	v_mov_b32_dpp v23, v14 row_ror:2 row_mask:0xf bank_mask:0xf
	v_mov_b32_dpp v25, v15 row_ror:2 row_mask:0xf bank_mask:0xf
	v_mov_b32_dpp v20, v15 row_ror:1 row_mask:0xf bank_mask:0xf
	v_cndmask_b32_e64 v30, v16, v34, s[10:11]
	v_cndmask_b32_e64 v31, v17, v36, s[10:11]
	v_cndmask_b32_e64 v28, v18, v38, s[10:11]
	v_cndmask_b32_e64 v34, v23, v46, s[8:9]
	v_cndmask_b32_e64 v36, v25, v47, s[8:9]
	v_cndmask_b32_e64 v38, v19, v39, s[8:9]
	v_cndmask_b32_e64 v39, v21, v45, s[8:9]
	v_cndmask_b32_e64 v29, v20, v44, s[10:11]
	v_cndmask_b32_e64 v39, v39, 0, s[42:43]
	v_cndmask_b32_e64 v38, v38, 0, s[42:43]
	v_cndmask_b32_e64 v41, v36, 0, s[42:43]
	v_cndmask_b32_e64 v40, v34, 0, s[42:43]
	v_cndmask_b32_e64 v29, v29, 0, s[44:45]
	v_cndmask_b32_e64 v28, v28, 0, s[44:45]
	v_cndmask_b32_e64 v31, v31, 0, s[44:45]
	v_cndmask_b32_e64 v30, v30, 0, s[44:45]
	v_pk_fma_f32 v[40:41], v[114:115], v[40:41], v[122:123]
	v_pk_fma_f32 v[38:39], v[112:113], v[38:39], v[120:121]
	v_pk_fma_f32 v[28:29], v[110:111], v[28:29], v[40:41]
	v_pk_fma_f32 v[30:31], v[108:109], v[30:31], v[38:39]
	v_pk_fma_f32 v[38:39], v[14:15], v[118:119], v[28:29]
	v_pk_fma_f32 v[40:41], v[12:13], v[116:117], v[30:31]
	v_mov_b32_dpp v12, v8 row_ror:1 row_mask:0xf bank_mask:0xf
	v_mov_b32_dpp v28, v11 row_ror:1 row_mask:0xf bank_mask:0xf
	v_mov_b32_dpp v15, v8 row_ror:2 row_mask:0xf bank_mask:0xf
	v_cndmask_b32_e64 v22, v12, v22, s[10:11]
	v_cndmask_b32_e64 v32, v28, v32, s[10:11]
	v_cndmask_b32_e64 v34, v15, v27, s[8:9]
	v_cndmask_b32_e64 v27, v32, 0, s[44:45]
	v_cndmask_b32_e64 v32, v22, 0, s[44:45]
	v_mul_f32_e32 v22, 0xbfb8aa3b, v40
	v_exp_f32_e32 v22, v22
	v_mov_b32_dpp v13, v9 row_ror:1 row_mask:0xf bank_mask:0xf
	v_mov_b32_dpp v29, v9 row_ror:2 row_mask:0xf bank_mask:0xf
	v_mov_b32_dpp v30, v10 row_ror:2 row_mask:0xf bank_mask:0xf
	v_cndmask_b32_e64 v24, v13, v24, s[10:11]
	v_add_f32_e32 v22, 1.0, v22
	v_cndmask_b32_e64 v36, v30, v35, s[8:9]
	v_cndmask_b32_e64 v35, v29, v33, s[8:9]
	v_cndmask_b32_e64 v33, v24, 0, s[44:45]
	v_rcp_f32_e32 v22, v22
	v_mul_f32_e32 v24, 0xbfb8aa3b, v41
	v_mov_b32_dpp v31, v11 row_ror:2 row_mask:0xf bank_mask:0xf
	v_cndmask_b32_e64 v35, v35, 0, s[42:43]
	v_cndmask_b32_e64 v34, v34, 0, s[42:43]
	v_exp_f32_e32 v24, v24
	v_mov_b32_dpp v14, v10 row_ror:1 row_mask:0xf bank_mask:0xf
	v_cndmask_b32_e64 v37, v31, v37, s[8:9]
	v_pk_fma_f32 v[34:35], v[84:85], v[34:35], v[104:105]
	v_cndmask_b32_e64 v26, v14, v26, s[10:11]
	v_cndmask_b32_e64 v37, v37, 0, s[42:43]
	v_cndmask_b32_e64 v36, v36, 0, s[42:43]
	v_pk_fma_f32 v[32:33], v[76:77], v[32:33], v[34:35]
	v_cndmask_b32_e64 v26, v26, 0, s[44:45]
	v_pk_fma_f32 v[36:37], v[86:87], v[36:37], v[106:107]
	v_pk_fma_f32 v[8:9], v[8:9], v[66:67], v[32:33]
	v_mul_f32_e32 v22, v40, v22
	v_pk_fma_f32 v[26:27], v[78:79], v[26:27], v[36:37]
	v_mul_f32_e32 v8, v22, v8
	v_add_f32_e32 v22, 1.0, v24
	v_mul_f32_e32 v24, 0xbfb8aa3b, v38
	v_pk_fma_f32 v[10:11], v[10:11], v[68:69], v[26:27]
	v_exp_f32_e32 v24, v24
	v_mul_f32_e32 v26, 0xbfb8aa3b, v39
	v_exp_f32_e32 v26, v26
	v_rcp_f32_e32 v22, v22
	v_add_f32_e32 v24, 1.0, v24
	v_rcp_f32_e32 v24, v24
	v_add_f32_e32 v26, 1.0, v26
	v_rcp_f32_e32 v26, v26
	v_mul_f32_e32 v22, v41, v22
	v_mul_f32_e32 v9, v22, v9
	v_mul_f32_e32 v22, v38, v24
	v_cmp_lt_i32_e32 vcc, 1, v143
	v_cmp_gt_i32_e64 s[12:13], s89, v142
	v_mul_f32_e32 v10, v22, v10
	v_mul_f32_e32 v22, v39, v26
	s_and_b64 s[14:15], vcc, s[12:13]
	v_mul_f32_e32 v11, v22, v11
	v_cvt_pk_bf16_f32 v74, v8, v9
	v_cvt_pk_bf16_f32 v75, v10, v11
	s_and_saveexec_b64 s[12:13], s[14:15]
	s_cbranch_execz .LBB0_994
	v_mov_b64_e32 v[8:9], s[4:5]
	v_mad_i64_i32 v[8:9], s[14:15], v142, s3, v[8:9]
	v_lshl_add_u64 v[8:9], v[194:195], 1, v[8:9]
	global_store_dwordx4 v[8:9], v[72:75], off
; __device__ __forceinline__ unsigned cvt_pk_bf16(float lo, float hi) { unsigned r; asm volatile("v_cvt_pk_bf16_f32 %0, %1, %2" : "=v"(r) : "v"(lo), "v"(hi)); return r; }
;     __device__ __forceinline__ void operator()(const f32x4 (&acc)[2][2][4][2], const Unit& u, int wr, int wc, int fr_, int fq_) const {
;     ...
;                         const f32x4 X = acc[ai][bj][m][n]; const f32x4 r1 = dpp_ror(X, 1), r2 = dpp_ror(X, 2);
;                         f32x4 p1 = (fr == 0) ? pr1[bj] : r1, p2 = (fr < 2) ? pr2[bj] : r2;
;                         pr1[bj] = r1; pr2[bj] = r2;
;                         if (t == 0) p1 = (f32x4){0.f, 0.f, 0.f, 0.f};
;                         if (t <= 1) p2 = (f32x4){0.f, 0.f, 0.f, 0.f};
;                         y[bj] = bj == 0 ? (gb + g0 * p2 + g1 * p1 + g2 * X) : (vb + v0 * p2 + v1 * p1 + v2 * X);
;                     }
;                     f32x4 o;
;                     o.x = y[0].x * __builtin_amdgcn_rcpf(1.f + __builtin_amdgcn_exp2f(-LOG2E * y[0].x)) * y[1].x; o.y = y[0].y * __builtin_amdgcn_rcpf(1.f + __builtin_amdgcn_exp2f(-LOG2E * y[0].y)) * y[1].y;
;                     o.z = y[0].z * __builtin_amdgcn_rcpf(1.f + __builtin_amdgcn_exp2f(-LOG2E * y[0].z)) * y[1].z; o.w = y[0].w * __builtin_amdgcn_rcpf(1.f + __builtin_amdgcn_exp2f(-LOG2E * y[0].w)) * y[1].w;
;                     { u32x2 w; w.x = cvt_pk_bf16(o.x, o.y); w.y = cvt_pk_bf16(o.z, o.w);
;                       if (n == 0) keep[ai][m] = w;
;                       else if (r >= 2 && R < MTOK) { u32x4 w4; w4.x = keep[ai][m].x; w4.y = keep[ai][m].y; w4.z = w.x; w4.w = w.y; *(u32x4*)(Gout + (size_t)R * DFF + cr - 4) = w4; } }
.LBB0_994:
	s_or_b64 exec, exec, s[12:13]
	v_mov_b32_dpp v8, v4 row_ror:1 row_mask:0xf bank_mask:0xf
	v_mov_b32_dpp v9, v5 row_ror:1 row_mask:0xf bank_mask:0xf
	v_mov_b32_dpp v10, v6 row_ror:1 row_mask:0xf bank_mask:0xf
	v_mov_b32_dpp v11, v7 row_ror:1 row_mask:0xf bank_mask:0xf
	v_mov_b32_dpp v22, v4 row_ror:2 row_mask:0xf bank_mask:0xf
	v_mov_b32_dpp v26, v6 row_ror:2 row_mask:0xf bank_mask:0xf
	v_mov_b32_dpp v27, v7 row_ror:2 row_mask:0xf bank_mask:0xf
	v_mov_b32_dpp v24, v5 row_ror:2 row_mask:0xf bank_mask:0xf
	v_cndmask_b32_e64 v16, v8, v16, s[10:11]
	v_cndmask_b32_e64 v17, v9, v17, s[10:11]
	v_cndmask_b32_e64 v8, v10, v18, s[10:11]
	v_cndmask_b32_e64 v9, v11, v20, s[10:11]
	v_cndmask_b32_e64 v18, v26, v23, s[8:9]
	v_cndmask_b32_e64 v20, v27, v25, s[8:9]
	v_cndmask_b32_e64 v19, v22, v19, s[8:9]
	v_cndmask_b32_e64 v21, v24, v21, s[8:9]
	v_cndmask_b32_e64 v10, v16, 0, s[48:49]
	v_cndmask_b32_e64 v16, v19, 0, s[46:47]
	v_cndmask_b32_e64 v19, v20, 0, s[46:47]
	v_cndmask_b32_e64 v18, v18, 0, s[46:47]
	v_cndmask_b32_e64 v9, v9, 0, s[48:49]
	v_cndmask_b32_e64 v8, v8, 0, s[48:49]
	v_cndmask_b32_e64 v11, v17, 0, s[48:49]
	v_cndmask_b32_e64 v17, v21, 0, s[46:47]
	v_pk_fma_f32 v[18:19], v[114:115], v[18:19], v[122:123]
	v_pk_fma_f32 v[16:17], v[112:113], v[16:17], v[120:121]
	v_pk_fma_f32 v[8:9], v[110:111], v[8:9], v[18:19]
	v_pk_fma_f32 v[10:11], v[108:109], v[10:11], v[16:17]
	v_pk_fma_f32 v[6:7], v[6:7], v[118:119], v[8:9]
	v_pk_fma_f32 v[4:5], v[4:5], v[116:117], v[10:11]
	v_mov_b32_dpp v9, v1 row_ror:1 row_mask:0xf bank_mask:0xf
	v_mov_b32_dpp v16, v0 row_ror:2 row_mask:0xf bank_mask:0xf
	v_mov_b32_dpp v17, v1 row_ror:2 row_mask:0xf bank_mask:0xf
	v_mov_b32_dpp v11, v3 row_ror:1 row_mask:0xf bank_mask:0xf
	v_cndmask_b32_e64 v13, v9, v13, s[10:11]
	v_cndmask_b32_e64 v15, v16, v15, s[8:9]
	v_cndmask_b32_e64 v16, v17, v29, s[8:9]
	v_mov_b32_dpp v8, v0 row_ror:1 row_mask:0xf bank_mask:0xf
	v_mov_b32_dpp v10, v2 row_ror:1 row_mask:0xf bank_mask:0xf
	v_mov_b32_dpp v18, v2 row_ror:2 row_mask:0xf bank_mask:0xf
	v_mov_b32_dpp v19, v3 row_ror:2 row_mask:0xf bank_mask:0xf
	v_cndmask_b32_e64 v9, v11, v28, s[10:11]
	v_cndmask_b32_e64 v11, v13, 0, s[48:49]
	v_cndmask_b32_e64 v13, v16, 0, s[46:47]
	v_mul_f32_e32 v16, 0xbfb8aa3b, v4
	v_cndmask_b32_e64 v12, v8, v12, s[10:11]
	v_cndmask_b32_e64 v8, v10, v14, s[10:11]
	v_cndmask_b32_e64 v14, v18, v30, s[8:9]
	v_cndmask_b32_e64 v18, v19, v31, s[8:9]
	v_exp_f32_e32 v16, v16
	v_cndmask_b32_e64 v10, v12, 0, s[48:49]
	v_cndmask_b32_e64 v12, v15, 0, s[46:47]
	v_cndmask_b32_e64 v15, v18, 0, s[46:47]
	v_cndmask_b32_e64 v14, v14, 0, s[46:47]
	v_cndmask_b32_e64 v9, v9, 0, s[48:49]
	v_cndmask_b32_e64 v8, v8, 0, s[48:49]
	v_pk_fma_f32 v[14:15], v[86:87], v[14:15], v[106:107]
	v_pk_fma_f32 v[12:13], v[84:85], v[12:13], v[104:105]
	v_pk_fma_f32 v[8:9], v[78:79], v[8:9], v[14:15]
	v_pk_fma_f32 v[10:11], v[76:77], v[10:11], v[12:13]
	v_pk_fma_f32 v[2:3], v[2:3], v[68:69], v[8:9]
	v_add_f32_e32 v8, 1.0, v16
	v_rcp_f32_e32 v8, v8
	v_mul_f32_e32 v9, 0xbfb8aa3b, v5
	v_exp_f32_e32 v9, v9
	v_pk_fma_f32 v[0:1], v[0:1], v[66:67], v[10:11]
	v_mul_f32_e32 v4, v4, v8
	v_mul_f32_e32 v0, v4, v0
	v_add_f32_e32 v4, 1.0, v9
	v_mul_f32_e32 v8, 0xbfb8aa3b, v6
	v_rcp_f32_e32 v4, v4
	v_exp_f32_e32 v8, v8
	v_mul_f32_e32 v9, 0xbfb8aa3b, v7
	v_exp_f32_e32 v9, v9
	v_mul_f32_e32 v4, v5, v4
	v_add_f32_e32 v5, 1.0, v8
	v_rcp_f32_e32 v5, v5
	v_add_f32_e32 v8, 1.0, v9
	v_rcp_f32_e32 v8, v8
	v_mul_f32_e32 v1, v4, v1
	v_mul_f32_e32 v4, v6, v5
	v_cmp_lt_i32_e32 vcc, 1, v145
	v_cmp_gt_i32_e64 s[8:9], s89, v144
	v_mul_f32_e32 v2, v4, v2
	v_mul_f32_e32 v4, v7, v8
	s_and_b64 s[10:11], vcc, s[8:9]
	v_mul_f32_e32 v3, v4, v3
	v_cvt_pk_bf16_f32 v66, v0, v1
	v_cvt_pk_bf16_f32 v67, v2, v3
	s_and_saveexec_b64 s[8:9], s[10:11]
	s_cbranch_execz .LBB0_996
	v_mov_b64_e32 v[0:1], s[4:5]
	v_mad_i64_i32 v[0:1], s[10:11], v144, s3, v[0:1]
	v_lshl_add_u64 v[0:1], v[194:195], 1, v[0:1]
	global_store_dwordx4 v[0:1], v[64:67], off
